# GEMM K-loops, loop-edge edit: LDS reads lead the post-barrier segment; scalar address updates moved behind them
# baseline (speedup 1.0000x reference)
.LBB0_305:
	ds_read_b128 v[150:153], v133
	ds_read_b128 v[156:159], v133 offset:1024
	ds_read_b128 v[160:163], v133 offset:2048
	ds_read_b128 v[164:167], v133 offset:3072
	s_add_u32 s30, s4, 0xfffc0080
	s_addc_u32 s31, s5, -1
	s_add_i32 s52, 0, 0x10000
	s_cmp_eq_u32 s51, 12
	s_cselect_b32 s35, s27, s31
	s_cselect_b32 s34, s26, s30
	s_cselect_b32 s31, s29, s25
	s_cselect_b32 s30, s28, s23
	s_add_i32 m0, s42, 0xc000
	ds_read_b128 v[168:171], v155
	ds_read_b128 v[172:175], v155 offset:1024
	ds_read_b128 v[176:179], v155 offset:2048
	ds_read_b128 v[180:183], v155 offset:3072
	ds_read_b128 v[184:187], v155 offset:4096
	ds_read_b128 v[188:191], v155 offset:5120
	ds_read_b128 v[198:201], v155 offset:6144
	ds_read_b128 v[202:205], v155 offset:7168
	global_load_lds_dwordx4 v146, s[4:5]
	s_add_i32 m0, s42, 0xe000
	s_nop 0
	global_load_lds_dwordx4 v148, s[4:5]
	s_waitcnt lgkmcnt(8)
	s_barrier
	s_waitcnt lgkmcnt(0)
	s_setprio 1
	s_waitcnt lgkmcnt(0)
	v_mfma_f32_16x16x32_bf16 v[126:129], v[150:153], v[168:171], v[126:129]
	v_mfma_f32_16x16x32_bf16 v[122:125], v[160:163], v[168:171], v[122:125]
	v_mfma_f32_16x16x32_bf16 v[110:113], v[150:153], v[176:179], v[110:113]
	v_mfma_f32_16x16x32_bf16 v[106:109], v[160:163], v[176:179], v[106:109]
	v_mfma_f32_16x16x32_bf16 v[94:97], v[150:153], v[184:187], v[94:97]
	v_mfma_f32_16x16x32_bf16 v[90:93], v[160:163], v[184:187], v[90:93]
	v_mfma_f32_16x16x32_bf16 v[78:81], v[150:153], v[198:201], v[78:81]
	v_mfma_f32_16x16x32_bf16 v[74:77], v[160:163], v[198:201], v[74:77]
	v_mfma_f32_16x16x32_bf16 v[126:129], v[156:159], v[172:175], v[126:129]
	v_mfma_f32_16x16x32_bf16 v[122:125], v[164:167], v[172:175], v[122:125]
	v_mfma_f32_16x16x32_bf16 v[110:113], v[156:159], v[180:183], v[110:113]
	v_mfma_f32_16x16x32_bf16 v[106:109], v[164:167], v[180:183], v[106:109]
	v_mfma_f32_16x16x32_bf16 v[94:97], v[156:159], v[188:191], v[94:97]
	v_mfma_f32_16x16x32_bf16 v[90:93], v[164:167], v[188:191], v[90:93]
	v_mfma_f32_16x16x32_bf16 v[78:81], v[156:159], v[202:205], v[78:81]
	v_mfma_f32_16x16x32_bf16 v[74:77], v[164:167], v[202:205], v[74:77]
	s_setprio 0
	s_barrier
	s_add_i32 s54, 0, 0x14000
	s_add_i32 s52, s52, s41
	s_mov_b32 m0, s52
	ds_read_b128 v[206:209], v133 offset:16384
	ds_read_b128 v[210:213], v133 offset:17408
	ds_read_b128 v[214:217], v133 offset:18432
	ds_read_b128 v[218:221], v133 offset:19456
	global_load_lds_dwordx4 v132, s[30:31]
	s_add_i32 m0, s52, 0x2000
	s_nop 0
	global_load_lds_dwordx4 v136, s[30:31]
	s_barrier
	s_waitcnt lgkmcnt(0)
	s_setprio 1
	s_waitcnt lgkmcnt(0)
	v_mfma_f32_16x16x32_bf16 v[118:121], v[206:209], v[168:171], v[118:121]
	v_mfma_f32_16x16x32_bf16 v[114:117], v[214:217], v[168:171], v[114:117]
	v_mfma_f32_16x16x32_bf16 v[102:105], v[206:209], v[176:179], v[102:105]
	v_mfma_f32_16x16x32_bf16 v[98:101], v[214:217], v[176:179], v[98:101]
	v_mfma_f32_16x16x32_bf16 v[86:89], v[206:209], v[184:187], v[86:89]
	v_mfma_f32_16x16x32_bf16 v[82:85], v[214:217], v[184:187], v[82:85]
	v_mfma_f32_16x16x32_bf16 v[70:73], v[206:209], v[198:201], v[70:73]
	v_mfma_f32_16x16x32_bf16 v[66:69], v[214:217], v[198:201], v[66:69]
	v_mfma_f32_16x16x32_bf16 v[118:121], v[210:213], v[172:175], v[118:121]
	v_mfma_f32_16x16x32_bf16 v[114:117], v[218:221], v[172:175], v[114:117]
	v_mfma_f32_16x16x32_bf16 v[102:105], v[210:213], v[180:183], v[102:105]
	v_mfma_f32_16x16x32_bf16 v[98:101], v[218:221], v[180:183], v[98:101]
	v_mfma_f32_16x16x32_bf16 v[86:89], v[210:213], v[188:191], v[86:89]
	v_mfma_f32_16x16x32_bf16 v[82:85], v[218:221], v[188:191], v[82:85]
	v_mfma_f32_16x16x32_bf16 v[70:73], v[210:213], v[202:205], v[70:73]
	v_mfma_f32_16x16x32_bf16 v[66:69], v[218:221], v[202:205], v[66:69]
	s_setprio 0
	s_mov_b32 m0, s42
	v_lshl_add_u64 v[242:243], s[34:35], 0, v[130:131]
	s_barrier
	ds_read_b128 v[168:171], v155 offset:16384
	ds_read_b128 v[172:175], v155 offset:17408
	ds_read_b128 v[176:179], v155 offset:18432
	ds_read_b128 v[180:183], v155 offset:19456
	ds_read_b128 v[184:187], v155 offset:20480
	ds_read_b128 v[188:191], v155 offset:21504
	ds_read_b128 v[198:201], v155 offset:22528
	ds_read_b128 v[202:205], v155 offset:23552
	global_load_lds_dwordx4 v[242:243], off
	v_lshl_add_u64 v[244:245], s[34:35], 0, v[134:135]
	s_mov_b32 m0, s43
	s_nop 0
	global_load_lds_dwordx4 v[244:245], off
	s_barrier
	s_waitcnt lgkmcnt(0)
	s_setprio 1
	s_waitcnt lgkmcnt(0)
	v_mfma_f32_16x16x32_bf16 v[62:65], v[150:153], v[168:171], v[62:65]
	v_mfma_f32_16x16x32_bf16 v[58:61], v[160:163], v[168:171], v[58:61]
	v_mfma_f32_16x16x32_bf16 v[44:47], v[150:153], v[176:179], v[44:47]
	v_mfma_f32_16x16x32_bf16 v[40:43], v[160:163], v[176:179], v[40:43]
	v_mfma_f32_16x16x32_bf16 v[28:31], v[150:153], v[184:187], v[28:31]
	v_mfma_f32_16x16x32_bf16 v[24:27], v[160:163], v[184:187], v[24:27]
	v_mfma_f32_16x16x32_bf16 v[12:15], v[150:153], v[198:201], v[12:15]
	v_mfma_f32_16x16x32_bf16 v[8:11], v[160:163], v[198:201], v[8:11]
	v_mfma_f32_16x16x32_bf16 v[62:65], v[156:159], v[172:175], v[62:65]
	v_mfma_f32_16x16x32_bf16 v[58:61], v[164:167], v[172:175], v[58:61]
	v_mfma_f32_16x16x32_bf16 v[44:47], v[156:159], v[180:183], v[44:47]
	v_mfma_f32_16x16x32_bf16 v[40:43], v[164:167], v[180:183], v[40:43]
	v_mfma_f32_16x16x32_bf16 v[28:31], v[156:159], v[188:191], v[28:31]
	v_mfma_f32_16x16x32_bf16 v[24:27], v[164:167], v[188:191], v[24:27]
	v_mfma_f32_16x16x32_bf16 v[12:15], v[156:159], v[202:205], v[12:15]
	v_mfma_f32_16x16x32_bf16 v[8:11], v[164:167], v[202:205], v[8:11]
	s_setprio 0
	s_barrier
	s_add_u32 s52, s30, 0x40000
	s_addc_u32 s53, s31, 0
	s_add_i32 s54, s54, s41
	s_mov_b32 m0, s54
	s_nop 0
	global_load_lds_dwordx4 v132, s[52:53]
	s_add_i32 m0, s54, 0x2000
	s_nop 0
	global_load_lds_dwordx4 v136, s[52:53]
	s_waitcnt vmcnt(6)
	s_barrier
	s_setprio 1
	v_mfma_f32_16x16x32_bf16 v[54:57], v[206:209], v[168:171], v[54:57]
	v_mfma_f32_16x16x32_bf16 v[50:53], v[214:217], v[168:171], v[50:53]
	v_mfma_f32_16x16x32_bf16 v[36:39], v[206:209], v[176:179], v[36:39]
	v_mfma_f32_16x16x32_bf16 v[32:35], v[214:217], v[176:179], v[32:35]
	v_mfma_f32_16x16x32_bf16 v[20:23], v[206:209], v[184:187], v[20:23]
	v_mfma_f32_16x16x32_bf16 v[16:19], v[214:217], v[184:187], v[16:19]
	v_mfma_f32_16x16x32_bf16 v[4:7], v[206:209], v[198:201], v[4:7]
	v_mfma_f32_16x16x32_bf16 v[0:3], v[214:217], v[198:201], v[0:3]
	v_mfma_f32_16x16x32_bf16 v[54:57], v[210:213], v[172:175], v[54:57]
	v_mfma_f32_16x16x32_bf16 v[50:53], v[218:221], v[172:175], v[50:53]
	v_mfma_f32_16x16x32_bf16 v[36:39], v[210:213], v[180:183], v[36:39]
	v_mfma_f32_16x16x32_bf16 v[32:35], v[218:221], v[180:183], v[32:35]
	v_mfma_f32_16x16x32_bf16 v[20:23], v[210:213], v[188:191], v[20:23]
	v_mfma_f32_16x16x32_bf16 v[16:19], v[218:221], v[188:191], v[16:19]
	v_mfma_f32_16x16x32_bf16 v[4:7], v[210:213], v[202:205], v[4:7]
	v_mfma_f32_16x16x32_bf16 v[0:3], v[218:221], v[202:205], v[0:3]
	s_setprio 0
	s_add_i32 s52, 0, 0x18000
	s_barrier
	ds_read_b128 v[150:153], v133 offset:32768
	ds_read_b128 v[156:159], v133 offset:33792
	ds_read_b128 v[160:163], v133 offset:34816
	ds_read_b128 v[164:167], v133 offset:35840
	s_add_u32 s34, s34, 0x40000
	s_addc_u32 s35, s35, 0
	s_mov_b32 m0, s44
	ds_read_b128 v[168:171], v155 offset:32768
	ds_read_b128 v[172:175], v155 offset:33792
	ds_read_b128 v[176:179], v155 offset:34816
	ds_read_b128 v[180:183], v155 offset:35840
	ds_read_b128 v[184:187], v155 offset:36864
	ds_read_b128 v[188:191], v155 offset:37888
	ds_read_b128 v[198:201], v155 offset:38912
	ds_read_b128 v[202:205], v155 offset:39936
	global_load_lds_dwordx4 v130, s[34:35]
	s_mov_b32 m0, s45
	s_nop 0
	global_load_lds_dwordx4 v134, s[34:35]
	s_waitcnt lgkmcnt(8)
	s_barrier
	s_waitcnt lgkmcnt(0)
	s_setprio 1
	s_waitcnt lgkmcnt(0)
	v_mfma_f32_16x16x32_bf16 v[126:129], v[150:153], v[168:171], v[126:129]
	v_mfma_f32_16x16x32_bf16 v[122:125], v[160:163], v[168:171], v[122:125]
	v_mfma_f32_16x16x32_bf16 v[110:113], v[150:153], v[176:179], v[110:113]
	v_mfma_f32_16x16x32_bf16 v[106:109], v[160:163], v[176:179], v[106:109]
	v_mfma_f32_16x16x32_bf16 v[94:97], v[150:153], v[184:187], v[94:97]
	v_mfma_f32_16x16x32_bf16 v[90:93], v[160:163], v[184:187], v[90:93]
	v_mfma_f32_16x16x32_bf16 v[78:81], v[150:153], v[198:201], v[78:81]
	v_mfma_f32_16x16x32_bf16 v[74:77], v[160:163], v[198:201], v[74:77]
	v_mfma_f32_16x16x32_bf16 v[126:129], v[156:159], v[172:175], v[126:129]
	v_mfma_f32_16x16x32_bf16 v[122:125], v[164:167], v[172:175], v[122:125]
	v_mfma_f32_16x16x32_bf16 v[110:113], v[156:159], v[180:183], v[110:113]
	v_mfma_f32_16x16x32_bf16 v[106:109], v[164:167], v[180:183], v[106:109]
	v_mfma_f32_16x16x32_bf16 v[94:97], v[156:159], v[188:191], v[94:97]
	v_mfma_f32_16x16x32_bf16 v[90:93], v[164:167], v[188:191], v[90:93]
	v_mfma_f32_16x16x32_bf16 v[78:81], v[156:159], v[202:205], v[78:81]
	v_mfma_f32_16x16x32_bf16 v[74:77], v[164:167], v[202:205], v[74:77]
	s_setprio 0
	s_barrier
	s_add_i32 s34, 0, 0x1c000
	s_add_i32 s35, s52, s41
	s_add_u32 s52, s30, s66
	s_addc_u32 s53, s31, s67
	s_mov_b32 m0, s35
	ds_read_b128 v[206:209], v133 offset:49152
	ds_read_b128 v[210:213], v133 offset:50176
	ds_read_b128 v[214:217], v133 offset:51200
	ds_read_b128 v[218:221], v133 offset:52224
	global_load_lds_dwordx4 v132, s[52:53]
	s_add_i32 m0, s35, 0x2000
	s_nop 0
	global_load_lds_dwordx4 v136, s[52:53]
	s_barrier
	s_waitcnt lgkmcnt(0)
	s_setprio 1
	s_waitcnt lgkmcnt(0)
	v_mfma_f32_16x16x32_bf16 v[118:121], v[206:209], v[168:171], v[118:121]
	v_mfma_f32_16x16x32_bf16 v[114:117], v[214:217], v[168:171], v[114:117]
	v_mfma_f32_16x16x32_bf16 v[102:105], v[206:209], v[176:179], v[102:105]
	v_mfma_f32_16x16x32_bf16 v[98:101], v[214:217], v[176:179], v[98:101]
	v_mfma_f32_16x16x32_bf16 v[86:89], v[206:209], v[184:187], v[86:89]
	v_mfma_f32_16x16x32_bf16 v[82:85], v[214:217], v[184:187], v[82:85]
	v_mfma_f32_16x16x32_bf16 v[70:73], v[206:209], v[198:201], v[70:73]
	v_mfma_f32_16x16x32_bf16 v[66:69], v[214:217], v[198:201], v[66:69]
	v_mfma_f32_16x16x32_bf16 v[118:121], v[210:213], v[172:175], v[118:121]
	v_mfma_f32_16x16x32_bf16 v[114:117], v[218:221], v[172:175], v[114:117]
	v_mfma_f32_16x16x32_bf16 v[102:105], v[210:213], v[180:183], v[102:105]
	v_mfma_f32_16x16x32_bf16 v[98:101], v[218:221], v[180:183], v[98:101]
	v_mfma_f32_16x16x32_bf16 v[86:89], v[210:213], v[188:191], v[86:89]
	v_mfma_f32_16x16x32_bf16 v[82:85], v[218:221], v[188:191], v[82:85]
	v_mfma_f32_16x16x32_bf16 v[70:73], v[210:213], v[202:205], v[70:73]
	v_mfma_f32_16x16x32_bf16 v[66:69], v[218:221], v[202:205], v[66:69]
	s_setprio 0
	s_mov_b32 m0, s46
	v_lshl_add_u64 v[192:193], v[242:243], 0, s[66:67]
	s_barrier
	ds_read_b128 v[168:171], v155 offset:49152
	ds_read_b128 v[172:175], v155 offset:50176
	ds_read_b128 v[176:179], v155 offset:51200
	ds_read_b128 v[180:183], v155 offset:52224
	ds_read_b128 v[184:187], v155 offset:53248
	ds_read_b128 v[188:191], v155 offset:54272
	ds_read_b128 v[198:201], v155 offset:55296
	ds_read_b128 v[202:205], v155 offset:56320
	global_load_lds_dwordx4 v[192:193], off
	v_lshl_add_u64 v[192:193], v[244:245], 0, s[66:67]
	s_mov_b32 m0, s47
	s_nop 0
	global_load_lds_dwordx4 v[192:193], off
	s_barrier
	s_waitcnt lgkmcnt(0)
	s_setprio 1
	s_waitcnt lgkmcnt(0)
	v_mfma_f32_16x16x32_bf16 v[62:65], v[150:153], v[168:171], v[62:65]
	v_mfma_f32_16x16x32_bf16 v[58:61], v[160:163], v[168:171], v[58:61]
	v_mfma_f32_16x16x32_bf16 v[44:47], v[150:153], v[176:179], v[44:47]
	v_mfma_f32_16x16x32_bf16 v[40:43], v[160:163], v[176:179], v[40:43]
	v_mfma_f32_16x16x32_bf16 v[28:31], v[150:153], v[184:187], v[28:31]
	v_mfma_f32_16x16x32_bf16 v[24:27], v[160:163], v[184:187], v[24:27]
	v_mfma_f32_16x16x32_bf16 v[12:15], v[150:153], v[198:201], v[12:15]
	v_mfma_f32_16x16x32_bf16 v[8:11], v[160:163], v[198:201], v[8:11]
	v_mfma_f32_16x16x32_bf16 v[62:65], v[156:159], v[172:175], v[62:65]
	v_mfma_f32_16x16x32_bf16 v[58:61], v[164:167], v[172:175], v[58:61]
	v_mfma_f32_16x16x32_bf16 v[44:47], v[156:159], v[180:183], v[44:47]
	v_mfma_f32_16x16x32_bf16 v[40:43], v[164:167], v[180:183], v[40:43]
	v_mfma_f32_16x16x32_bf16 v[28:31], v[156:159], v[188:191], v[28:31]
	v_mfma_f32_16x16x32_bf16 v[24:27], v[164:167], v[188:191], v[24:27]
	v_mfma_f32_16x16x32_bf16 v[12:15], v[156:159], v[202:205], v[12:15]
	v_mfma_f32_16x16x32_bf16 v[8:11], v[164:167], v[202:205], v[8:11]
	s_setprio 0
	s_barrier
	s_add_u32 s30, s30, 0x40080
	s_addc_u32 s31, s31, 0
	s_add_i32 s34, s34, s41
	s_mov_b32 m0, s34
	s_nop 0
	global_load_lds_dwordx4 v132, s[30:31]
	s_add_i32 m0, s34, 0x2000
	s_nop 0
	global_load_lds_dwordx4 v136, s[30:31]
	s_waitcnt vmcnt(6)
	s_barrier
	s_setprio 1
	v_mfma_f32_16x16x32_bf16 v[54:57], v[206:209], v[168:171], v[54:57]
	v_mfma_f32_16x16x32_bf16 v[50:53], v[214:217], v[168:171], v[50:53]
	v_mfma_f32_16x16x32_bf16 v[36:39], v[206:209], v[176:179], v[36:39]
	v_mfma_f32_16x16x32_bf16 v[32:35], v[214:217], v[176:179], v[32:35]
	v_mfma_f32_16x16x32_bf16 v[20:23], v[206:209], v[184:187], v[20:23]
	v_mfma_f32_16x16x32_bf16 v[16:19], v[214:217], v[184:187], v[16:19]
	v_mfma_f32_16x16x32_bf16 v[4:7], v[206:209], v[198:201], v[4:7]
	v_mfma_f32_16x16x32_bf16 v[0:3], v[214:217], v[198:201], v[0:3]
	v_mfma_f32_16x16x32_bf16 v[54:57], v[210:213], v[172:175], v[54:57]
	v_mfma_f32_16x16x32_bf16 v[50:53], v[218:221], v[172:175], v[50:53]
	v_mfma_f32_16x16x32_bf16 v[36:39], v[210:213], v[180:183], v[36:39]
	v_mfma_f32_16x16x32_bf16 v[32:35], v[218:221], v[180:183], v[32:35]
	v_mfma_f32_16x16x32_bf16 v[20:23], v[210:213], v[188:191], v[20:23]
	v_mfma_f32_16x16x32_bf16 v[16:19], v[218:221], v[188:191], v[16:19]
	v_mfma_f32_16x16x32_bf16 v[4:7], v[210:213], v[202:205], v[4:7]
	v_mfma_f32_16x16x32_bf16 v[0:3], v[218:221], v[202:205], v[0:3]
	s_setprio 0
	s_add_i32 s51, s51, 2
	s_add_u32 s4, s4, 0x100
	s_addc_u32 s5, s5, 0
	s_add_u32 s23, s23, 0x100
	s_addc_u32 s25, s25, 0
	s_cmp_gt_u32 s51, 13
	s_barrier
	s_cbranch_scc0 .LBB0_305
	v_lshl_add_u32 v156, s50, 8, v139
	v_ashrrev_i32_e32 v48, 31, v156
	v_alignbit_b32 v150, v48, v156, 6
	v_mad_u64_u32 v[150:151], s[4:5], v150, s71, 0
	v_mad_i32_i24 v151, v48, s71, v151
	v_lshlrev_b32_e32 v48, 3, v156
	s_cmp_lg_u32 s49, 0
	v_and_b32_e32 v48, 0x78, v48
	s_cselect_b64 s[30:31], -1, 0
	s_and_b64 vcc, exec, s[30:31]
	v_lshl_add_u32 v157, s49, 8, v145
	v_lshlrev_b32_e32 v48, 1, v48
	s_cbranch_vccz .LBB0_314
	v_ashrrev_i32_e32 v152, 3, v157
	v_ashrrev_i32_e32 v153, 31, v152
	v_lshl_add_u64 v[152:153], v[150:151], 0, v[152:153]
	v_lshlrev_b64 v[152:153], 10, v[152:153]
	v_lshl_add_u64 v[152:153], s[18:19], 0, v[152:153]
	v_lshl_add_u64 v[152:153], v[152:153], 0, v[48:49]
	v_ashrrev_i32_e32 v159, 5, v156
	v_add_u32_e32 v158, v159, v140
	s_cbranch_execnz .LBB0_309

.LBB0_641:
	ds_read_b128 v[146:149], v131
	ds_read_b128 v[150:153], v131 offset:1024
	ds_read_b128 v[154:157], v131 offset:2048
	ds_read_b128 v[158:161], v131 offset:3072
	s_add_u32 s24, s22, 0x100
	s_addc_u32 s25, s23, 0
	s_add_i32 s50, 0, 0x10000
	s_cmp_eq_u32 s49, 4
	s_cselect_b32 s29, s19, s25
	s_cselect_b32 s28, s18, s24
	s_cselect_b32 s27, s21, s48
	s_cselect_b32 s26, s20, s5
	v_lshl_add_u64 v[198:199], s[22:23], 0, v[138:139]
	s_add_i32 m0, s38, 0xc000
	ds_read_b128 v[162:165], v144
	ds_read_b128 v[166:169], v144 offset:1024
	ds_read_b128 v[170:173], v144 offset:2048
	ds_read_b128 v[174:177], v144 offset:3072
	ds_read_b128 v[178:181], v144 offset:4096
	ds_read_b128 v[182:185], v144 offset:5120
	ds_read_b128 v[186:189], v144 offset:6144
	ds_read_b128 v[190:193], v144 offset:7168
	global_load_lds_dwordx4 v[198:199], off
	v_lshl_add_u64 v[198:199], s[22:23], 0, v[140:141]
	s_add_i32 m0, s38, 0xe000
	s_nop 0
	global_load_lds_dwordx4 v[198:199], off
	s_waitcnt lgkmcnt(8)
	s_barrier
	s_waitcnt lgkmcnt(0)
	s_setprio 1
	s_waitcnt lgkmcnt(0)
	v_mfma_f32_16x16x32_bf16 v[126:129], v[146:149], v[162:165], v[126:129]
	v_mfma_f32_16x16x32_bf16 v[122:125], v[154:157], v[162:165], v[122:125]
	v_mfma_f32_16x16x32_bf16 v[118:121], v[146:149], v[170:173], v[118:121]
	v_mfma_f32_16x16x32_bf16 v[114:117], v[154:157], v[170:173], v[114:117]
	v_mfma_f32_16x16x32_bf16 v[106:109], v[146:149], v[178:181], v[106:109]
	v_mfma_f32_16x16x32_bf16 v[98:101], v[154:157], v[178:181], v[98:101]
	v_mfma_f32_16x16x32_bf16 v[90:93], v[146:149], v[186:189], v[90:93]
	v_mfma_f32_16x16x32_bf16 v[82:85], v[154:157], v[186:189], v[82:85]
	v_mfma_f32_16x16x32_bf16 v[126:129], v[150:153], v[166:169], v[126:129]
	v_mfma_f32_16x16x32_bf16 v[122:125], v[158:161], v[166:169], v[122:125]
	v_mfma_f32_16x16x32_bf16 v[118:121], v[150:153], v[174:177], v[118:121]
	v_mfma_f32_16x16x32_bf16 v[114:117], v[158:161], v[174:177], v[114:117]
	v_mfma_f32_16x16x32_bf16 v[106:109], v[150:153], v[182:185], v[106:109]
	v_mfma_f32_16x16x32_bf16 v[98:101], v[158:161], v[182:185], v[98:101]
	v_mfma_f32_16x16x32_bf16 v[90:93], v[150:153], v[190:193], v[90:93]
	v_mfma_f32_16x16x32_bf16 v[82:85], v[158:161], v[190:193], v[82:85]
	s_setprio 0
	s_barrier
	s_add_i32 s51, 0, 0x14000
	s_add_i32 s22, s50, s37
	s_mov_b32 m0, s22
	ds_read_b128 v[198:201], v131 offset:16384
	ds_read_b128 v[202:205], v131 offset:17408
	ds_read_b128 v[206:209], v131 offset:18432
	ds_read_b128 v[210:213], v131 offset:19456
	global_load_lds_dwordx4 v48, s[26:27]
	s_add_i32 m0, s22, 0x2000
	s_nop 0
	global_load_lds_dwordx4 v130, s[26:27]
	s_barrier
	s_waitcnt lgkmcnt(0)
	s_setprio 1
	s_waitcnt lgkmcnt(0)
	v_mfma_f32_16x16x32_bf16 v[110:113], v[198:201], v[162:165], v[110:113]
	v_mfma_f32_16x16x32_bf16 v[102:105], v[206:209], v[162:165], v[102:105]
	v_mfma_f32_16x16x32_bf16 v[94:97], v[198:201], v[170:173], v[94:97]
	v_mfma_f32_16x16x32_bf16 v[86:89], v[206:209], v[170:173], v[86:89]
	v_mfma_f32_16x16x32_bf16 v[78:81], v[198:201], v[178:181], v[78:81]
	v_mfma_f32_16x16x32_bf16 v[74:77], v[206:209], v[178:181], v[74:77]
	v_mfma_f32_16x16x32_bf16 v[70:73], v[198:201], v[186:189], v[70:73]
	v_mfma_f32_16x16x32_bf16 v[66:69], v[206:209], v[186:189], v[66:69]
	v_mfma_f32_16x16x32_bf16 v[110:113], v[202:205], v[166:169], v[110:113]
	v_mfma_f32_16x16x32_bf16 v[102:105], v[210:213], v[166:169], v[102:105]
	v_mfma_f32_16x16x32_bf16 v[94:97], v[202:205], v[174:177], v[94:97]
	v_mfma_f32_16x16x32_bf16 v[86:89], v[210:213], v[174:177], v[86:89]
	v_mfma_f32_16x16x32_bf16 v[78:81], v[202:205], v[182:185], v[78:81]
	v_mfma_f32_16x16x32_bf16 v[74:77], v[210:213], v[182:185], v[74:77]
	v_mfma_f32_16x16x32_bf16 v[70:73], v[202:205], v[190:193], v[70:73]
	v_mfma_f32_16x16x32_bf16 v[66:69], v[210:213], v[190:193], v[66:69]
	s_setprio 0
	s_mov_b32 m0, s38
	v_lshl_add_u64 v[218:219], s[28:29], 0, v[134:135]
	s_barrier
	ds_read_b128 v[162:165], v144 offset:16384
	ds_read_b128 v[166:169], v144 offset:17408
	ds_read_b128 v[170:173], v144 offset:18432
	ds_read_b128 v[174:177], v144 offset:19456
	ds_read_b128 v[178:181], v144 offset:20480
	ds_read_b128 v[182:185], v144 offset:21504
	ds_read_b128 v[186:189], v144 offset:22528
	ds_read_b128 v[190:193], v144 offset:23552
	global_load_lds_dwordx4 v[218:219], off
	v_lshl_add_u64 v[220:221], s[28:29], 0, v[132:133]
	s_mov_b32 m0, s39
	s_nop 0
	global_load_lds_dwordx4 v[220:221], off
	s_barrier
	s_waitcnt lgkmcnt(0)
	s_setprio 1
	s_waitcnt lgkmcnt(0)
	v_mfma_f32_16x16x32_bf16 v[62:65], v[146:149], v[162:165], v[62:65]
	v_mfma_f32_16x16x32_bf16 v[58:61], v[154:157], v[162:165], v[58:61]
	v_mfma_f32_16x16x32_bf16 v[54:57], v[146:149], v[170:173], v[54:57]
	v_mfma_f32_16x16x32_bf16 v[50:53], v[154:157], v[170:173], v[50:53]
	v_mfma_f32_16x16x32_bf16 v[36:39], v[146:149], v[178:181], v[36:39]
	v_mfma_f32_16x16x32_bf16 v[32:35], v[154:157], v[178:181], v[32:35]
	v_mfma_f32_16x16x32_bf16 v[20:23], v[146:149], v[186:189], v[20:23]
	v_mfma_f32_16x16x32_bf16 v[16:19], v[154:157], v[186:189], v[16:19]
	v_mfma_f32_16x16x32_bf16 v[62:65], v[150:153], v[166:169], v[62:65]
	v_mfma_f32_16x16x32_bf16 v[58:61], v[158:161], v[166:169], v[58:61]
	v_mfma_f32_16x16x32_bf16 v[54:57], v[150:153], v[174:177], v[54:57]
	v_mfma_f32_16x16x32_bf16 v[50:53], v[158:161], v[174:177], v[50:53]
	v_mfma_f32_16x16x32_bf16 v[36:39], v[150:153], v[182:185], v[36:39]
	v_mfma_f32_16x16x32_bf16 v[32:35], v[158:161], v[182:185], v[32:35]
	v_mfma_f32_16x16x32_bf16 v[20:23], v[150:153], v[190:193], v[20:23]
	v_mfma_f32_16x16x32_bf16 v[16:19], v[158:161], v[190:193], v[16:19]
	s_setprio 0
	s_barrier
	s_add_u32 s22, s26, 0x20000
	s_addc_u32 s23, s27, 0
	s_add_i32 s50, s51, s37
	s_mov_b32 m0, s50
	s_nop 0
	global_load_lds_dwordx4 v48, s[22:23]
	s_add_i32 m0, s50, 0x2000
	s_nop 0
	global_load_lds_dwordx4 v130, s[22:23]
	s_waitcnt vmcnt(6)
	s_barrier
	s_setprio 1
	v_mfma_f32_16x16x32_bf16 v[44:47], v[198:201], v[162:165], v[44:47]
	v_mfma_f32_16x16x32_bf16 v[40:43], v[206:209], v[162:165], v[40:43]
	v_mfma_f32_16x16x32_bf16 v[28:31], v[198:201], v[170:173], v[28:31]
	v_mfma_f32_16x16x32_bf16 v[24:27], v[206:209], v[170:173], v[24:27]
	v_mfma_f32_16x16x32_bf16 v[12:15], v[198:201], v[178:181], v[12:15]
	v_mfma_f32_16x16x32_bf16 v[8:11], v[206:209], v[178:181], v[8:11]
	v_mfma_f32_16x16x32_bf16 v[4:7], v[198:201], v[186:189], v[4:7]
	v_mfma_f32_16x16x32_bf16 v[0:3], v[206:209], v[186:189], v[0:3]
	v_mfma_f32_16x16x32_bf16 v[44:47], v[202:205], v[166:169], v[44:47]
	v_mfma_f32_16x16x32_bf16 v[40:43], v[210:213], v[166:169], v[40:43]
	v_mfma_f32_16x16x32_bf16 v[28:31], v[202:205], v[174:177], v[28:31]
	v_mfma_f32_16x16x32_bf16 v[24:27], v[210:213], v[174:177], v[24:27]
	v_mfma_f32_16x16x32_bf16 v[12:15], v[202:205], v[182:185], v[12:15]
	v_mfma_f32_16x16x32_bf16 v[8:11], v[210:213], v[182:185], v[8:11]
	v_mfma_f32_16x16x32_bf16 v[4:7], v[202:205], v[190:193], v[4:7]
	v_mfma_f32_16x16x32_bf16 v[0:3], v[210:213], v[190:193], v[0:3]
	s_setprio 0
	s_add_i32 s50, 0, 0x18000
	s_barrier
	ds_read_b128 v[146:149], v131 offset:32768
	ds_read_b128 v[150:153], v131 offset:33792
	ds_read_b128 v[154:157], v131 offset:34816
	ds_read_b128 v[158:161], v131 offset:35840
	s_add_u32 s22, s28, 0x30000
	s_addc_u32 s23, s29, 0
	s_mov_b32 m0, s40
	ds_read_b128 v[162:165], v144 offset:32768
	ds_read_b128 v[166:169], v144 offset:33792
	ds_read_b128 v[170:173], v144 offset:34816
	ds_read_b128 v[174:177], v144 offset:35840
	ds_read_b128 v[178:181], v144 offset:36864
	ds_read_b128 v[182:185], v144 offset:37888
	ds_read_b128 v[186:189], v144 offset:38912
	ds_read_b128 v[190:193], v144 offset:39936
	global_load_lds_dwordx4 v134, s[22:23]
	s_mov_b32 m0, s41
	s_nop 0
	global_load_lds_dwordx4 v132, s[22:23]
	s_waitcnt lgkmcnt(8)
	s_barrier
	s_waitcnt lgkmcnt(0)
	s_setprio 1
	s_waitcnt lgkmcnt(0)
	v_mfma_f32_16x16x32_bf16 v[126:129], v[146:149], v[162:165], v[126:129]
	v_mfma_f32_16x16x32_bf16 v[122:125], v[154:157], v[162:165], v[122:125]
	v_mfma_f32_16x16x32_bf16 v[118:121], v[146:149], v[170:173], v[118:121]
	v_mfma_f32_16x16x32_bf16 v[114:117], v[154:157], v[170:173], v[114:117]
	v_mfma_f32_16x16x32_bf16 v[106:109], v[146:149], v[178:181], v[106:109]
	v_mfma_f32_16x16x32_bf16 v[98:101], v[154:157], v[178:181], v[98:101]
	v_mfma_f32_16x16x32_bf16 v[90:93], v[146:149], v[186:189], v[90:93]
	v_mfma_f32_16x16x32_bf16 v[82:85], v[154:157], v[186:189], v[82:85]
	v_mfma_f32_16x16x32_bf16 v[126:129], v[150:153], v[166:169], v[126:129]
	v_mfma_f32_16x16x32_bf16 v[122:125], v[158:161], v[166:169], v[122:125]
	v_mfma_f32_16x16x32_bf16 v[118:121], v[150:153], v[174:177], v[118:121]
	v_mfma_f32_16x16x32_bf16 v[114:117], v[158:161], v[174:177], v[114:117]
	v_mfma_f32_16x16x32_bf16 v[106:109], v[150:153], v[182:185], v[106:109]
	v_mfma_f32_16x16x32_bf16 v[98:101], v[158:161], v[182:185], v[98:101]
	v_mfma_f32_16x16x32_bf16 v[90:93], v[150:153], v[190:193], v[90:93]
	v_mfma_f32_16x16x32_bf16 v[82:85], v[158:161], v[190:193], v[82:85]
	s_setprio 0
	s_barrier
	s_add_i32 s28, 0, 0x1c000
	s_add_i32 s22, s50, s37
	s_add_u32 s52, s26, s66
	s_addc_u32 s53, s27, s67
	s_mov_b32 m0, s22
	ds_read_b128 v[198:201], v131 offset:49152
	ds_read_b128 v[202:205], v131 offset:50176
	ds_read_b128 v[206:209], v131 offset:51200
	ds_read_b128 v[210:213], v131 offset:52224
	global_load_lds_dwordx4 v48, s[52:53]
	s_add_i32 m0, s22, 0x2000
	s_nop 0
	global_load_lds_dwordx4 v130, s[52:53]
	s_barrier
	s_waitcnt lgkmcnt(0)
	s_setprio 1
	s_waitcnt lgkmcnt(0)
	v_mfma_f32_16x16x32_bf16 v[110:113], v[198:201], v[162:165], v[110:113]
	v_mfma_f32_16x16x32_bf16 v[102:105], v[206:209], v[162:165], v[102:105]
	v_mfma_f32_16x16x32_bf16 v[94:97], v[198:201], v[170:173], v[94:97]
	v_mfma_f32_16x16x32_bf16 v[86:89], v[206:209], v[170:173], v[86:89]
	v_mfma_f32_16x16x32_bf16 v[78:81], v[198:201], v[178:181], v[78:81]
	v_mfma_f32_16x16x32_bf16 v[74:77], v[206:209], v[178:181], v[74:77]
	v_mfma_f32_16x16x32_bf16 v[70:73], v[198:201], v[186:189], v[70:73]
	v_mfma_f32_16x16x32_bf16 v[66:69], v[206:209], v[186:189], v[66:69]
	v_mfma_f32_16x16x32_bf16 v[110:113], v[202:205], v[166:169], v[110:113]
	v_mfma_f32_16x16x32_bf16 v[102:105], v[210:213], v[166:169], v[102:105]
	v_mfma_f32_16x16x32_bf16 v[94:97], v[202:205], v[174:177], v[94:97]
	v_mfma_f32_16x16x32_bf16 v[86:89], v[210:213], v[174:177], v[86:89]
	v_mfma_f32_16x16x32_bf16 v[78:81], v[202:205], v[182:185], v[78:81]
	v_mfma_f32_16x16x32_bf16 v[74:77], v[210:213], v[182:185], v[74:77]
	v_mfma_f32_16x16x32_bf16 v[70:73], v[202:205], v[190:193], v[70:73]
	v_mfma_f32_16x16x32_bf16 v[66:69], v[210:213], v[190:193], v[66:69]
	s_setprio 0
	s_mov_b32 m0, s42
	v_lshl_add_u64 v[214:215], v[218:219], 0, s[66:67]
	s_barrier
	ds_read_b128 v[162:165], v144 offset:49152
	ds_read_b128 v[166:169], v144 offset:50176
	ds_read_b128 v[170:173], v144 offset:51200
	ds_read_b128 v[174:177], v144 offset:52224
	ds_read_b128 v[178:181], v144 offset:53248
	ds_read_b128 v[182:185], v144 offset:54272
	ds_read_b128 v[186:189], v144 offset:55296
	ds_read_b128 v[190:193], v144 offset:56320
	global_load_lds_dwordx4 v[214:215], off
	v_lshl_add_u64 v[214:215], v[220:221], 0, s[66:67]
	s_mov_b32 m0, s43
	s_nop 0
	global_load_lds_dwordx4 v[214:215], off
	s_barrier
	s_waitcnt lgkmcnt(0)
	s_setprio 1
	s_waitcnt lgkmcnt(0)
	v_mfma_f32_16x16x32_bf16 v[62:65], v[146:149], v[162:165], v[62:65]
	v_mfma_f32_16x16x32_bf16 v[58:61], v[154:157], v[162:165], v[58:61]
	v_mfma_f32_16x16x32_bf16 v[54:57], v[146:149], v[170:173], v[54:57]
	v_mfma_f32_16x16x32_bf16 v[50:53], v[154:157], v[170:173], v[50:53]
	v_mfma_f32_16x16x32_bf16 v[36:39], v[146:149], v[178:181], v[36:39]
	v_mfma_f32_16x16x32_bf16 v[32:35], v[154:157], v[178:181], v[32:35]
	v_mfma_f32_16x16x32_bf16 v[20:23], v[146:149], v[186:189], v[20:23]
	v_mfma_f32_16x16x32_bf16 v[16:19], v[154:157], v[186:189], v[16:19]
	v_mfma_f32_16x16x32_bf16 v[62:65], v[150:153], v[166:169], v[62:65]
	v_mfma_f32_16x16x32_bf16 v[58:61], v[158:161], v[166:169], v[58:61]
	v_mfma_f32_16x16x32_bf16 v[54:57], v[150:153], v[174:177], v[54:57]
	v_mfma_f32_16x16x32_bf16 v[50:53], v[158:161], v[174:177], v[50:53]
	v_mfma_f32_16x16x32_bf16 v[36:39], v[150:153], v[182:185], v[36:39]
	v_mfma_f32_16x16x32_bf16 v[32:35], v[158:161], v[182:185], v[32:35]
	v_mfma_f32_16x16x32_bf16 v[20:23], v[150:153], v[190:193], v[20:23]
	v_mfma_f32_16x16x32_bf16 v[16:19], v[158:161], v[190:193], v[16:19]
	s_setprio 0
	s_barrier
	s_add_u32 s22, s26, 0x20080
	s_addc_u32 s23, s27, 0
	s_add_i32 s26, s28, s37
	s_mov_b32 m0, s26
	s_nop 0
	global_load_lds_dwordx4 v48, s[22:23]
	s_add_i32 m0, s26, 0x2000
	s_nop 0
	global_load_lds_dwordx4 v130, s[22:23]
	s_waitcnt vmcnt(6)
	s_barrier
	s_setprio 1
	v_mfma_f32_16x16x32_bf16 v[44:47], v[198:201], v[162:165], v[44:47]
	v_mfma_f32_16x16x32_bf16 v[40:43], v[206:209], v[162:165], v[40:43]
	v_mfma_f32_16x16x32_bf16 v[28:31], v[198:201], v[170:173], v[28:31]
	v_mfma_f32_16x16x32_bf16 v[24:27], v[206:209], v[170:173], v[24:27]
	v_mfma_f32_16x16x32_bf16 v[12:15], v[198:201], v[178:181], v[12:15]
	v_mfma_f32_16x16x32_bf16 v[8:11], v[206:209], v[178:181], v[8:11]
	v_mfma_f32_16x16x32_bf16 v[4:7], v[198:201], v[186:189], v[4:7]
	v_mfma_f32_16x16x32_bf16 v[0:3], v[206:209], v[186:189], v[0:3]
	v_mfma_f32_16x16x32_bf16 v[44:47], v[202:205], v[166:169], v[44:47]
	v_mfma_f32_16x16x32_bf16 v[40:43], v[210:213], v[166:169], v[40:43]
	v_mfma_f32_16x16x32_bf16 v[28:31], v[202:205], v[174:177], v[28:31]
	v_mfma_f32_16x16x32_bf16 v[24:27], v[210:213], v[174:177], v[24:27]
	v_mfma_f32_16x16x32_bf16 v[12:15], v[202:205], v[182:185], v[12:15]
	v_mfma_f32_16x16x32_bf16 v[8:11], v[210:213], v[182:185], v[8:11]
	v_mfma_f32_16x16x32_bf16 v[4:7], v[202:205], v[190:193], v[4:7]
	v_mfma_f32_16x16x32_bf16 v[0:3], v[210:213], v[190:193], v[0:3]
	s_setprio 0
	s_add_i32 s49, s49, 2
	s_add_u32 s5, s5, 0x100
	s_addc_u32 s48, s48, 0
	s_cmp_gt_u32 s49, 5
	s_mov_b64 s[22:23], s[24:25]
	s_barrier
	s_cbranch_scc0 .LBB0_641
	v_lshl_add_u32 v146, s47, 8, v142
	v_mov_b32_e32 v145, 0x240000
	v_ashrrev_i32_e32 v147, 31, v146
	v_mad_i64_i32 v[148:149], s[22:23], s46, v145, v[136:137]
	v_lshlrev_b64 v[150:151], 10, v[146:147]
	v_lshl_add_u64 v[150:151], v[148:149], 0, v[150:151]
	global_store_dwordx4 v[150:151], v[126:129], off
	global_store_dwordx4 v[150:151], v[122:125], off offset:64
	global_store_dwordx4 v[150:151], v[110:113], off offset:512
	global_store_dwordx4 v[150:151], v[102:105], off offset:576
	s_mov_b32 s5, 0x20000
	s_mov_b64 s[22:23], 0x20000
	v_or_b32_e32 v102, 16, v146
	v_ashrrev_i32_e32 v103, 31, v102
	v_lshlrev_b64 v[102:103], 10, v[102:103]
	v_lshl_add_u64 v[102:103], v[148:149], 0, v[102:103]
	global_store_dwordx4 v[102:103], v[118:121], off
	global_store_dwordx4 v[102:103], v[114:117], off offset:64
	global_store_dwordx4 v[102:103], v[94:97], off offset:512
	global_store_dwordx4 v[102:103], v[86:89], off offset:576
	s_mov_b32 s46, s4
	s_mov_b32 s47, s45
	v_or_b32_e32 v86, 32, v146
	v_ashrrev_i32_e32 v87, 31, v86
	v_lshlrev_b64 v[86:87], 10, v[86:87]
	v_lshl_add_u64 v[86:87], v[148:149], 0, v[86:87]
	global_store_dwordx4 v[86:87], v[106:109], off
	global_store_dwordx4 v[86:87], v[98:101], off offset:64
	global_store_dwordx4 v[86:87], v[78:81], off offset:512
	global_store_dwordx4 v[86:87], v[74:77], off offset:576
	s_mov_b64 s[24:25], s[20:21]
	s_nop 0
	v_or_b32_e32 v74, 48, v146
	v_ashrrev_i32_e32 v75, 31, v74
	v_lshlrev_b64 v[74:75], 10, v[74:75]
	v_lshl_add_u64 v[74:75], v[148:149], 0, v[74:75]
	global_store_dwordx4 v[74:75], v[90:93], off
	global_store_dwordx4 v[74:75], v[82:85], off offset:64
	global_store_dwordx4 v[74:75], v[70:73], off offset:512
	global_store_dwordx4 v[74:75], v[66:69], off offset:576
	s_nop 1
	v_add_co_u32_e32 v68, vcc, s5, v150
	s_mov_b32 s5, 0x24000
	s_nop 0
	v_addc_co_u32_e32 v69, vcc, 0, v151, vcc
	v_lshl_add_u64 v[66:67], v[150:151], 0, s[22:23]
	global_store_dwordx4 v[68:69], v[62:65], off
	global_store_dwordx4 v[66:67], v[58:61], off offset:64
	global_store_dwordx4 v[66:67], v[44:47], off offset:512
	global_store_dwordx4 v[66:67], v[40:43], off offset:576
	s_mov_b64 s[22:23], 0x24000
	s_nop 0
	v_add_co_u32_e32 v42, vcc, s5, v150
	s_mov_b32 s5, 0x28000
	s_nop 0
	v_addc_co_u32_e32 v43, vcc, 0, v151, vcc
	v_lshl_add_u64 v[40:41], v[150:151], 0, s[22:23]
	global_store_dwordx4 v[42:43], v[54:57], off
	global_store_dwordx4 v[40:41], v[50:53], off offset:64
	global_store_dwordx4 v[40:41], v[28:31], off offset:512
	global_store_dwordx4 v[40:41], v[24:27], off offset:576
	s_mov_b64 s[22:23], 0x28000
	s_nop 0
	v_add_co_u32_e32 v26, vcc, s5, v150
	v_lshl_add_u64 v[24:25], v[150:151], 0, s[22:23]
	s_nop 0
	v_addc_co_u32_e32 v27, vcc, 0, v151, vcc
	global_store_dwordx4 v[26:27], v[36:39], off
	global_store_dwordx4 v[24:25], v[32:35], off offset:64
	global_store_dwordx4 v[24:25], v[12:15], off offset:512
	global_store_dwordx4 v[24:25], v[8:11], off offset:576
	s_mov_b64 s[22:23], 0x2c000
	s_nop 0
	v_add_co_u32_e32 v10, vcc, 0x2c000, v150
	v_lshl_add_u64 v[8:9], v[150:151], 0, s[22:23]
	s_nop 0
	v_addc_co_u32_e32 v11, vcc, 0, v151, vcc
	s_and_b64 vcc, exec, s[0:1]
	s_mov_b64 s[22:23], s[18:19]
	global_store_dwordx4 v[10:11], v[20:23], off
	global_store_dwordx4 v[8:9], v[16:19], off offset:64
	global_store_dwordx4 v[8:9], v[4:7], off offset:512
	global_store_dwordx4 v[8:9], v[0:3], off offset:576
	s_cbranch_vccz .LBB0_638
	s_waitcnt vmcnt(0)
	s_cmpk_gt_u32 s30, 0xff
	s_cbranch_scc1 .LBB0_645
	s_barrier

.LBB0_822:
	ds_read_b128 v[142:145], v131
	ds_read_b128 v[150:153], v131 offset:1024
	ds_read_b128 v[154:157], v131 offset:2048
	ds_read_b128 v[158:161], v131 offset:3072
	s_add_u32 s12, s10, 0x100
	s_addc_u32 s13, s11, 0
	s_add_i32 s42, 0, 0x10000
	s_cmp_eq_u32 s41, 8
	s_cselect_b32 s17, s5, s13
	s_cselect_b32 s16, s4, s12
	s_cselect_b32 s15, s7, s40
	s_cselect_b32 s14, s6, s39
	v_lshl_add_u64 v[198:199], s[10:11], 0, v[138:139]
	s_add_i32 m0, s24, 0xc000
	ds_read_b128 v[162:165], v149
	ds_read_b128 v[166:169], v149 offset:1024
	ds_read_b128 v[170:173], v149 offset:2048
	ds_read_b128 v[174:177], v149 offset:3072
	ds_read_b128 v[178:181], v149 offset:4096
	ds_read_b128 v[182:185], v149 offset:5120
	ds_read_b128 v[186:189], v149 offset:6144
	ds_read_b128 v[190:193], v149 offset:7168
	global_load_lds_dwordx4 v[198:199], off
	v_lshl_add_u64 v[198:199], s[10:11], 0, v[140:141]
	s_add_i32 m0, s24, 0xe000
	s_nop 0
	global_load_lds_dwordx4 v[198:199], off
	s_waitcnt lgkmcnt(8)
	s_barrier
	s_waitcnt lgkmcnt(0)
	s_setprio 1
	s_waitcnt lgkmcnt(0)
	v_mfma_f32_16x16x32_bf16 v[126:129], v[142:145], v[162:165], v[126:129]
	v_mfma_f32_16x16x32_bf16 v[122:125], v[154:157], v[162:165], v[122:125]
	v_mfma_f32_16x16x32_bf16 v[110:113], v[142:145], v[170:173], v[110:113]
	v_mfma_f32_16x16x32_bf16 v[106:109], v[154:157], v[170:173], v[106:109]
	v_mfma_f32_16x16x32_bf16 v[94:97], v[142:145], v[178:181], v[94:97]
	v_mfma_f32_16x16x32_bf16 v[90:93], v[154:157], v[178:181], v[90:93]
	v_mfma_f32_16x16x32_bf16 v[78:81], v[142:145], v[186:189], v[78:81]
	v_mfma_f32_16x16x32_bf16 v[74:77], v[154:157], v[186:189], v[74:77]
	v_mfma_f32_16x16x32_bf16 v[126:129], v[150:153], v[166:169], v[126:129]
	v_mfma_f32_16x16x32_bf16 v[122:125], v[158:161], v[166:169], v[122:125]
	v_mfma_f32_16x16x32_bf16 v[110:113], v[150:153], v[174:177], v[110:113]
	v_mfma_f32_16x16x32_bf16 v[106:109], v[158:161], v[174:177], v[106:109]
	v_mfma_f32_16x16x32_bf16 v[94:97], v[150:153], v[182:185], v[94:97]
	v_mfma_f32_16x16x32_bf16 v[90:93], v[158:161], v[182:185], v[90:93]
	v_mfma_f32_16x16x32_bf16 v[78:81], v[150:153], v[190:193], v[78:81]
	v_mfma_f32_16x16x32_bf16 v[74:77], v[158:161], v[190:193], v[74:77]
	s_setprio 0
	s_barrier
	s_add_i32 s43, 0, 0x14000
	s_add_i32 s10, s42, s23
	s_mov_b32 m0, s10
	ds_read_b128 v[198:201], v131 offset:16384
	ds_read_b128 v[202:205], v131 offset:17408
	ds_read_b128 v[206:209], v131 offset:18432
	ds_read_b128 v[210:213], v131 offset:19456
	global_load_lds_dwordx4 v134, s[14:15]
	s_add_i32 m0, s10, 0x2000
	s_nop 0
	global_load_lds_dwordx4 v130, s[14:15]
	s_barrier
	s_waitcnt lgkmcnt(0)
	s_setprio 1
	s_waitcnt lgkmcnt(0)
	v_mfma_f32_16x16x32_bf16 v[118:121], v[198:201], v[162:165], v[118:121]
	v_mfma_f32_16x16x32_bf16 v[114:117], v[206:209], v[162:165], v[114:117]
	v_mfma_f32_16x16x32_bf16 v[102:105], v[198:201], v[170:173], v[102:105]
	v_mfma_f32_16x16x32_bf16 v[98:101], v[206:209], v[170:173], v[98:101]
	v_mfma_f32_16x16x32_bf16 v[86:89], v[198:201], v[178:181], v[86:89]
	v_mfma_f32_16x16x32_bf16 v[82:85], v[206:209], v[178:181], v[82:85]
	v_mfma_f32_16x16x32_bf16 v[70:73], v[198:201], v[186:189], v[70:73]
	v_mfma_f32_16x16x32_bf16 v[66:69], v[206:209], v[186:189], v[66:69]
	v_mfma_f32_16x16x32_bf16 v[118:121], v[202:205], v[166:169], v[118:121]
	v_mfma_f32_16x16x32_bf16 v[114:117], v[210:213], v[166:169], v[114:117]
	v_mfma_f32_16x16x32_bf16 v[102:105], v[202:205], v[174:177], v[102:105]
	v_mfma_f32_16x16x32_bf16 v[98:101], v[210:213], v[174:177], v[98:101]
	v_mfma_f32_16x16x32_bf16 v[86:89], v[202:205], v[182:185], v[86:89]
	v_mfma_f32_16x16x32_bf16 v[82:85], v[210:213], v[182:185], v[82:85]
	v_mfma_f32_16x16x32_bf16 v[70:73], v[202:205], v[190:193], v[70:73]
	v_mfma_f32_16x16x32_bf16 v[66:69], v[210:213], v[190:193], v[66:69]
	s_setprio 0
	s_mov_b32 m0, s24
	v_lshl_add_u64 v[218:219], s[16:17], 0, v[136:137]
	s_barrier
	ds_read_b128 v[162:165], v149 offset:16384
	ds_read_b128 v[166:169], v149 offset:17408
	ds_read_b128 v[170:173], v149 offset:18432
	ds_read_b128 v[174:177], v149 offset:19456
	ds_read_b128 v[178:181], v149 offset:20480
	ds_read_b128 v[182:185], v149 offset:21504
	ds_read_b128 v[186:189], v149 offset:22528
	ds_read_b128 v[190:193], v149 offset:23552
	global_load_lds_dwordx4 v[218:219], off
	v_lshl_add_u64 v[220:221], s[16:17], 0, v[132:133]
	s_mov_b32 m0, s25
	s_nop 0
	global_load_lds_dwordx4 v[220:221], off
	s_barrier
	s_waitcnt lgkmcnt(0)
	s_setprio 1
	s_waitcnt lgkmcnt(0)
	v_mfma_f32_16x16x32_bf16 v[62:65], v[142:145], v[162:165], v[62:65]
	v_mfma_f32_16x16x32_bf16 v[58:61], v[154:157], v[162:165], v[58:61]
	v_mfma_f32_16x16x32_bf16 v[44:47], v[142:145], v[170:173], v[44:47]
	v_mfma_f32_16x16x32_bf16 v[40:43], v[154:157], v[170:173], v[40:43]
	v_mfma_f32_16x16x32_bf16 v[28:31], v[142:145], v[178:181], v[28:31]
	v_mfma_f32_16x16x32_bf16 v[24:27], v[154:157], v[178:181], v[24:27]
	v_mfma_f32_16x16x32_bf16 v[12:15], v[142:145], v[186:189], v[12:15]
	v_mfma_f32_16x16x32_bf16 v[8:11], v[154:157], v[186:189], v[8:11]
	v_mfma_f32_16x16x32_bf16 v[62:65], v[150:153], v[166:169], v[62:65]
	v_mfma_f32_16x16x32_bf16 v[58:61], v[158:161], v[166:169], v[58:61]
	v_mfma_f32_16x16x32_bf16 v[44:47], v[150:153], v[174:177], v[44:47]
	v_mfma_f32_16x16x32_bf16 v[40:43], v[158:161], v[174:177], v[40:43]
	v_mfma_f32_16x16x32_bf16 v[28:31], v[150:153], v[182:185], v[28:31]
	v_mfma_f32_16x16x32_bf16 v[24:27], v[158:161], v[182:185], v[24:27]
	v_mfma_f32_16x16x32_bf16 v[12:15], v[150:153], v[190:193], v[12:15]
	v_mfma_f32_16x16x32_bf16 v[8:11], v[158:161], v[190:193], v[8:11]
	s_setprio 0
	s_barrier
	s_add_u32 s10, s14, 0x30000
	s_addc_u32 s11, s15, 0
	s_add_i32 s42, s43, s23
	s_mov_b32 m0, s42
	s_nop 0
	global_load_lds_dwordx4 v134, s[10:11]
	s_add_i32 m0, s42, 0x2000
	s_nop 0
	global_load_lds_dwordx4 v130, s[10:11]
	s_waitcnt vmcnt(6)
	s_barrier
	s_setprio 1
	v_mfma_f32_16x16x32_bf16 v[54:57], v[198:201], v[162:165], v[54:57]
	v_mfma_f32_16x16x32_bf16 v[50:53], v[206:209], v[162:165], v[50:53]
	v_mfma_f32_16x16x32_bf16 v[36:39], v[198:201], v[170:173], v[36:39]
	v_mfma_f32_16x16x32_bf16 v[32:35], v[206:209], v[170:173], v[32:35]
	v_mfma_f32_16x16x32_bf16 v[20:23], v[198:201], v[178:181], v[20:23]
	v_mfma_f32_16x16x32_bf16 v[16:19], v[206:209], v[178:181], v[16:19]
	v_mfma_f32_16x16x32_bf16 v[4:7], v[198:201], v[186:189], v[4:7]
	v_mfma_f32_16x16x32_bf16 v[0:3], v[206:209], v[186:189], v[0:3]
	v_mfma_f32_16x16x32_bf16 v[54:57], v[202:205], v[166:169], v[54:57]
	v_mfma_f32_16x16x32_bf16 v[50:53], v[210:213], v[166:169], v[50:53]
	v_mfma_f32_16x16x32_bf16 v[36:39], v[202:205], v[174:177], v[36:39]
	v_mfma_f32_16x16x32_bf16 v[32:35], v[210:213], v[174:177], v[32:35]
	v_mfma_f32_16x16x32_bf16 v[20:23], v[202:205], v[182:185], v[20:23]
	v_mfma_f32_16x16x32_bf16 v[16:19], v[210:213], v[182:185], v[16:19]
	v_mfma_f32_16x16x32_bf16 v[4:7], v[202:205], v[190:193], v[4:7]
	v_mfma_f32_16x16x32_bf16 v[0:3], v[210:213], v[190:193], v[0:3]
	s_setprio 0
	s_add_i32 s42, 0, 0x18000
	s_barrier
	ds_read_b128 v[142:145], v131 offset:32768
	ds_read_b128 v[150:153], v131 offset:33792
	ds_read_b128 v[154:157], v131 offset:34816
	ds_read_b128 v[158:161], v131 offset:35840
	s_add_u32 s10, s16, 0x30000
	s_addc_u32 s11, s17, 0
	s_mov_b32 m0, s26
	ds_read_b128 v[162:165], v149 offset:32768
	ds_read_b128 v[166:169], v149 offset:33792
	ds_read_b128 v[170:173], v149 offset:34816
	ds_read_b128 v[174:177], v149 offset:35840
	ds_read_b128 v[178:181], v149 offset:36864
	ds_read_b128 v[182:185], v149 offset:37888
	ds_read_b128 v[186:189], v149 offset:38912
	ds_read_b128 v[190:193], v149 offset:39936
	global_load_lds_dwordx4 v136, s[10:11]
	s_mov_b32 m0, s27
	s_nop 0
	global_load_lds_dwordx4 v132, s[10:11]
	s_waitcnt lgkmcnt(8)
	s_barrier
	s_waitcnt lgkmcnt(0)
	s_setprio 1
	s_waitcnt lgkmcnt(0)
	v_mfma_f32_16x16x32_bf16 v[126:129], v[142:145], v[162:165], v[126:129]
	v_mfma_f32_16x16x32_bf16 v[122:125], v[154:157], v[162:165], v[122:125]
	v_mfma_f32_16x16x32_bf16 v[110:113], v[142:145], v[170:173], v[110:113]
	v_mfma_f32_16x16x32_bf16 v[106:109], v[154:157], v[170:173], v[106:109]
	v_mfma_f32_16x16x32_bf16 v[94:97], v[142:145], v[178:181], v[94:97]
	v_mfma_f32_16x16x32_bf16 v[90:93], v[154:157], v[178:181], v[90:93]
	v_mfma_f32_16x16x32_bf16 v[78:81], v[142:145], v[186:189], v[78:81]
	v_mfma_f32_16x16x32_bf16 v[74:77], v[154:157], v[186:189], v[74:77]
	v_mfma_f32_16x16x32_bf16 v[126:129], v[150:153], v[166:169], v[126:129]
	v_mfma_f32_16x16x32_bf16 v[122:125], v[158:161], v[166:169], v[122:125]
	v_mfma_f32_16x16x32_bf16 v[110:113], v[150:153], v[174:177], v[110:113]
	v_mfma_f32_16x16x32_bf16 v[106:109], v[158:161], v[174:177], v[106:109]
	v_mfma_f32_16x16x32_bf16 v[94:97], v[150:153], v[182:185], v[94:97]
	v_mfma_f32_16x16x32_bf16 v[90:93], v[158:161], v[182:185], v[90:93]
	v_mfma_f32_16x16x32_bf16 v[78:81], v[150:153], v[190:193], v[78:81]
	v_mfma_f32_16x16x32_bf16 v[74:77], v[158:161], v[190:193], v[74:77]
	s_setprio 0
	s_barrier
	s_add_i32 s16, 0, 0x1c000
	s_add_i32 s10, s42, s23
	s_add_u32 s72, s14, s66
	s_addc_u32 s73, s15, s67
	s_mov_b32 m0, s10
	ds_read_b128 v[198:201], v131 offset:49152
	ds_read_b128 v[202:205], v131 offset:50176
	ds_read_b128 v[206:209], v131 offset:51200
	ds_read_b128 v[210:213], v131 offset:52224
	global_load_lds_dwordx4 v134, s[72:73]
	s_add_i32 m0, s10, 0x2000
	s_nop 0
	global_load_lds_dwordx4 v130, s[72:73]
	s_barrier
	s_waitcnt lgkmcnt(0)
	s_setprio 1
	s_waitcnt lgkmcnt(0)
	v_mfma_f32_16x16x32_bf16 v[118:121], v[198:201], v[162:165], v[118:121]
	v_mfma_f32_16x16x32_bf16 v[114:117], v[206:209], v[162:165], v[114:117]
	v_mfma_f32_16x16x32_bf16 v[102:105], v[198:201], v[170:173], v[102:105]
	v_mfma_f32_16x16x32_bf16 v[98:101], v[206:209], v[170:173], v[98:101]
	v_mfma_f32_16x16x32_bf16 v[86:89], v[198:201], v[178:181], v[86:89]
	v_mfma_f32_16x16x32_bf16 v[82:85], v[206:209], v[178:181], v[82:85]
	v_mfma_f32_16x16x32_bf16 v[70:73], v[198:201], v[186:189], v[70:73]
	v_mfma_f32_16x16x32_bf16 v[66:69], v[206:209], v[186:189], v[66:69]
	v_mfma_f32_16x16x32_bf16 v[118:121], v[202:205], v[166:169], v[118:121]
	v_mfma_f32_16x16x32_bf16 v[114:117], v[210:213], v[166:169], v[114:117]
	v_mfma_f32_16x16x32_bf16 v[102:105], v[202:205], v[174:177], v[102:105]
	v_mfma_f32_16x16x32_bf16 v[98:101], v[210:213], v[174:177], v[98:101]
	v_mfma_f32_16x16x32_bf16 v[86:89], v[202:205], v[182:185], v[86:89]
	v_mfma_f32_16x16x32_bf16 v[82:85], v[210:213], v[182:185], v[82:85]
	v_mfma_f32_16x16x32_bf16 v[70:73], v[202:205], v[190:193], v[70:73]
	v_mfma_f32_16x16x32_bf16 v[66:69], v[210:213], v[190:193], v[66:69]
	s_setprio 0
	s_mov_b32 m0, s28
	v_lshl_add_u64 v[214:215], v[218:219], 0, s[66:67]
	s_barrier
	ds_read_b128 v[162:165], v149 offset:49152
	ds_read_b128 v[166:169], v149 offset:50176
	ds_read_b128 v[170:173], v149 offset:51200
	ds_read_b128 v[174:177], v149 offset:52224
	ds_read_b128 v[178:181], v149 offset:53248
	ds_read_b128 v[182:185], v149 offset:54272
	ds_read_b128 v[186:189], v149 offset:55296
	ds_read_b128 v[190:193], v149 offset:56320
	global_load_lds_dwordx4 v[214:215], off
	v_lshl_add_u64 v[214:215], v[220:221], 0, s[66:67]
	s_mov_b32 m0, s29
	s_nop 0
	global_load_lds_dwordx4 v[214:215], off
	s_barrier
	s_waitcnt lgkmcnt(0)
	s_setprio 1
	s_waitcnt lgkmcnt(0)
	v_mfma_f32_16x16x32_bf16 v[62:65], v[142:145], v[162:165], v[62:65]
	v_mfma_f32_16x16x32_bf16 v[58:61], v[154:157], v[162:165], v[58:61]
	v_mfma_f32_16x16x32_bf16 v[44:47], v[142:145], v[170:173], v[44:47]
	v_mfma_f32_16x16x32_bf16 v[40:43], v[154:157], v[170:173], v[40:43]
	v_mfma_f32_16x16x32_bf16 v[28:31], v[142:145], v[178:181], v[28:31]
	v_mfma_f32_16x16x32_bf16 v[24:27], v[154:157], v[178:181], v[24:27]
	v_mfma_f32_16x16x32_bf16 v[12:15], v[142:145], v[186:189], v[12:15]
	v_mfma_f32_16x16x32_bf16 v[8:11], v[154:157], v[186:189], v[8:11]
	v_mfma_f32_16x16x32_bf16 v[62:65], v[150:153], v[166:169], v[62:65]
	v_mfma_f32_16x16x32_bf16 v[58:61], v[158:161], v[166:169], v[58:61]
	v_mfma_f32_16x16x32_bf16 v[44:47], v[150:153], v[174:177], v[44:47]
	v_mfma_f32_16x16x32_bf16 v[40:43], v[158:161], v[174:177], v[40:43]
	v_mfma_f32_16x16x32_bf16 v[28:31], v[150:153], v[182:185], v[28:31]
	v_mfma_f32_16x16x32_bf16 v[24:27], v[158:161], v[182:185], v[24:27]
	v_mfma_f32_16x16x32_bf16 v[12:15], v[150:153], v[190:193], v[12:15]
	v_mfma_f32_16x16x32_bf16 v[8:11], v[158:161], v[190:193], v[8:11]
	s_setprio 0
	s_barrier
	s_add_u32 s10, s14, 0x30080
	s_addc_u32 s11, s15, 0
	s_add_i32 s14, s16, s23
	s_mov_b32 m0, s14
	s_nop 0
	global_load_lds_dwordx4 v134, s[10:11]
	s_add_i32 m0, s14, 0x2000
	s_nop 0
	global_load_lds_dwordx4 v130, s[10:11]
	s_waitcnt vmcnt(6)
	s_barrier
	s_setprio 1
	v_mfma_f32_16x16x32_bf16 v[54:57], v[198:201], v[162:165], v[54:57]
	v_mfma_f32_16x16x32_bf16 v[50:53], v[206:209], v[162:165], v[50:53]
	v_mfma_f32_16x16x32_bf16 v[36:39], v[198:201], v[170:173], v[36:39]
	v_mfma_f32_16x16x32_bf16 v[32:35], v[206:209], v[170:173], v[32:35]
	v_mfma_f32_16x16x32_bf16 v[20:23], v[198:201], v[178:181], v[20:23]
	v_mfma_f32_16x16x32_bf16 v[16:19], v[206:209], v[178:181], v[16:19]
	v_mfma_f32_16x16x32_bf16 v[4:7], v[198:201], v[186:189], v[4:7]
	v_mfma_f32_16x16x32_bf16 v[0:3], v[206:209], v[186:189], v[0:3]
	v_mfma_f32_16x16x32_bf16 v[54:57], v[202:205], v[166:169], v[54:57]
	v_mfma_f32_16x16x32_bf16 v[50:53], v[210:213], v[166:169], v[50:53]
	v_mfma_f32_16x16x32_bf16 v[36:39], v[202:205], v[174:177], v[36:39]
	v_mfma_f32_16x16x32_bf16 v[32:35], v[210:213], v[174:177], v[32:35]
	v_mfma_f32_16x16x32_bf16 v[20:23], v[202:205], v[182:185], v[20:23]
	v_mfma_f32_16x16x32_bf16 v[16:19], v[210:213], v[182:185], v[16:19]
	v_mfma_f32_16x16x32_bf16 v[4:7], v[202:205], v[190:193], v[4:7]
	v_mfma_f32_16x16x32_bf16 v[0:3], v[210:213], v[190:193], v[0:3]
	s_setprio 0
	s_add_i32 s41, s41, 2
	s_add_u32 s39, s39, 0x100
	s_addc_u32 s40, s40, 0
	s_cmp_gt_u32 s41, 9
	s_mov_b64 s[10:11], s[12:13]
	s_barrier
	s_cbranch_scc0 .LBB0_822
	v_lshl_add_u32 v142, s38, 8, v146
	v_ashrrev_i32_e32 v143, 31, v142
	v_lshlrev_b64 v[144:145], 14, v[142:143]
	v_mul_f32_e32 v143, 0x3d372713, v126
	v_mul_f32_e32 v143, v126, v143
	v_fma_f32 v143, v126, v143, v126
	v_mul_f32_e32 v143, 0xbfcc422a, v143
	v_mul_f32_e32 v143, 0x3fb8aa3b, v143
	v_exp_f32_e32 v150, v143
	v_mul_f32_e32 v143, 0x3d372713, v122
	v_mul_f32_e32 v143, v122, v143
	v_fma_f32 v143, v122, v143, v122
	v_mul_f32_e32 v143, 0xbfcc422a, v143
	v_mul_f32_e32 v143, 0x3fb8aa3b, v143
	v_exp_f32_e32 v152, v143
	v_mul_f32_e32 v143, 0x3d372713, v127
	v_mul_f32_e32 v143, v127, v143
	v_fma_f32 v143, v127, v143, v127
	v_mul_f32_e32 v143, 0xbfcc422a, v143
	v_mul_f32_e32 v143, 0x3fb8aa3b, v143
	v_exp_f32_e32 v151, v143
	v_lshl_or_b32 v154, s37, 8, v148
	s_lshl_b32 s10, s36, 4
	s_ashr_i32 s11, s10, 31
	v_pk_add_f32 v[150:151], v[150:151], 1.0 op_sel_hi:[1,0]
	s_lshl_b64 s[10:11], s[10:11], 1
	s_mov_b32 s36, s31
	s_mov_b32 s37, s35
	s_mov_b32 s38, s34
	v_rcp_f32_e32 v143, v151
	s_nop 0
	v_mul_f32_e32 v143, v127, v143
	s_nop 0
	v_rcp_f32_e32 v127, v150
	s_nop 0
	v_mul_f32_e32 v150, v126, v127
	v_mul_f32_e32 v126, 0x3d372713, v123
	v_mul_f32_e32 v126, v123, v126
	v_fma_f32 v126, v123, v126, v123
	v_mul_f32_e32 v126, 0xbfcc422a, v126
	v_mul_f32_e32 v126, 0x3fb8aa3b, v126
	v_exp_f32_e32 v153, v126
	v_cvt_pk_bf16_f32 v150, v150, v143
	v_pk_add_f32 v[126:127], v[152:153], 1.0 op_sel_hi:[1,0]
	s_nop 0
	s_nop 0
	v_rcp_f32_e32 v151, v127
	s_nop 0
	v_mul_f32_e32 v152, v123, v151
	s_nop 0
	v_rcp_f32_e32 v123, v126
	s_nop 0
	v_mul_f32_e32 v153, v122, v123
	v_mul_f32_e32 v123, 0x3d372713, v124
	v_mul_f32_e32 v123, v124, v123
	v_fma_f32 v123, v124, v123, v124
	v_mul_f32_e32 v123, 0xbfcc422a, v123
	v_mul_f32_e32 v123, 0x3fb8aa3b, v123
	v_mul_f32_e32 v122, 0x3d372713, v128
	v_exp_f32_e32 v126, v123
	v_mul_f32_e32 v123, 0x3d372713, v129
	v_mul_f32_e32 v122, v128, v122
	v_mul_f32_e32 v123, v129, v123
	v_fma_f32 v122, v128, v122, v128
	v_fma_f32 v123, v129, v123, v129
	v_mul_f32_e32 v122, 0xbfcc422a, v122
	v_mul_f32_e32 v123, 0xbfcc422a, v123
	v_mul_f32_e32 v122, 0x3fb8aa3b, v122
	v_mul_f32_e32 v123, 0x3fb8aa3b, v123
	v_exp_f32_e32 v122, v122
	v_exp_f32_e32 v123, v123
	v_cvt_pk_bf16_f32 v152, v153, v152
	v_pk_add_f32 v[122:123], v[122:123], 1.0 op_sel_hi:[1,0]
	s_nop 0
	s_nop 0
	v_rcp_f32_e32 v127, v123
	s_nop 0
	v_mul_f32_e32 v129, v129, v127
	s_nop 0
	v_rcp_f32_e32 v123, v122
	s_nop 0
	v_mul_f32_e32 v128, v128, v123
	v_mul_f32_e32 v122, 0x3d372713, v125
	v_mul_f32_e32 v122, v125, v122
	v_fma_f32 v122, v125, v122, v125
	v_mul_f32_e32 v122, 0xbfcc422a, v122
	v_mul_f32_e32 v122, 0x3fb8aa3b, v122
	v_exp_f32_e32 v127, v122
	s_nop 0
	v_pk_add_f32 v[122:123], v[126:127], 1.0 op_sel_hi:[1,0]
	s_nop 0
	s_nop 0
	v_rcp_f32_e32 v126, v123
	s_nop 0
	v_mul_f32_e32 v123, v125, v126
	s_nop 0
	v_ashrrev_i32_e32 v126, 4, v154
	v_ashrrev_i32_e32 v127, 31, v126
	v_rcp_f32_e32 v125, v122
	s_nop 0
	v_mul_f32_e32 v122, v124, v125
	v_lshlrev_b64 v[124:125], 9, v[126:127]
	v_mul_f32_e32 v127, 0x3d372713, v118
	v_cvt_pk_bf16_f32 v153, v122, v123
	v_lshl_add_u64 v[122:123], s[0:1], 0, v[144:145]
	v_mul_f32_e32 v127, v118, v127
	v_cvt_pk_bf16_f32 v151, v128, v129
	v_lshl_add_u64 v[128:129], v[122:123], 0, v[124:125]
	v_fma_f32 v127, v118, v127, v118
	v_lshl_add_u64 v[128:129], v[128:129], 0, s[10:11]
	v_mul_f32_e32 v127, 0xbfcc422a, v127
	v_lshl_add_u64 v[128:129], v[128:129], 0, v[48:49]
	v_mul_f32_e32 v127, 0x3fb8aa3b, v127
	global_store_dwordx4 v[128:129], v[150:153], off
	v_exp_f32_e32 v128, v127
	v_mul_f32_e32 v127, 0x3d372713, v114
	v_mul_f32_e32 v127, v114, v127
	v_fma_f32 v127, v114, v127, v114
	v_mul_f32_e32 v127, 0xbfcc422a, v127
	v_mul_f32_e32 v127, 0x3fb8aa3b, v127
	v_exp_f32_e32 v144, v127
	v_mul_f32_e32 v127, 0x3d372713, v119
	v_mul_f32_e32 v127, v119, v127
	v_fma_f32 v127, v119, v127, v119
	v_mul_f32_e32 v127, 0xbfcc422a, v127
	v_mul_f32_e32 v127, 0x3fb8aa3b, v127
	v_exp_f32_e32 v129, v127
	s_nop 0
	v_pk_add_f32 v[128:129], v[128:129], 1.0 op_sel_hi:[1,0]
	s_nop 0
	s_nop 0
	v_rcp_f32_e32 v127, v129
	s_nop 0
	v_mul_f32_e32 v127, v119, v127
	s_nop 0
	v_rcp_f32_e32 v119, v128
	s_nop 0
	v_mul_f32_e32 v128, v118, v119
	v_mul_f32_e32 v118, 0x3d372713, v115
	v_mul_f32_e32 v118, v115, v118
	v_fma_f32 v118, v115, v118, v115
	v_mul_f32_e32 v118, 0xbfcc422a, v118
	v_mul_f32_e32 v118, 0x3fb8aa3b, v118
	v_exp_f32_e32 v145, v118
	s_nop 0
	v_pk_add_f32 v[118:119], v[144:145], 1.0 op_sel_hi:[1,0]
	s_nop 0
	s_nop 0
	v_rcp_f32_e32 v129, v119
	s_nop 0
	v_mul_f32_e32 v129, v115, v129
	s_nop 0
	v_rcp_f32_e32 v115, v118
	s_nop 0
	v_mul_f32_e32 v143, v114, v115
	v_mul_f32_e32 v115, 0x3d372713, v116
	v_mul_f32_e32 v115, v116, v115
	v_fma_f32 v115, v116, v115, v116
	v_mul_f32_e32 v115, 0xbfcc422a, v115
	v_mul_f32_e32 v115, 0x3fb8aa3b, v115
	v_mul_f32_e32 v114, 0x3d372713, v120
	v_exp_f32_e32 v118, v115
	v_mul_f32_e32 v115, 0x3d372713, v121
	v_mul_f32_e32 v114, v120, v114
	v_mul_f32_e32 v115, v121, v115
	v_fma_f32 v114, v120, v114, v120
	v_fma_f32 v115, v121, v115, v121
	v_mul_f32_e32 v114, 0xbfcc422a, v114
	v_mul_f32_e32 v115, 0xbfcc422a, v115
	v_mul_f32_e32 v114, 0x3fb8aa3b, v114
	v_mul_f32_e32 v115, 0x3fb8aa3b, v115
	v_exp_f32_e32 v114, v114
	v_exp_f32_e32 v115, v115
	s_nop 0
	v_pk_add_f32 v[114:115], v[114:115], 1.0 op_sel_hi:[1,0]
	s_nop 0
	s_nop 0
	v_rcp_f32_e32 v119, v115
	s_nop 0
	v_mul_f32_e32 v121, v121, v119
	s_nop 0
	v_rcp_f32_e32 v115, v114
	s_nop 0
	v_mul_f32_e32 v120, v120, v115
	v_mul_f32_e32 v114, 0x3d372713, v117
	v_mul_f32_e32 v114, v117, v114
	v_fma_f32 v114, v117, v114, v117
	v_mul_f32_e32 v114, 0xbfcc422a, v114
	v_mul_f32_e32 v114, 0x3fb8aa3b, v114
	v_exp_f32_e32 v119, v114
	s_nop 0
	v_pk_add_f32 v[114:115], v[118:119], 1.0 op_sel_hi:[1,0]
	s_nop 0
	s_nop 0
	v_rcp_f32_e32 v118, v115
	s_nop 0
	v_mul_f32_e32 v115, v117, v118
	s_nop 0
	v_rcp_f32_e32 v117, v114
	s_nop 0
	v_mul_f32_e32 v119, v116, v117
	v_or_b32_e32 v114, 8, v126
	v_cvt_pk_bf16_f32 v119, v119, v115
	v_ashrrev_i32_e32 v115, 31, v114
	v_lshlrev_b64 v[114:115], 9, v[114:115]
	v_cvt_pk_bf16_f32 v117, v120, v121
	v_lshl_add_u64 v[120:121], v[122:123], 0, v[114:115]
	v_lshl_add_u64 v[120:121], v[120:121], 0, s[10:11]
	v_cvt_pk_bf16_f32 v116, v128, v127
	v_cvt_pk_bf16_f32 v118, v143, v129
	v_lshl_add_u64 v[120:121], v[120:121], 0, v[48:49]
	global_store_dwordx4 v[120:121], v[116:119], off
	s_nop 1
	v_mul_f32_e32 v119, 0x3d372713, v106
	v_mul_f32_e32 v119, v106, v119
	v_fma_f32 v119, v106, v119, v106
	v_mul_f32_e32 v119, 0xbfcc422a, v119
	v_mul_f32_e32 v119, 0x3fb8aa3b, v119
	v_mul_f32_e32 v118, 0x3d372713, v110
	v_exp_f32_e32 v120, v119
	v_mul_f32_e32 v119, 0x3d372713, v111
	v_mul_f32_e32 v118, v110, v118
	v_mul_f32_e32 v119, v111, v119
	v_fma_f32 v118, v110, v118, v110
	v_fma_f32 v119, v111, v119, v111
	v_mul_f32_e32 v118, 0xbfcc422a, v118
	v_mul_f32_e32 v119, 0xbfcc422a, v119
	v_mul_f32_e32 v118, 0x3fb8aa3b, v118
	v_mul_f32_e32 v119, 0x3fb8aa3b, v119
	v_exp_f32_e32 v118, v118
	v_exp_f32_e32 v119, v119
	v_or_b32_e32 v116, 16, v142
	v_ashrrev_i32_e32 v117, 31, v116
	v_lshlrev_b64 v[116:117], 14, v[116:117]
	v_pk_add_f32 v[118:119], v[118:119], 1.0 op_sel_hi:[1,0]
	s_nop 0
	s_nop 0
	v_rcp_f32_e32 v121, v119
	s_nop 0
	v_mul_f32_e32 v119, v111, v121
	s_nop 0
	v_rcp_f32_e32 v111, v118
	s_nop 0
	v_mul_f32_e32 v118, v110, v111
	v_mul_f32_e32 v110, 0x3d372713, v107
	v_mul_f32_e32 v110, v107, v110
	v_fma_f32 v110, v107, v110, v107
	v_mul_f32_e32 v110, 0xbfcc422a, v110
	v_mul_f32_e32 v110, 0x3fb8aa3b, v110
	v_exp_f32_e32 v121, v110
	s_nop 0
	v_pk_add_f32 v[110:111], v[120:121], 1.0 op_sel_hi:[1,0]
	s_nop 0
	s_nop 0
	v_rcp_f32_e32 v120, v111
	s_nop 0
	v_mul_f32_e32 v120, v107, v120
	s_nop 0
	v_rcp_f32_e32 v107, v110
	s_nop 0
	v_mul_f32_e32 v121, v106, v107
	v_mul_f32_e32 v107, 0x3d372713, v108
	v_mul_f32_e32 v107, v108, v107
	v_fma_f32 v107, v108, v107, v108
	v_mul_f32_e32 v107, 0xbfcc422a, v107
	v_mul_f32_e32 v107, 0x3fb8aa3b, v107
	v_mul_f32_e32 v106, 0x3d372713, v112
	v_exp_f32_e32 v110, v107
	v_mul_f32_e32 v107, 0x3d372713, v113
	v_mul_f32_e32 v106, v112, v106
	v_mul_f32_e32 v107, v113, v107
	v_fma_f32 v106, v112, v106, v112
	v_fma_f32 v107, v113, v107, v113
	v_mul_f32_e32 v106, 0xbfcc422a, v106
	v_mul_f32_e32 v107, 0xbfcc422a, v107
	v_mul_f32_e32 v106, 0x3fb8aa3b, v106
	v_mul_f32_e32 v107, 0x3fb8aa3b, v107
	v_exp_f32_e32 v106, v106
	v_exp_f32_e32 v107, v107
	s_nop 0
	v_pk_add_f32 v[106:107], v[106:107], 1.0 op_sel_hi:[1,0]
	s_nop 0
	s_nop 0
	v_rcp_f32_e32 v111, v107
	s_nop 0
	v_mul_f32_e32 v113, v113, v111
	s_nop 0
	v_rcp_f32_e32 v107, v106
	s_nop 0
	v_mul_f32_e32 v112, v112, v107
	v_mul_f32_e32 v106, 0x3d372713, v109
	v_mul_f32_e32 v106, v109, v106
	v_fma_f32 v106, v109, v106, v109
	v_mul_f32_e32 v106, 0xbfcc422a, v106
	v_mul_f32_e32 v106, 0x3fb8aa3b, v106
	v_exp_f32_e32 v111, v106
	s_nop 0
	v_pk_add_f32 v[106:107], v[110:111], 1.0 op_sel_hi:[1,0]
	s_nop 0
	s_nop 0
	v_rcp_f32_e32 v110, v107
	s_nop 0
	v_mul_f32_e32 v107, v109, v110
	s_nop 0
	v_rcp_f32_e32 v109, v106
	s_nop 0
	v_mul_f32_e32 v106, v108, v109
	v_cvt_pk_bf16_f32 v111, v106, v107
	v_lshl_add_u64 v[106:107], s[0:1], 0, v[116:117]
	v_cvt_pk_bf16_f32 v109, v112, v113
	v_lshl_add_u64 v[112:113], v[106:107], 0, v[124:125]
	v_lshl_add_u64 v[112:113], v[112:113], 0, s[10:11]
	v_cvt_pk_bf16_f32 v108, v118, v119
	v_cvt_pk_bf16_f32 v110, v121, v120
	v_lshl_add_u64 v[112:113], v[112:113], 0, v[48:49]
	global_store_dwordx4 v[112:113], v[108:111], off
	s_nop 1
	v_mul_f32_e32 v109, 0x3d372713, v98
	v_mul_f32_e32 v109, v98, v109
	v_fma_f32 v109, v98, v109, v98
	v_mul_f32_e32 v109, 0xbfcc422a, v109
	v_mul_f32_e32 v109, 0x3fb8aa3b, v109
	v_mul_f32_e32 v108, 0x3d372713, v102
	v_exp_f32_e32 v110, v109
	v_mul_f32_e32 v109, 0x3d372713, v103
	v_mul_f32_e32 v108, v102, v108
	v_mul_f32_e32 v109, v103, v109
	v_fma_f32 v108, v102, v108, v102
	v_fma_f32 v109, v103, v109, v103
	v_mul_f32_e32 v108, 0xbfcc422a, v108
	v_mul_f32_e32 v109, 0xbfcc422a, v109
	v_mul_f32_e32 v108, 0x3fb8aa3b, v108
	v_mul_f32_e32 v109, 0x3fb8aa3b, v109
	v_exp_f32_e32 v108, v108
	v_exp_f32_e32 v109, v109
	s_nop 0
	v_pk_add_f32 v[108:109], v[108:109], 1.0 op_sel_hi:[1,0]
	s_nop 0
	s_nop 0
	v_rcp_f32_e32 v111, v109
	s_nop 0
	v_mul_f32_e32 v109, v103, v111
	s_nop 0
	v_rcp_f32_e32 v103, v108
	s_nop 0
	v_mul_f32_e32 v108, v102, v103
	v_mul_f32_e32 v102, 0x3d372713, v99
	v_mul_f32_e32 v102, v99, v102
	v_fma_f32 v102, v99, v102, v99
	v_mul_f32_e32 v102, 0xbfcc422a, v102
	v_mul_f32_e32 v102, 0x3fb8aa3b, v102
	v_exp_f32_e32 v111, v102
	s_nop 0
	v_pk_add_f32 v[102:103], v[110:111], 1.0 op_sel_hi:[1,0]
	s_nop 0
	s_nop 0
	v_rcp_f32_e32 v110, v103
	s_nop 0
	v_mul_f32_e32 v110, v99, v110
	s_nop 0
	v_rcp_f32_e32 v99, v102
	s_nop 0
	v_mul_f32_e32 v111, v98, v99
	v_mul_f32_e32 v99, 0x3d372713, v100
	v_mul_f32_e32 v99, v100, v99
	v_fma_f32 v99, v100, v99, v100
	v_mul_f32_e32 v99, 0xbfcc422a, v99
	v_mul_f32_e32 v99, 0x3fb8aa3b, v99
	v_mul_f32_e32 v98, 0x3d372713, v104
	v_exp_f32_e32 v102, v99
	v_mul_f32_e32 v99, 0x3d372713, v105
	v_mul_f32_e32 v98, v104, v98
	v_mul_f32_e32 v99, v105, v99
	v_fma_f32 v98, v104, v98, v104
	v_fma_f32 v99, v105, v99, v105
	v_mul_f32_e32 v98, 0xbfcc422a, v98
	v_mul_f32_e32 v99, 0xbfcc422a, v99
	v_mul_f32_e32 v98, 0x3fb8aa3b, v98
	v_mul_f32_e32 v99, 0x3fb8aa3b, v99
	v_exp_f32_e32 v98, v98
	v_exp_f32_e32 v99, v99
	s_nop 0
	v_pk_add_f32 v[98:99], v[98:99], 1.0 op_sel_hi:[1,0]
	s_nop 0
	s_nop 0
	v_rcp_f32_e32 v103, v99
	s_nop 0
	v_mul_f32_e32 v105, v105, v103
	s_nop 0
	v_rcp_f32_e32 v99, v98
	s_nop 0
	v_mul_f32_e32 v104, v104, v99
	v_mul_f32_e32 v98, 0x3d372713, v101
	v_mul_f32_e32 v98, v101, v98
	v_fma_f32 v98, v101, v98, v101
	v_mul_f32_e32 v98, 0xbfcc422a, v98
	v_mul_f32_e32 v98, 0x3fb8aa3b, v98
	v_exp_f32_e32 v103, v98
	s_nop 0
	v_pk_add_f32 v[98:99], v[102:103], 1.0 op_sel_hi:[1,0]
	s_nop 0
	s_nop 0
	v_rcp_f32_e32 v102, v99
	s_nop 0
	v_mul_f32_e32 v101, v101, v102
	s_nop 0
	v_rcp_f32_e32 v99, v98
	s_nop 0
	v_mul_f32_e32 v102, v100, v99
	v_cvt_pk_bf16_f32 v101, v102, v101
	v_lshl_add_u64 v[102:103], v[106:107], 0, v[114:115]
	v_lshl_add_u64 v[102:103], v[102:103], 0, s[10:11]
	v_cvt_pk_bf16_f32 v98, v108, v109
	v_cvt_pk_bf16_f32 v99, v104, v105
	v_cvt_pk_bf16_f32 v100, v111, v110
	v_lshl_add_u64 v[102:103], v[102:103], 0, v[48:49]
	global_store_dwordx4 v[102:103], v[98:101], off
	s_nop 1
	v_mul_f32_e32 v101, 0x3d372713, v90
	v_mul_f32_e32 v101, v90, v101
	v_fma_f32 v101, v90, v101, v90
	v_mul_f32_e32 v101, 0xbfcc422a, v101
	v_mul_f32_e32 v101, 0x3fb8aa3b, v101
	v_mul_f32_e32 v100, 0x3d372713, v94
	v_exp_f32_e32 v102, v101
	v_mul_f32_e32 v101, 0x3d372713, v95
	v_mul_f32_e32 v100, v94, v100
	v_mul_f32_e32 v101, v95, v101
	v_fma_f32 v100, v94, v100, v94
	v_fma_f32 v101, v95, v101, v95
	v_mul_f32_e32 v100, 0xbfcc422a, v100
	v_mul_f32_e32 v101, 0xbfcc422a, v101
	v_mul_f32_e32 v100, 0x3fb8aa3b, v100
	v_mul_f32_e32 v101, 0x3fb8aa3b, v101
	v_exp_f32_e32 v100, v100
	v_exp_f32_e32 v101, v101
	v_or_b32_e32 v98, 32, v142
	v_ashrrev_i32_e32 v99, 31, v98
	v_lshlrev_b64 v[98:99], 14, v[98:99]
	v_pk_add_f32 v[100:101], v[100:101], 1.0 op_sel_hi:[1,0]
	s_nop 0
	s_nop 0
	v_rcp_f32_e32 v103, v101
	s_nop 0
	v_mul_f32_e32 v101, v95, v103
	s_nop 0
	v_rcp_f32_e32 v95, v100
	s_nop 0
	v_mul_f32_e32 v100, v94, v95
	v_mul_f32_e32 v94, 0x3d372713, v91
	v_mul_f32_e32 v94, v91, v94
	v_fma_f32 v94, v91, v94, v91
	v_mul_f32_e32 v94, 0xbfcc422a, v94
	v_mul_f32_e32 v94, 0x3fb8aa3b, v94
	v_exp_f32_e32 v103, v94
	s_nop 0
	v_pk_add_f32 v[94:95], v[102:103], 1.0 op_sel_hi:[1,0]
	s_nop 0
	s_nop 0
	v_rcp_f32_e32 v102, v95
	s_nop 0
	v_mul_f32_e32 v102, v91, v102
	s_nop 0
	v_rcp_f32_e32 v91, v94
	s_nop 0
	v_mul_f32_e32 v103, v90, v91
	v_mul_f32_e32 v91, 0x3d372713, v92
	v_mul_f32_e32 v91, v92, v91
	v_fma_f32 v91, v92, v91, v92
	v_mul_f32_e32 v91, 0xbfcc422a, v91
	v_mul_f32_e32 v91, 0x3fb8aa3b, v91
	v_mul_f32_e32 v90, 0x3d372713, v96
	v_exp_f32_e32 v94, v91
	v_mul_f32_e32 v91, 0x3d372713, v97
	v_mul_f32_e32 v90, v96, v90
	v_mul_f32_e32 v91, v97, v91
	v_fma_f32 v90, v96, v90, v96
	v_fma_f32 v91, v97, v91, v97
	v_mul_f32_e32 v90, 0xbfcc422a, v90
	v_mul_f32_e32 v91, 0xbfcc422a, v91
	v_mul_f32_e32 v90, 0x3fb8aa3b, v90
	v_mul_f32_e32 v91, 0x3fb8aa3b, v91
	v_exp_f32_e32 v90, v90
	v_exp_f32_e32 v91, v91
	s_nop 0
	v_pk_add_f32 v[90:91], v[90:91], 1.0 op_sel_hi:[1,0]
	s_nop 0
	s_nop 0
	v_rcp_f32_e32 v95, v91
	s_nop 0
	v_mul_f32_e32 v97, v97, v95
	s_nop 0
	v_rcp_f32_e32 v91, v90
	s_nop 0
	v_mul_f32_e32 v96, v96, v91
	v_mul_f32_e32 v90, 0x3d372713, v93
	v_mul_f32_e32 v90, v93, v90
	v_fma_f32 v90, v93, v90, v93
	v_mul_f32_e32 v90, 0xbfcc422a, v90
	v_mul_f32_e32 v90, 0x3fb8aa3b, v90
	v_exp_f32_e32 v95, v90
	s_nop 0
	v_pk_add_f32 v[90:91], v[94:95], 1.0 op_sel_hi:[1,0]
	s_nop 0
	s_nop 0
	v_rcp_f32_e32 v94, v91
	s_nop 0
	v_mul_f32_e32 v91, v93, v94
	s_nop 0
	v_rcp_f32_e32 v93, v90
	s_nop 0
	v_mul_f32_e32 v90, v92, v93
	v_cvt_pk_bf16_f32 v95, v90, v91
	v_lshl_add_u64 v[90:91], s[0:1], 0, v[98:99]
	v_cvt_pk_bf16_f32 v93, v96, v97
	v_lshl_add_u64 v[96:97], v[90:91], 0, v[124:125]
	v_lshl_add_u64 v[96:97], v[96:97], 0, s[10:11]
	v_cvt_pk_bf16_f32 v92, v100, v101
	v_cvt_pk_bf16_f32 v94, v103, v102
	v_lshl_add_u64 v[96:97], v[96:97], 0, v[48:49]
	global_store_dwordx4 v[96:97], v[92:95], off
	s_nop 1
	v_mul_f32_e32 v93, 0x3d372713, v82
	v_mul_f32_e32 v93, v82, v93
	v_fma_f32 v93, v82, v93, v82
	v_mul_f32_e32 v93, 0xbfcc422a, v93
	v_mul_f32_e32 v93, 0x3fb8aa3b, v93
	v_mul_f32_e32 v92, 0x3d372713, v86
	v_exp_f32_e32 v94, v93
	v_mul_f32_e32 v93, 0x3d372713, v87
	v_mul_f32_e32 v92, v86, v92
	v_mul_f32_e32 v93, v87, v93
	v_fma_f32 v92, v86, v92, v86
	v_fma_f32 v93, v87, v93, v87
	v_mul_f32_e32 v92, 0xbfcc422a, v92
	v_mul_f32_e32 v93, 0xbfcc422a, v93
	v_mul_f32_e32 v92, 0x3fb8aa3b, v92
	v_mul_f32_e32 v93, 0x3fb8aa3b, v93
	v_exp_f32_e32 v92, v92
	v_exp_f32_e32 v93, v93
	s_nop 0
	v_pk_add_f32 v[92:93], v[92:93], 1.0 op_sel_hi:[1,0]
	s_nop 0
	s_nop 0
	v_rcp_f32_e32 v95, v93
	s_nop 0
	v_mul_f32_e32 v93, v87, v95
	s_nop 0
	v_rcp_f32_e32 v87, v92
	s_nop 0
	v_mul_f32_e32 v92, v86, v87
	v_mul_f32_e32 v86, 0x3d372713, v83
	v_mul_f32_e32 v86, v83, v86
	v_fma_f32 v86, v83, v86, v83
	v_mul_f32_e32 v86, 0xbfcc422a, v86
	v_mul_f32_e32 v86, 0x3fb8aa3b, v86
	v_exp_f32_e32 v95, v86
	s_nop 0
	v_pk_add_f32 v[86:87], v[94:95], 1.0 op_sel_hi:[1,0]
	s_nop 0
	s_nop 0
	v_rcp_f32_e32 v94, v87
	s_nop 0
	v_mul_f32_e32 v94, v83, v94
	s_nop 0
	v_rcp_f32_e32 v83, v86
	s_nop 0
	v_mul_f32_e32 v95, v82, v83
	v_mul_f32_e32 v83, 0x3d372713, v84
	v_mul_f32_e32 v83, v84, v83
	v_fma_f32 v83, v84, v83, v84
	v_mul_f32_e32 v83, 0xbfcc422a, v83
	v_mul_f32_e32 v83, 0x3fb8aa3b, v83
	v_mul_f32_e32 v82, 0x3d372713, v88
	v_exp_f32_e32 v86, v83
	v_mul_f32_e32 v83, 0x3d372713, v89
	v_mul_f32_e32 v82, v88, v82
	v_mul_f32_e32 v83, v89, v83
	v_fma_f32 v82, v88, v82, v88
	v_fma_f32 v83, v89, v83, v89
	v_mul_f32_e32 v82, 0xbfcc422a, v82
	v_mul_f32_e32 v83, 0xbfcc422a, v83
	v_mul_f32_e32 v82, 0x3fb8aa3b, v82
	v_mul_f32_e32 v83, 0x3fb8aa3b, v83
	v_exp_f32_e32 v82, v82
	v_exp_f32_e32 v83, v83
	s_nop 0
	v_pk_add_f32 v[82:83], v[82:83], 1.0 op_sel_hi:[1,0]
	s_nop 0
	s_nop 0
	v_rcp_f32_e32 v87, v83
	s_nop 0
	v_mul_f32_e32 v89, v89, v87
	s_nop 0
	v_rcp_f32_e32 v83, v82
	s_nop 0
	v_mul_f32_e32 v88, v88, v83
	v_mul_f32_e32 v82, 0x3d372713, v85
	v_mul_f32_e32 v82, v85, v82
	v_fma_f32 v82, v85, v82, v85
	v_mul_f32_e32 v82, 0xbfcc422a, v82
	v_mul_f32_e32 v82, 0x3fb8aa3b, v82
	v_exp_f32_e32 v87, v82
	s_nop 0
	v_pk_add_f32 v[82:83], v[86:87], 1.0 op_sel_hi:[1,0]
	s_nop 0
	s_nop 0
	v_rcp_f32_e32 v86, v83
	s_nop 0
	v_mul_f32_e32 v85, v85, v86
	s_nop 0
	v_rcp_f32_e32 v83, v82
	s_nop 0
	v_mul_f32_e32 v86, v84, v83
	v_cvt_pk_bf16_f32 v85, v86, v85
	v_lshl_add_u64 v[86:87], v[90:91], 0, v[114:115]
	v_lshl_add_u64 v[86:87], v[86:87], 0, s[10:11]
	v_cvt_pk_bf16_f32 v82, v92, v93
	v_cvt_pk_bf16_f32 v83, v88, v89
	v_cvt_pk_bf16_f32 v84, v95, v94
	v_lshl_add_u64 v[86:87], v[86:87], 0, v[48:49]
	global_store_dwordx4 v[86:87], v[82:85], off
	s_nop 1
	v_mul_f32_e32 v85, 0x3d372713, v74
	v_mul_f32_e32 v85, v74, v85
	v_fma_f32 v85, v74, v85, v74
	v_mul_f32_e32 v85, 0xbfcc422a, v85
	v_mul_f32_e32 v85, 0x3fb8aa3b, v85
	v_mul_f32_e32 v84, 0x3d372713, v78
	v_exp_f32_e32 v86, v85
	v_mul_f32_e32 v85, 0x3d372713, v79
	v_mul_f32_e32 v84, v78, v84
	v_mul_f32_e32 v85, v79, v85
	v_fma_f32 v84, v78, v84, v78
	v_fma_f32 v85, v79, v85, v79
	v_mul_f32_e32 v84, 0xbfcc422a, v84
	v_mul_f32_e32 v85, 0xbfcc422a, v85
	v_mul_f32_e32 v84, 0x3fb8aa3b, v84
	v_mul_f32_e32 v85, 0x3fb8aa3b, v85
	v_exp_f32_e32 v84, v84
	v_exp_f32_e32 v85, v85
	v_or_b32_e32 v82, 48, v142
	v_ashrrev_i32_e32 v83, 31, v82
	v_lshlrev_b64 v[82:83], 14, v[82:83]
	v_pk_add_f32 v[84:85], v[84:85], 1.0 op_sel_hi:[1,0]
	s_nop 0
	s_nop 0
	v_rcp_f32_e32 v87, v85
	s_nop 0
	v_mul_f32_e32 v85, v79, v87
	s_nop 0
	v_rcp_f32_e32 v79, v84
	s_nop 0
	v_mul_f32_e32 v84, v78, v79
	v_mul_f32_e32 v78, 0x3d372713, v75
	v_mul_f32_e32 v78, v75, v78
	v_fma_f32 v78, v75, v78, v75
	v_mul_f32_e32 v78, 0xbfcc422a, v78
	v_mul_f32_e32 v78, 0x3fb8aa3b, v78
	v_exp_f32_e32 v87, v78
	s_nop 0
	v_pk_add_f32 v[78:79], v[86:87], 1.0 op_sel_hi:[1,0]
	s_nop 0
	s_nop 0
	v_rcp_f32_e32 v86, v79
	s_nop 0
	v_mul_f32_e32 v86, v75, v86
	s_nop 0
	v_rcp_f32_e32 v75, v78
	s_nop 0
	v_mul_f32_e32 v87, v74, v75
	v_mul_f32_e32 v75, 0x3d372713, v76
	v_mul_f32_e32 v75, v76, v75
	v_fma_f32 v75, v76, v75, v76
	v_mul_f32_e32 v75, 0xbfcc422a, v75
	v_mul_f32_e32 v75, 0x3fb8aa3b, v75
	v_mul_f32_e32 v74, 0x3d372713, v80
	v_exp_f32_e32 v78, v75
	v_mul_f32_e32 v75, 0x3d372713, v81
	v_mul_f32_e32 v74, v80, v74
	v_mul_f32_e32 v75, v81, v75
	v_fma_f32 v74, v80, v74, v80
	v_fma_f32 v75, v81, v75, v81
	v_mul_f32_e32 v74, 0xbfcc422a, v74
	v_mul_f32_e32 v75, 0xbfcc422a, v75
	v_mul_f32_e32 v74, 0x3fb8aa3b, v74
	v_mul_f32_e32 v75, 0x3fb8aa3b, v75
	v_exp_f32_e32 v74, v74
	v_exp_f32_e32 v75, v75
	s_nop 0
	v_pk_add_f32 v[74:75], v[74:75], 1.0 op_sel_hi:[1,0]
	s_nop 0
	s_nop 0
	v_rcp_f32_e32 v79, v75
	s_nop 0
	v_mul_f32_e32 v81, v81, v79
	s_nop 0
	v_rcp_f32_e32 v75, v74
	s_nop 0
	v_mul_f32_e32 v80, v80, v75
	v_mul_f32_e32 v74, 0x3d372713, v77
	v_mul_f32_e32 v74, v77, v74
	v_fma_f32 v74, v77, v74, v77
	v_mul_f32_e32 v74, 0xbfcc422a, v74
	v_mul_f32_e32 v74, 0x3fb8aa3b, v74
	v_exp_f32_e32 v79, v74
	s_nop 0
	v_pk_add_f32 v[74:75], v[78:79], 1.0 op_sel_hi:[1,0]
	s_nop 0
	s_nop 0
	v_rcp_f32_e32 v78, v75
	s_nop 0
	v_mul_f32_e32 v75, v77, v78
	s_nop 0
	v_rcp_f32_e32 v77, v74
	s_nop 0
	v_mul_f32_e32 v74, v76, v77
	v_cvt_pk_bf16_f32 v79, v74, v75
	v_lshl_add_u64 v[74:75], s[0:1], 0, v[82:83]
	v_cvt_pk_bf16_f32 v77, v80, v81
	v_lshl_add_u64 v[80:81], v[74:75], 0, v[124:125]
	v_lshl_add_u64 v[80:81], v[80:81], 0, s[10:11]
	v_cvt_pk_bf16_f32 v76, v84, v85
	v_cvt_pk_bf16_f32 v78, v87, v86
	v_lshl_add_u64 v[80:81], v[80:81], 0, v[48:49]
	global_store_dwordx4 v[80:81], v[76:79], off
	s_nop 1
	v_mul_f32_e32 v77, 0x3d372713, v66
	v_mul_f32_e32 v77, v66, v77
	v_fma_f32 v77, v66, v77, v66
	v_mul_f32_e32 v77, 0xbfcc422a, v77
	v_mul_f32_e32 v77, 0x3fb8aa3b, v77
	v_mul_f32_e32 v76, 0x3d372713, v70
	v_exp_f32_e32 v78, v77
	v_mul_f32_e32 v77, 0x3d372713, v71
	v_mul_f32_e32 v76, v70, v76
	v_mul_f32_e32 v77, v71, v77
	v_fma_f32 v76, v70, v76, v70
	v_fma_f32 v77, v71, v77, v71
	v_mul_f32_e32 v76, 0xbfcc422a, v76
	v_mul_f32_e32 v77, 0xbfcc422a, v77
	v_mul_f32_e32 v76, 0x3fb8aa3b, v76
	v_mul_f32_e32 v77, 0x3fb8aa3b, v77
	v_exp_f32_e32 v76, v76
	v_exp_f32_e32 v77, v77
	s_nop 0
	v_pk_add_f32 v[76:77], v[76:77], 1.0 op_sel_hi:[1,0]
	s_nop 0
	s_nop 0
	v_rcp_f32_e32 v79, v77
	s_nop 0
	v_mul_f32_e32 v77, v71, v79
	s_nop 0
	v_rcp_f32_e32 v71, v76
	s_nop 0
	v_mul_f32_e32 v76, v70, v71
	v_mul_f32_e32 v70, 0x3d372713, v67
	v_mul_f32_e32 v70, v67, v70
	v_fma_f32 v70, v67, v70, v67
	v_mul_f32_e32 v70, 0xbfcc422a, v70
	v_mul_f32_e32 v70, 0x3fb8aa3b, v70
	v_exp_f32_e32 v79, v70
	s_nop 0
	v_pk_add_f32 v[70:71], v[78:79], 1.0 op_sel_hi:[1,0]
	s_nop 0
	s_nop 0
	v_rcp_f32_e32 v78, v71
	s_nop 0
	v_mul_f32_e32 v78, v67, v78
	s_nop 0
	v_rcp_f32_e32 v67, v70
	s_nop 0
	v_mul_f32_e32 v79, v66, v67
	v_mul_f32_e32 v67, 0x3d372713, v68
	v_mul_f32_e32 v67, v68, v67
	v_fma_f32 v67, v68, v67, v68
	v_mul_f32_e32 v67, 0xbfcc422a, v67
	v_mul_f32_e32 v67, 0x3fb8aa3b, v67
	v_mul_f32_e32 v66, 0x3d372713, v72
	v_exp_f32_e32 v70, v67
	v_mul_f32_e32 v67, 0x3d372713, v73
	v_mul_f32_e32 v66, v72, v66
	v_mul_f32_e32 v67, v73, v67
	v_fma_f32 v66, v72, v66, v72
	v_fma_f32 v67, v73, v67, v73
	v_mul_f32_e32 v66, 0xbfcc422a, v66
	v_mul_f32_e32 v67, 0xbfcc422a, v67
	v_mul_f32_e32 v66, 0x3fb8aa3b, v66
	v_mul_f32_e32 v67, 0x3fb8aa3b, v67
	v_exp_f32_e32 v66, v66
	v_exp_f32_e32 v67, v67
	s_nop 0
	v_pk_add_f32 v[66:67], v[66:67], 1.0 op_sel_hi:[1,0]
	s_nop 0
	s_nop 0
	v_rcp_f32_e32 v71, v67
	s_nop 0
	v_mul_f32_e32 v73, v73, v71
	s_nop 0
	v_rcp_f32_e32 v67, v66
	s_nop 0
	v_mul_f32_e32 v72, v72, v67
	v_mul_f32_e32 v66, 0x3d372713, v69
	v_mul_f32_e32 v66, v69, v66
	v_fma_f32 v66, v69, v66, v69
	v_mul_f32_e32 v66, 0xbfcc422a, v66
	v_mul_f32_e32 v66, 0x3fb8aa3b, v66
	v_exp_f32_e32 v71, v66
	s_nop 0
	v_pk_add_f32 v[66:67], v[70:71], 1.0 op_sel_hi:[1,0]
	s_nop 0
	s_nop 0
	v_rcp_f32_e32 v70, v67
	s_nop 0
	v_mul_f32_e32 v69, v69, v70
	s_nop 0
	v_rcp_f32_e32 v67, v66
	s_nop 0
	v_mul_f32_e32 v70, v68, v67
	v_cvt_pk_bf16_f32 v69, v70, v69
	v_lshl_add_u64 v[70:71], v[74:75], 0, v[114:115]
	v_lshl_add_u64 v[70:71], v[70:71], 0, s[10:11]
	v_cvt_pk_bf16_f32 v66, v76, v77
	v_cvt_pk_bf16_f32 v67, v72, v73
	v_cvt_pk_bf16_f32 v68, v79, v78
	v_lshl_add_u64 v[70:71], v[70:71], 0, v[48:49]
	global_store_dwordx4 v[70:71], v[66:69], off
	s_nop 1
	v_mul_f32_e32 v67, 0x3d372713, v58
	v_mul_f32_e32 v67, v58, v67
	v_fma_f32 v67, v58, v67, v58
	v_mul_f32_e32 v67, 0xbfcc422a, v67
	v_mul_f32_e32 v67, 0x3fb8aa3b, v67
	v_mul_f32_e32 v66, 0x3d372713, v62
	v_exp_f32_e32 v68, v67
	v_mul_f32_e32 v67, 0x3d372713, v63
	v_mul_f32_e32 v66, v62, v66
	v_mul_f32_e32 v67, v63, v67
	v_fma_f32 v66, v62, v66, v62
	v_fma_f32 v67, v63, v67, v63
	v_mul_f32_e32 v66, 0xbfcc422a, v66
	v_mul_f32_e32 v67, 0xbfcc422a, v67
	v_mul_f32_e32 v66, 0x3fb8aa3b, v66
	v_mul_f32_e32 v67, 0x3fb8aa3b, v67
	v_exp_f32_e32 v66, v66
	v_exp_f32_e32 v67, v67
	s_nop 0
	v_pk_add_f32 v[66:67], v[66:67], 1.0 op_sel_hi:[1,0]
	s_nop 0
	s_nop 0
	v_rcp_f32_e32 v69, v67
	s_nop 0
	v_mul_f32_e32 v67, v63, v69
	s_nop 0
	v_rcp_f32_e32 v63, v66
	s_nop 0
	v_mul_f32_e32 v66, v62, v63
	v_mul_f32_e32 v62, 0x3d372713, v59
	v_mul_f32_e32 v62, v59, v62
	v_fma_f32 v62, v59, v62, v59
	v_mul_f32_e32 v62, 0xbfcc422a, v62
	v_mul_f32_e32 v62, 0x3fb8aa3b, v62
	v_exp_f32_e32 v69, v62
	s_nop 0
	v_pk_add_f32 v[62:63], v[68:69], 1.0 op_sel_hi:[1,0]
	s_nop 0
	s_nop 0
	v_rcp_f32_e32 v68, v63
	s_nop 0
	v_mul_f32_e32 v68, v59, v68
	s_nop 0
	v_rcp_f32_e32 v59, v62
	s_nop 0
	v_mul_f32_e32 v69, v58, v59
	v_mul_f32_e32 v59, 0x3d372713, v60
	v_mul_f32_e32 v59, v60, v59
	v_fma_f32 v59, v60, v59, v60
	v_mul_f32_e32 v59, 0xbfcc422a, v59
	v_mul_f32_e32 v59, 0x3fb8aa3b, v59
	v_mul_f32_e32 v58, 0x3d372713, v64
	v_exp_f32_e32 v62, v59
	v_mul_f32_e32 v59, 0x3d372713, v65
	v_mul_f32_e32 v58, v64, v58
	v_mul_f32_e32 v59, v65, v59
	v_fma_f32 v58, v64, v58, v64
	v_fma_f32 v59, v65, v59, v65
	v_mul_f32_e32 v58, 0xbfcc422a, v58
	v_mul_f32_e32 v59, 0xbfcc422a, v59
	v_mul_f32_e32 v58, 0x3fb8aa3b, v58
	v_mul_f32_e32 v59, 0x3fb8aa3b, v59
	v_exp_f32_e32 v58, v58
	v_exp_f32_e32 v59, v59
	s_nop 0
	v_pk_add_f32 v[58:59], v[58:59], 1.0 op_sel_hi:[1,0]
	s_nop 0
	s_nop 0
	v_rcp_f32_e32 v63, v59
	s_nop 0
	v_mul_f32_e32 v65, v65, v63
	s_nop 0
	v_rcp_f32_e32 v59, v58
	s_nop 0
	v_mul_f32_e32 v64, v64, v59
	v_mul_f32_e32 v58, 0x3d372713, v61
	v_mul_f32_e32 v58, v61, v58
	v_fma_f32 v58, v61, v58, v61
	v_mul_f32_e32 v58, 0xbfcc422a, v58
	v_mul_f32_e32 v58, 0x3fb8aa3b, v58
	v_exp_f32_e32 v63, v58
	s_nop 0
	v_pk_add_f32 v[58:59], v[62:63], 1.0 op_sel_hi:[1,0]
	s_nop 0
	s_nop 0
	v_rcp_f32_e32 v62, v59
	s_nop 0
	v_mul_f32_e32 v59, v61, v62
	s_mov_b64 s[12:13], 0x200000
	v_rcp_f32_e32 v61, v58
	s_nop 0
	v_mul_f32_e32 v58, v60, v61
	v_cvt_pk_bf16_f32 v63, v58, v59
	v_lshl_add_u64 v[58:59], v[122:123], 0, s[12:13]
	v_cvt_pk_bf16_f32 v61, v64, v65
	v_lshl_add_u64 v[64:65], v[58:59], 0, v[124:125]
	v_lshl_add_u64 v[64:65], v[64:65], 0, s[10:11]
	v_cvt_pk_bf16_f32 v60, v66, v67
	v_cvt_pk_bf16_f32 v62, v69, v68
	v_lshl_add_u64 v[64:65], v[64:65], 0, v[48:49]
	global_store_dwordx4 v[64:65], v[60:63], off
	s_nop 1
	v_mul_f32_e32 v61, 0x3d372713, v50
	v_mul_f32_e32 v61, v50, v61
	v_fma_f32 v61, v50, v61, v50
	v_mul_f32_e32 v61, 0xbfcc422a, v61
	v_mul_f32_e32 v61, 0x3fb8aa3b, v61
	v_mul_f32_e32 v60, 0x3d372713, v54
	v_exp_f32_e32 v62, v61
	v_mul_f32_e32 v61, 0x3d372713, v55
	v_mul_f32_e32 v60, v54, v60
	v_mul_f32_e32 v61, v55, v61
	v_fma_f32 v60, v54, v60, v54
	v_fma_f32 v61, v55, v61, v55
	v_mul_f32_e32 v60, 0xbfcc422a, v60
	v_mul_f32_e32 v61, 0xbfcc422a, v61
	v_mul_f32_e32 v60, 0x3fb8aa3b, v60
	v_mul_f32_e32 v61, 0x3fb8aa3b, v61
	v_exp_f32_e32 v60, v60
	v_exp_f32_e32 v61, v61
	s_nop 0
	v_pk_add_f32 v[60:61], v[60:61], 1.0 op_sel_hi:[1,0]
	s_nop 0
	s_nop 0
	v_rcp_f32_e32 v63, v61
	s_nop 0
	v_mul_f32_e32 v61, v55, v63
	s_nop 0
	v_rcp_f32_e32 v55, v60
	s_nop 0
	v_mul_f32_e32 v60, v54, v55
	v_mul_f32_e32 v54, 0x3d372713, v51
	v_mul_f32_e32 v54, v51, v54
	v_fma_f32 v54, v51, v54, v51
	v_mul_f32_e32 v54, 0xbfcc422a, v54
	v_mul_f32_e32 v54, 0x3fb8aa3b, v54
	v_exp_f32_e32 v63, v54
	s_nop 0
	v_pk_add_f32 v[54:55], v[62:63], 1.0 op_sel_hi:[1,0]
	s_nop 0
	s_nop 0
	v_rcp_f32_e32 v62, v55
	s_nop 0
	v_mul_f32_e32 v62, v51, v62
	s_nop 0
	v_rcp_f32_e32 v51, v54
	s_nop 0
	v_mul_f32_e32 v63, v50, v51
	v_mul_f32_e32 v51, 0x3d372713, v52
	v_mul_f32_e32 v51, v52, v51
	v_fma_f32 v51, v52, v51, v52
	v_mul_f32_e32 v51, 0xbfcc422a, v51
	v_mul_f32_e32 v51, 0x3fb8aa3b, v51
	v_mul_f32_e32 v50, 0x3d372713, v56
	v_exp_f32_e32 v54, v51
	v_mul_f32_e32 v51, 0x3d372713, v57
	v_mul_f32_e32 v50, v56, v50
	v_mul_f32_e32 v51, v57, v51
	v_fma_f32 v50, v56, v50, v56
	v_fma_f32 v51, v57, v51, v57
	v_mul_f32_e32 v50, 0xbfcc422a, v50
	v_mul_f32_e32 v51, 0xbfcc422a, v51
	v_mul_f32_e32 v50, 0x3fb8aa3b, v50
	v_mul_f32_e32 v51, 0x3fb8aa3b, v51
	v_exp_f32_e32 v50, v50
	v_exp_f32_e32 v51, v51
	s_nop 0
	v_pk_add_f32 v[50:51], v[50:51], 1.0 op_sel_hi:[1,0]
	s_nop 0
	s_nop 0
	v_rcp_f32_e32 v55, v51
	s_nop 0
	v_mul_f32_e32 v57, v57, v55
	s_nop 0
	v_rcp_f32_e32 v51, v50
	s_nop 0
	v_mul_f32_e32 v56, v56, v51
	v_mul_f32_e32 v50, 0x3d372713, v53
	v_mul_f32_e32 v50, v53, v50
	v_fma_f32 v50, v53, v50, v53
	v_mul_f32_e32 v50, 0xbfcc422a, v50
	v_mul_f32_e32 v50, 0x3fb8aa3b, v50
	v_exp_f32_e32 v55, v50
	s_nop 0
	v_pk_add_f32 v[50:51], v[54:55], 1.0 op_sel_hi:[1,0]
	s_nop 0
	s_nop 0
	v_rcp_f32_e32 v54, v51
	s_nop 0
	v_mul_f32_e32 v53, v53, v54
	s_nop 0
	v_rcp_f32_e32 v51, v50
	s_nop 0
	v_mul_f32_e32 v54, v52, v51
	v_cvt_pk_bf16_f32 v53, v54, v53
	v_lshl_add_u64 v[54:55], v[58:59], 0, v[114:115]
	v_lshl_add_u64 v[54:55], v[54:55], 0, s[10:11]
	v_cvt_pk_bf16_f32 v50, v60, v61
	v_cvt_pk_bf16_f32 v51, v56, v57
	v_cvt_pk_bf16_f32 v52, v63, v62
	v_lshl_add_u64 v[54:55], v[54:55], 0, v[48:49]
	global_store_dwordx4 v[54:55], v[50:53], off
	s_nop 1
	v_mul_f32_e32 v51, 0x3d372713, v40
	v_mul_f32_e32 v51, v40, v51
	v_fma_f32 v51, v40, v51, v40
	v_mul_f32_e32 v51, 0xbfcc422a, v51
	v_mul_f32_e32 v51, 0x3fb8aa3b, v51
	v_mul_f32_e32 v50, 0x3d372713, v44
	v_exp_f32_e32 v52, v51
	v_mul_f32_e32 v51, 0x3d372713, v45
	v_mul_f32_e32 v50, v44, v50
	v_mul_f32_e32 v51, v45, v51
	v_fma_f32 v50, v44, v50, v44
	v_fma_f32 v51, v45, v51, v45
	v_mul_f32_e32 v50, 0xbfcc422a, v50
	v_mul_f32_e32 v51, 0xbfcc422a, v51
	v_mul_f32_e32 v50, 0x3fb8aa3b, v50
	v_mul_f32_e32 v51, 0x3fb8aa3b, v51
	v_exp_f32_e32 v50, v50
	v_exp_f32_e32 v51, v51
	s_nop 0
	v_pk_add_f32 v[50:51], v[50:51], 1.0 op_sel_hi:[1,0]
	s_nop 0
	s_nop 0
	v_rcp_f32_e32 v53, v51
	s_nop 0
	v_mul_f32_e32 v51, v45, v53
	s_nop 0
	v_rcp_f32_e32 v45, v50
	s_nop 0
	v_mul_f32_e32 v50, v44, v45
	v_mul_f32_e32 v44, 0x3d372713, v41
	v_mul_f32_e32 v44, v41, v44
	v_fma_f32 v44, v41, v44, v41
	v_mul_f32_e32 v44, 0xbfcc422a, v44
	v_mul_f32_e32 v44, 0x3fb8aa3b, v44
	v_exp_f32_e32 v53, v44
	s_nop 0
	v_pk_add_f32 v[44:45], v[52:53], 1.0 op_sel_hi:[1,0]
	s_nop 0
	s_nop 0
	v_rcp_f32_e32 v52, v45
	s_nop 0
	v_mul_f32_e32 v52, v41, v52
	s_nop 0
	v_rcp_f32_e32 v41, v44
	s_nop 0
	v_mul_f32_e32 v53, v40, v41
	v_mul_f32_e32 v41, 0x3d372713, v42
	v_mul_f32_e32 v41, v42, v41
	v_fma_f32 v41, v42, v41, v42
	v_mul_f32_e32 v41, 0xbfcc422a, v41
	v_mul_f32_e32 v41, 0x3fb8aa3b, v41
	v_mul_f32_e32 v40, 0x3d372713, v46
	v_exp_f32_e32 v44, v41
	v_mul_f32_e32 v41, 0x3d372713, v47
	v_mul_f32_e32 v40, v46, v40
	v_mul_f32_e32 v41, v47, v41
	v_fma_f32 v40, v46, v40, v46
	v_fma_f32 v41, v47, v41, v47
	v_mul_f32_e32 v40, 0xbfcc422a, v40
	v_mul_f32_e32 v41, 0xbfcc422a, v41
	v_mul_f32_e32 v40, 0x3fb8aa3b, v40
	v_mul_f32_e32 v41, 0x3fb8aa3b, v41
	v_exp_f32_e32 v40, v40
	v_exp_f32_e32 v41, v41
	s_nop 0
	v_pk_add_f32 v[40:41], v[40:41], 1.0 op_sel_hi:[1,0]
	s_nop 0
	s_nop 0
	v_rcp_f32_e32 v45, v41
	s_nop 0
	v_mul_f32_e32 v47, v47, v45
	s_nop 0
	v_rcp_f32_e32 v41, v40
	s_nop 0
	v_mul_f32_e32 v46, v46, v41
	v_mul_f32_e32 v40, 0x3d372713, v43
	v_mul_f32_e32 v40, v43, v40
	v_fma_f32 v40, v43, v40, v43
	v_mul_f32_e32 v40, 0xbfcc422a, v40
	v_mul_f32_e32 v40, 0x3fb8aa3b, v40
	v_exp_f32_e32 v45, v40
	s_nop 0
	v_pk_add_f32 v[40:41], v[44:45], 1.0 op_sel_hi:[1,0]
	s_nop 0
	s_nop 0
	v_rcp_f32_e32 v44, v41
	s_nop 0
	v_mul_f32_e32 v41, v43, v44
	s_mov_b64 s[12:13], 0x240000
	v_rcp_f32_e32 v43, v40
	s_nop 0
	v_mul_f32_e32 v40, v42, v43
	v_cvt_pk_bf16_f32 v45, v40, v41
	v_lshl_add_u64 v[40:41], v[122:123], 0, s[12:13]
	v_cvt_pk_bf16_f32 v43, v46, v47
	v_lshl_add_u64 v[46:47], v[40:41], 0, v[124:125]
	v_lshl_add_u64 v[46:47], v[46:47], 0, s[10:11]
	v_cvt_pk_bf16_f32 v42, v50, v51
	v_cvt_pk_bf16_f32 v44, v53, v52
	v_lshl_add_u64 v[46:47], v[46:47], 0, v[48:49]
	global_store_dwordx4 v[46:47], v[42:45], off
	s_nop 1
	v_mul_f32_e32 v43, 0x3d372713, v32
	v_mul_f32_e32 v43, v32, v43
	v_fma_f32 v43, v32, v43, v32
	v_mul_f32_e32 v43, 0xbfcc422a, v43
	v_mul_f32_e32 v43, 0x3fb8aa3b, v43
	v_mul_f32_e32 v42, 0x3d372713, v36
	v_exp_f32_e32 v44, v43
	v_mul_f32_e32 v43, 0x3d372713, v37
	v_mul_f32_e32 v42, v36, v42
	v_mul_f32_e32 v43, v37, v43
	v_fma_f32 v42, v36, v42, v36
	v_fma_f32 v43, v37, v43, v37
	v_mul_f32_e32 v42, 0xbfcc422a, v42
	v_mul_f32_e32 v43, 0xbfcc422a, v43
	v_mul_f32_e32 v42, 0x3fb8aa3b, v42
	v_mul_f32_e32 v43, 0x3fb8aa3b, v43
	v_exp_f32_e32 v42, v42
	v_exp_f32_e32 v43, v43
	s_nop 0
	v_pk_add_f32 v[42:43], v[42:43], 1.0 op_sel_hi:[1,0]
	s_nop 0
	s_nop 0
	v_rcp_f32_e32 v45, v43
	s_nop 0
	v_mul_f32_e32 v43, v37, v45
	s_nop 0
	v_rcp_f32_e32 v37, v42
	s_nop 0
	v_mul_f32_e32 v42, v36, v37
	v_mul_f32_e32 v36, 0x3d372713, v33
	v_mul_f32_e32 v36, v33, v36
	v_fma_f32 v36, v33, v36, v33
	v_mul_f32_e32 v36, 0xbfcc422a, v36
	v_mul_f32_e32 v36, 0x3fb8aa3b, v36
	v_exp_f32_e32 v45, v36
	s_nop 0
	v_pk_add_f32 v[36:37], v[44:45], 1.0 op_sel_hi:[1,0]
	s_nop 0
	s_nop 0
	v_rcp_f32_e32 v44, v37
	s_nop 0
	v_mul_f32_e32 v44, v33, v44
	s_nop 0
	v_rcp_f32_e32 v33, v36
	s_nop 0
	v_mul_f32_e32 v45, v32, v33
	v_mul_f32_e32 v33, 0x3d372713, v34
	v_mul_f32_e32 v33, v34, v33
	v_fma_f32 v33, v34, v33, v34
	v_mul_f32_e32 v33, 0xbfcc422a, v33
	v_mul_f32_e32 v33, 0x3fb8aa3b, v33
	v_mul_f32_e32 v32, 0x3d372713, v38
	v_exp_f32_e32 v36, v33
	v_mul_f32_e32 v33, 0x3d372713, v39
	v_mul_f32_e32 v32, v38, v32
	v_mul_f32_e32 v33, v39, v33
	v_fma_f32 v32, v38, v32, v38
	v_fma_f32 v33, v39, v33, v39
	v_mul_f32_e32 v32, 0xbfcc422a, v32
	v_mul_f32_e32 v33, 0xbfcc422a, v33
	v_mul_f32_e32 v32, 0x3fb8aa3b, v32
	v_mul_f32_e32 v33, 0x3fb8aa3b, v33
	v_exp_f32_e32 v32, v32
	v_exp_f32_e32 v33, v33
	s_nop 0
	v_pk_add_f32 v[32:33], v[32:33], 1.0 op_sel_hi:[1,0]
	s_nop 0
	s_nop 0
	v_rcp_f32_e32 v37, v33
	s_nop 0
	v_mul_f32_e32 v39, v39, v37
	s_nop 0
	v_rcp_f32_e32 v33, v32
	s_nop 0
	v_mul_f32_e32 v38, v38, v33
	v_mul_f32_e32 v32, 0x3d372713, v35
	v_mul_f32_e32 v32, v35, v32
	v_fma_f32 v32, v35, v32, v35
	v_mul_f32_e32 v32, 0xbfcc422a, v32
	v_mul_f32_e32 v32, 0x3fb8aa3b, v32
	v_exp_f32_e32 v37, v32
	s_nop 0
	v_pk_add_f32 v[32:33], v[36:37], 1.0 op_sel_hi:[1,0]
	s_nop 0
	s_nop 0
	v_rcp_f32_e32 v36, v33
	s_nop 0
	v_mul_f32_e32 v35, v35, v36
	s_nop 0
	v_rcp_f32_e32 v33, v32
	s_nop 0
	v_mul_f32_e32 v36, v34, v33
	v_cvt_pk_bf16_f32 v35, v36, v35
	v_lshl_add_u64 v[36:37], v[40:41], 0, v[114:115]
	v_lshl_add_u64 v[36:37], v[36:37], 0, s[10:11]
	v_cvt_pk_bf16_f32 v32, v42, v43
	v_cvt_pk_bf16_f32 v33, v38, v39
	v_cvt_pk_bf16_f32 v34, v45, v44
	v_lshl_add_u64 v[36:37], v[36:37], 0, v[48:49]
	global_store_dwordx4 v[36:37], v[32:35], off
	s_nop 1
	v_mul_f32_e32 v33, 0x3d372713, v24
	v_mul_f32_e32 v33, v24, v33
	v_fma_f32 v33, v24, v33, v24
	v_mul_f32_e32 v33, 0xbfcc422a, v33
	v_mul_f32_e32 v33, 0x3fb8aa3b, v33
	v_mul_f32_e32 v32, 0x3d372713, v28
	v_exp_f32_e32 v34, v33
	v_mul_f32_e32 v33, 0x3d372713, v29
	v_mul_f32_e32 v32, v28, v32
	v_mul_f32_e32 v33, v29, v33
	v_fma_f32 v32, v28, v32, v28
	v_fma_f32 v33, v29, v33, v29
	v_mul_f32_e32 v32, 0xbfcc422a, v32
	v_mul_f32_e32 v33, 0xbfcc422a, v33
	v_mul_f32_e32 v32, 0x3fb8aa3b, v32
	v_mul_f32_e32 v33, 0x3fb8aa3b, v33
	v_exp_f32_e32 v32, v32
	v_exp_f32_e32 v33, v33
	s_nop 0
	v_pk_add_f32 v[32:33], v[32:33], 1.0 op_sel_hi:[1,0]
	s_nop 0
	s_nop 0
	v_rcp_f32_e32 v35, v33
	s_nop 0
	v_mul_f32_e32 v33, v29, v35
	s_nop 0
	v_rcp_f32_e32 v29, v32
	s_nop 0
	v_mul_f32_e32 v32, v28, v29
	v_mul_f32_e32 v28, 0x3d372713, v25
	v_mul_f32_e32 v28, v25, v28
	v_fma_f32 v28, v25, v28, v25
	v_mul_f32_e32 v28, 0xbfcc422a, v28
	v_mul_f32_e32 v28, 0x3fb8aa3b, v28
	v_exp_f32_e32 v35, v28
	s_nop 0
	v_pk_add_f32 v[28:29], v[34:35], 1.0 op_sel_hi:[1,0]
	s_nop 0
	s_nop 0
	v_rcp_f32_e32 v34, v29
	s_nop 0
	v_mul_f32_e32 v34, v25, v34
	s_nop 0
	v_rcp_f32_e32 v25, v28
	s_nop 0
	v_mul_f32_e32 v35, v24, v25
	v_mul_f32_e32 v25, 0x3d372713, v26
	v_mul_f32_e32 v25, v26, v25
	v_fma_f32 v25, v26, v25, v26
	v_mul_f32_e32 v25, 0xbfcc422a, v25
	v_mul_f32_e32 v25, 0x3fb8aa3b, v25
	v_mul_f32_e32 v24, 0x3d372713, v30
	v_exp_f32_e32 v28, v25
	v_mul_f32_e32 v25, 0x3d372713, v31
	v_mul_f32_e32 v24, v30, v24
	v_mul_f32_e32 v25, v31, v25
	v_fma_f32 v24, v30, v24, v30
	v_fma_f32 v25, v31, v25, v31
	v_mul_f32_e32 v24, 0xbfcc422a, v24
	v_mul_f32_e32 v25, 0xbfcc422a, v25
	v_mul_f32_e32 v24, 0x3fb8aa3b, v24
	v_mul_f32_e32 v25, 0x3fb8aa3b, v25
	v_exp_f32_e32 v24, v24
	v_exp_f32_e32 v25, v25
	s_nop 0
	v_pk_add_f32 v[24:25], v[24:25], 1.0 op_sel_hi:[1,0]
	s_nop 0
	s_nop 0
	v_rcp_f32_e32 v29, v25
	s_nop 0
	v_mul_f32_e32 v31, v31, v29
	s_nop 0
	v_rcp_f32_e32 v25, v24
	s_nop 0
	v_mul_f32_e32 v30, v30, v25
	v_mul_f32_e32 v24, 0x3d372713, v27
	v_mul_f32_e32 v24, v27, v24
	v_fma_f32 v24, v27, v24, v27
	v_mul_f32_e32 v24, 0xbfcc422a, v24
	v_mul_f32_e32 v24, 0x3fb8aa3b, v24
	v_exp_f32_e32 v29, v24
	s_nop 0
	v_pk_add_f32 v[24:25], v[28:29], 1.0 op_sel_hi:[1,0]
	s_nop 0
	s_nop 0
	v_rcp_f32_e32 v28, v25
	s_nop 0
	v_mul_f32_e32 v25, v27, v28
	s_mov_b64 s[12:13], 0x280000
	v_rcp_f32_e32 v27, v24
	s_nop 0
	v_mul_f32_e32 v24, v26, v27
	v_cvt_pk_bf16_f32 v29, v24, v25
	v_lshl_add_u64 v[24:25], v[122:123], 0, s[12:13]
	v_cvt_pk_bf16_f32 v27, v30, v31
	v_lshl_add_u64 v[30:31], v[24:25], 0, v[124:125]
	v_lshl_add_u64 v[30:31], v[30:31], 0, s[10:11]
	v_cvt_pk_bf16_f32 v26, v32, v33
	v_cvt_pk_bf16_f32 v28, v35, v34
	v_lshl_add_u64 v[30:31], v[30:31], 0, v[48:49]
	global_store_dwordx4 v[30:31], v[26:29], off
	s_nop 1
	v_mul_f32_e32 v27, 0x3d372713, v16
	v_mul_f32_e32 v27, v16, v27
	v_fma_f32 v27, v16, v27, v16
	v_mul_f32_e32 v27, 0xbfcc422a, v27
	v_mul_f32_e32 v27, 0x3fb8aa3b, v27
	v_mul_f32_e32 v26, 0x3d372713, v20
	v_exp_f32_e32 v28, v27
	v_mul_f32_e32 v27, 0x3d372713, v21
	v_mul_f32_e32 v26, v20, v26
	v_mul_f32_e32 v27, v21, v27
	v_fma_f32 v26, v20, v26, v20
	v_fma_f32 v27, v21, v27, v21
	v_mul_f32_e32 v26, 0xbfcc422a, v26
	v_mul_f32_e32 v27, 0xbfcc422a, v27
	v_mul_f32_e32 v26, 0x3fb8aa3b, v26
	v_mul_f32_e32 v27, 0x3fb8aa3b, v27
	v_exp_f32_e32 v26, v26
	v_exp_f32_e32 v27, v27
	s_nop 0
	v_pk_add_f32 v[26:27], v[26:27], 1.0 op_sel_hi:[1,0]
	s_nop 0
	s_nop 0
	v_rcp_f32_e32 v29, v27
	s_nop 0
	v_mul_f32_e32 v27, v21, v29
	s_nop 0
	v_rcp_f32_e32 v21, v26
	s_nop 0
	v_mul_f32_e32 v26, v20, v21
	v_mul_f32_e32 v20, 0x3d372713, v17
	v_mul_f32_e32 v20, v17, v20
	v_fma_f32 v20, v17, v20, v17
	v_mul_f32_e32 v20, 0xbfcc422a, v20
	v_mul_f32_e32 v20, 0x3fb8aa3b, v20
	v_exp_f32_e32 v29, v20
	s_nop 0
	v_pk_add_f32 v[20:21], v[28:29], 1.0 op_sel_hi:[1,0]
	s_nop 0
	s_nop 0
	v_rcp_f32_e32 v28, v21
	s_nop 0
	v_mul_f32_e32 v28, v17, v28
	s_nop 0
	v_rcp_f32_e32 v17, v20
	s_nop 0
	v_mul_f32_e32 v29, v16, v17
	v_mul_f32_e32 v17, 0x3d372713, v18
	v_mul_f32_e32 v17, v18, v17
	v_fma_f32 v17, v18, v17, v18
	v_mul_f32_e32 v17, 0xbfcc422a, v17
	v_mul_f32_e32 v17, 0x3fb8aa3b, v17
	v_mul_f32_e32 v16, 0x3d372713, v22
	v_exp_f32_e32 v20, v17
	v_mul_f32_e32 v17, 0x3d372713, v23
	v_mul_f32_e32 v16, v22, v16
	v_mul_f32_e32 v17, v23, v17
	v_fma_f32 v16, v22, v16, v22
	v_fma_f32 v17, v23, v17, v23
	v_mul_f32_e32 v16, 0xbfcc422a, v16
	v_mul_f32_e32 v17, 0xbfcc422a, v17
	v_mul_f32_e32 v16, 0x3fb8aa3b, v16
	v_mul_f32_e32 v17, 0x3fb8aa3b, v17
	v_exp_f32_e32 v16, v16
	v_exp_f32_e32 v17, v17
	s_nop 0
	v_pk_add_f32 v[16:17], v[16:17], 1.0 op_sel_hi:[1,0]
	s_nop 0
	s_nop 0
	v_rcp_f32_e32 v21, v17
	s_nop 0
	v_mul_f32_e32 v23, v23, v21
	s_nop 0
	v_rcp_f32_e32 v17, v16
	s_nop 0
	v_mul_f32_e32 v22, v22, v17
	v_mul_f32_e32 v16, 0x3d372713, v19
	v_mul_f32_e32 v16, v19, v16
	v_fma_f32 v16, v19, v16, v19
	v_mul_f32_e32 v16, 0xbfcc422a, v16
	v_mul_f32_e32 v16, 0x3fb8aa3b, v16
	v_exp_f32_e32 v21, v16
	s_nop 0
	v_pk_add_f32 v[16:17], v[20:21], 1.0 op_sel_hi:[1,0]
	s_nop 0
	s_nop 0
	v_rcp_f32_e32 v20, v17
	s_nop 0
	v_mul_f32_e32 v19, v19, v20
	s_nop 0
	v_rcp_f32_e32 v17, v16
	s_nop 0
	v_mul_f32_e32 v20, v18, v17
	v_cvt_pk_bf16_f32 v19, v20, v19
	v_lshl_add_u64 v[20:21], v[24:25], 0, v[114:115]
	v_lshl_add_u64 v[20:21], v[20:21], 0, s[10:11]
	v_cvt_pk_bf16_f32 v16, v26, v27
	v_cvt_pk_bf16_f32 v17, v22, v23
	v_cvt_pk_bf16_f32 v18, v29, v28
	v_lshl_add_u64 v[20:21], v[20:21], 0, v[48:49]
	global_store_dwordx4 v[20:21], v[16:19], off
	s_nop 1
	v_mul_f32_e32 v17, 0x3d372713, v8
	v_mul_f32_e32 v17, v8, v17
	v_fma_f32 v17, v8, v17, v8
	v_mul_f32_e32 v17, 0xbfcc422a, v17
	v_mul_f32_e32 v17, 0x3fb8aa3b, v17
	v_mul_f32_e32 v16, 0x3d372713, v12
	v_exp_f32_e32 v18, v17
	v_mul_f32_e32 v17, 0x3d372713, v13
	v_mul_f32_e32 v16, v12, v16
	v_mul_f32_e32 v17, v13, v17
	v_fma_f32 v16, v12, v16, v12
	v_fma_f32 v17, v13, v17, v13
	v_mul_f32_e32 v16, 0xbfcc422a, v16
	v_mul_f32_e32 v17, 0xbfcc422a, v17
	v_mul_f32_e32 v16, 0x3fb8aa3b, v16
	v_mul_f32_e32 v17, 0x3fb8aa3b, v17
	v_exp_f32_e32 v16, v16
	v_exp_f32_e32 v17, v17
	s_nop 0
	v_pk_add_f32 v[16:17], v[16:17], 1.0 op_sel_hi:[1,0]
	s_nop 0
	s_nop 0
	v_rcp_f32_e32 v19, v17
	s_nop 0
	v_mul_f32_e32 v17, v13, v19
	s_nop 0
	v_rcp_f32_e32 v13, v16
	s_nop 0
	v_mul_f32_e32 v16, v12, v13
	v_mul_f32_e32 v12, 0x3d372713, v9
	v_mul_f32_e32 v12, v9, v12
	v_fma_f32 v12, v9, v12, v9
	v_mul_f32_e32 v12, 0xbfcc422a, v12
	v_mul_f32_e32 v12, 0x3fb8aa3b, v12
	v_exp_f32_e32 v19, v12
	s_nop 0
	v_pk_add_f32 v[12:13], v[18:19], 1.0 op_sel_hi:[1,0]
	s_nop 0
	s_nop 0
	v_rcp_f32_e32 v18, v13
	s_nop 0
	v_mul_f32_e32 v18, v9, v18
	s_nop 0
	v_rcp_f32_e32 v9, v12
	s_nop 0
	v_mul_f32_e32 v19, v8, v9
	v_mul_f32_e32 v9, 0x3d372713, v10
	v_mul_f32_e32 v9, v10, v9
	v_fma_f32 v9, v10, v9, v10
	v_mul_f32_e32 v9, 0xbfcc422a, v9
	v_mul_f32_e32 v9, 0x3fb8aa3b, v9
	v_mul_f32_e32 v8, 0x3d372713, v14
	v_exp_f32_e32 v12, v9
	v_mul_f32_e32 v9, 0x3d372713, v15
	v_mul_f32_e32 v8, v14, v8
	v_mul_f32_e32 v9, v15, v9
	v_fma_f32 v8, v14, v8, v14
	v_fma_f32 v9, v15, v9, v15
	v_mul_f32_e32 v8, 0xbfcc422a, v8
	v_mul_f32_e32 v9, 0xbfcc422a, v9
	v_mul_f32_e32 v8, 0x3fb8aa3b, v8
	v_mul_f32_e32 v9, 0x3fb8aa3b, v9
	v_exp_f32_e32 v8, v8
	v_exp_f32_e32 v9, v9
	s_nop 0
	v_pk_add_f32 v[8:9], v[8:9], 1.0 op_sel_hi:[1,0]
	s_nop 0
	s_nop 0
	v_rcp_f32_e32 v13, v9
	s_nop 0
	v_mul_f32_e32 v15, v15, v13
	s_nop 0
	v_rcp_f32_e32 v9, v8
	s_nop 0
	v_mul_f32_e32 v14, v14, v9
	v_mul_f32_e32 v8, 0x3d372713, v11
	v_mul_f32_e32 v8, v11, v8
	v_fma_f32 v8, v11, v8, v11
	v_mul_f32_e32 v8, 0xbfcc422a, v8
	v_mul_f32_e32 v8, 0x3fb8aa3b, v8
	v_exp_f32_e32 v13, v8
	s_nop 0
	v_pk_add_f32 v[8:9], v[12:13], 1.0 op_sel_hi:[1,0]
	s_nop 0
	s_nop 0
	v_rcp_f32_e32 v12, v9
	s_nop 0
	v_mul_f32_e32 v9, v11, v12
	s_mov_b64 s[12:13], 0x2c0000
	v_rcp_f32_e32 v11, v8
	s_nop 0
	v_mul_f32_e32 v8, v10, v11
	v_cvt_pk_bf16_f32 v13, v8, v9
	v_lshl_add_u64 v[8:9], v[122:123], 0, s[12:13]
	v_cvt_pk_bf16_f32 v11, v14, v15
	v_lshl_add_u64 v[14:15], v[8:9], 0, v[124:125]
	v_lshl_add_u64 v[14:15], v[14:15], 0, s[10:11]
	v_cvt_pk_bf16_f32 v10, v16, v17
	v_cvt_pk_bf16_f32 v12, v19, v18
	v_lshl_add_u64 v[14:15], v[14:15], 0, v[48:49]
	global_store_dwordx4 v[14:15], v[10:13], off
	s_nop 1
	v_mul_f32_e32 v11, 0x3d372713, v0
	v_mul_f32_e32 v11, v0, v11
	v_fma_f32 v11, v0, v11, v0
	v_mul_f32_e32 v11, 0xbfcc422a, v11
	v_mul_f32_e32 v11, 0x3fb8aa3b, v11
	v_mul_f32_e32 v10, 0x3d372713, v4
	v_exp_f32_e32 v12, v11
	v_mul_f32_e32 v11, 0x3d372713, v5
	v_mul_f32_e32 v10, v4, v10
	v_mul_f32_e32 v11, v5, v11
	v_fma_f32 v10, v4, v10, v4
	v_fma_f32 v11, v5, v11, v5
	v_mul_f32_e32 v10, 0xbfcc422a, v10
	v_mul_f32_e32 v11, 0xbfcc422a, v11
	v_mul_f32_e32 v10, 0x3fb8aa3b, v10
	v_mul_f32_e32 v11, 0x3fb8aa3b, v11
	v_exp_f32_e32 v10, v10
	v_exp_f32_e32 v11, v11
	s_nop 0
	v_pk_add_f32 v[10:11], v[10:11], 1.0 op_sel_hi:[1,0]
	s_nop 0
	s_nop 0
	v_rcp_f32_e32 v13, v11
	s_nop 0
	v_mul_f32_e32 v11, v5, v13
	s_nop 0
	v_rcp_f32_e32 v5, v10
	s_nop 0
	v_mul_f32_e32 v10, v4, v5
	v_mul_f32_e32 v4, 0x3d372713, v1
	v_mul_f32_e32 v4, v1, v4
	v_fma_f32 v4, v1, v4, v1
	v_mul_f32_e32 v4, 0xbfcc422a, v4
	v_mul_f32_e32 v4, 0x3fb8aa3b, v4
	v_exp_f32_e32 v13, v4
	s_nop 0
	v_pk_add_f32 v[4:5], v[12:13], 1.0 op_sel_hi:[1,0]
	s_nop 0
	s_nop 0
	v_rcp_f32_e32 v12, v5
	s_nop 0
	v_mul_f32_e32 v12, v1, v12
	s_nop 0
	v_rcp_f32_e32 v1, v4
	s_nop 0
	v_mul_f32_e32 v13, v0, v1
	v_mul_f32_e32 v1, 0x3d372713, v2
	v_mul_f32_e32 v1, v2, v1
	v_fma_f32 v1, v2, v1, v2
	v_mul_f32_e32 v1, 0xbfcc422a, v1
	v_mul_f32_e32 v1, 0x3fb8aa3b, v1
	v_mul_f32_e32 v0, 0x3d372713, v6
	v_exp_f32_e32 v4, v1
	v_mul_f32_e32 v1, 0x3d372713, v7
	v_mul_f32_e32 v0, v6, v0
	v_mul_f32_e32 v1, v7, v1
	v_fma_f32 v0, v6, v0, v6
	v_fma_f32 v1, v7, v1, v7
	v_mul_f32_e32 v0, 0xbfcc422a, v0
	v_mul_f32_e32 v1, 0xbfcc422a, v1
	v_mul_f32_e32 v0, 0x3fb8aa3b, v0
	v_mul_f32_e32 v1, 0x3fb8aa3b, v1
	v_exp_f32_e32 v0, v0
	v_exp_f32_e32 v1, v1
	s_nop 0
	v_pk_add_f32 v[0:1], v[0:1], 1.0 op_sel_hi:[1,0]
	s_nop 0
	s_nop 0
	v_rcp_f32_e32 v5, v1
	s_nop 0
	v_mul_f32_e32 v7, v7, v5
	s_nop 0
	v_rcp_f32_e32 v1, v0
	s_nop 0
	v_mul_f32_e32 v6, v6, v1
	v_mul_f32_e32 v0, 0x3d372713, v3
	v_mul_f32_e32 v0, v3, v0
	v_fma_f32 v0, v3, v0, v3
	v_mul_f32_e32 v0, 0xbfcc422a, v0
	v_mul_f32_e32 v0, 0x3fb8aa3b, v0
	v_exp_f32_e32 v5, v0
	s_nop 0
	v_pk_add_f32 v[0:1], v[4:5], 1.0 op_sel_hi:[1,0]
	s_nop 0
	s_nop 0
	v_rcp_f32_e32 v4, v1
	s_nop 0
	v_mul_f32_e32 v3, v3, v4
	s_mov_b64 s[12:13], s[6:7]
	v_rcp_f32_e32 v1, v0
	s_nop 0
	v_mul_f32_e32 v4, v2, v1
	v_cvt_pk_bf16_f32 v3, v4, v3
	v_lshl_add_u64 v[4:5], v[8:9], 0, v[114:115]
	v_lshl_add_u64 v[4:5], v[4:5], 0, s[10:11]
	v_cvt_pk_bf16_f32 v0, v10, v11
	v_cvt_pk_bf16_f32 v1, v6, v7
	v_cvt_pk_bf16_f32 v2, v13, v12
	v_lshl_add_u64 v[4:5], v[4:5], 0, v[48:49]
	s_and_b64 vcc, exec, s[8:9]
	s_mov_b64 s[10:11], s[4:5]
	global_store_dwordx4 v[4:5], v[0:3], off
	s_cbranch_vccz .LBB0_819
	s_waitcnt vmcnt(0)
	s_cmpk_gt_u32 s18, 0xff
	s_cbranch_scc1 .LBB0_826
	s_barrier

.LBB0_1056:
	ds_read_b128 v[130:133], v203
	ds_read_b128 v[134:137], v203 offset:1024
	ds_read_b128 v[138:141], v203 offset:2048
	ds_read_b128 v[142:145], v203 offset:3072
	s_add_i32 s56, s28, 2
	s_add_u32 s29, s24, 0xfffc0080
	s_addc_u32 s30, s25, -1
	s_add_i32 s57, 0, 0x10000
	s_cmp_eq_u32 s17, s28
	s_cselect_b32 s28, s22, s19
	s_cselect_b32 s31, s21, s30
	s_cselect_b32 s30, s20, s29
	s_cselect_b32 s29, s23, s27
	s_add_i32 m0, s39, 0xc000
	ds_read_b128 v[146:149], v217
	ds_read_b128 v[150:153], v217 offset:1024
	ds_read_b128 v[154:157], v217 offset:2048
	ds_read_b128 v[158:161], v217 offset:3072
	ds_read_b128 v[162:165], v217 offset:4096
	ds_read_b128 v[166:169], v217 offset:5120
	ds_read_b128 v[170:173], v217 offset:6144
	ds_read_b128 v[174:177], v217 offset:7168
	global_load_lds_dwordx4 v204, s[24:25]
	s_add_i32 m0, s39, 0xe000
	s_nop 0
	global_load_lds_dwordx4 v206, s[24:25]
	s_waitcnt lgkmcnt(8)
	s_barrier
	s_waitcnt lgkmcnt(0)
	s_setprio 1
	s_waitcnt lgkmcnt(0)
	v_mfma_f32_16x16x32_bf16 v[126:129], v[130:133], v[146:149], v[126:129]
	v_mfma_f32_16x16x32_bf16 v[122:125], v[138:141], v[146:149], v[122:125]
	v_mfma_f32_16x16x32_bf16 v[118:121], v[130:133], v[154:157], v[118:121]
	v_mfma_f32_16x16x32_bf16 v[114:117], v[138:141], v[154:157], v[114:117]
	v_mfma_f32_16x16x32_bf16 v[102:105], v[130:133], v[162:165], v[102:105]
	v_mfma_f32_16x16x32_bf16 v[98:101], v[138:141], v[162:165], v[98:101]
	v_mfma_f32_16x16x32_bf16 v[86:89], v[130:133], v[170:173], v[86:89]
	v_mfma_f32_16x16x32_bf16 v[82:85], v[138:141], v[170:173], v[82:85]
	v_mfma_f32_16x16x32_bf16 v[126:129], v[134:137], v[150:153], v[126:129]
	v_mfma_f32_16x16x32_bf16 v[122:125], v[142:145], v[150:153], v[122:125]
	v_mfma_f32_16x16x32_bf16 v[118:121], v[134:137], v[158:161], v[118:121]
	v_mfma_f32_16x16x32_bf16 v[114:117], v[142:145], v[158:161], v[114:117]
	v_mfma_f32_16x16x32_bf16 v[102:105], v[134:137], v[166:169], v[102:105]
	v_mfma_f32_16x16x32_bf16 v[98:101], v[142:145], v[166:169], v[98:101]
	v_mfma_f32_16x16x32_bf16 v[86:89], v[134:137], v[174:177], v[86:89]
	v_mfma_f32_16x16x32_bf16 v[82:85], v[142:145], v[174:177], v[82:85]
	s_setprio 0
	s_barrier
	s_add_i32 s60, 0, 0x14000
	s_add_i32 s57, s57, s38
	s_mov_b32 m0, s57
	ds_read_b128 v[178:181], v203 offset:16384
	ds_read_b128 v[182:185], v203 offset:17408
	ds_read_b128 v[186:189], v203 offset:18432
	ds_read_b128 v[190:193], v203 offset:19456
	global_load_lds_dwordx4 v48, s[28:29]
	s_add_i32 m0, s57, 0x2000
	s_nop 0
	global_load_lds_dwordx4 v202, s[28:29]
	s_barrier
	s_waitcnt lgkmcnt(0)
	s_setprio 1
	s_waitcnt lgkmcnt(0)
	v_mfma_f32_16x16x32_bf16 v[110:113], v[178:181], v[146:149], v[110:113]
	v_mfma_f32_16x16x32_bf16 v[106:109], v[186:189], v[146:149], v[106:109]
	v_mfma_f32_16x16x32_bf16 v[94:97], v[178:181], v[154:157], v[94:97]
	v_mfma_f32_16x16x32_bf16 v[90:93], v[186:189], v[154:157], v[90:93]
	v_mfma_f32_16x16x32_bf16 v[78:81], v[178:181], v[162:165], v[78:81]
	v_mfma_f32_16x16x32_bf16 v[74:77], v[186:189], v[162:165], v[74:77]
	v_mfma_f32_16x16x32_bf16 v[70:73], v[178:181], v[170:173], v[70:73]
	v_mfma_f32_16x16x32_bf16 v[66:69], v[186:189], v[170:173], v[66:69]
	v_mfma_f32_16x16x32_bf16 v[110:113], v[182:185], v[150:153], v[110:113]
	v_mfma_f32_16x16x32_bf16 v[106:109], v[190:193], v[150:153], v[106:109]
	v_mfma_f32_16x16x32_bf16 v[94:97], v[182:185], v[158:161], v[94:97]
	v_mfma_f32_16x16x32_bf16 v[90:93], v[190:193], v[158:161], v[90:93]
	v_mfma_f32_16x16x32_bf16 v[78:81], v[182:185], v[166:169], v[78:81]
	v_mfma_f32_16x16x32_bf16 v[74:77], v[190:193], v[166:169], v[74:77]
	v_mfma_f32_16x16x32_bf16 v[70:73], v[182:185], v[174:177], v[70:73]
	v_mfma_f32_16x16x32_bf16 v[66:69], v[190:193], v[174:177], v[66:69]
	s_setprio 0
	s_mov_b32 m0, s39
	v_lshl_add_u64 v[212:213], s[30:31], 0, v[198:199]
	s_barrier
	ds_read_b128 v[146:149], v217 offset:16384
	ds_read_b128 v[150:153], v217 offset:17408
	ds_read_b128 v[154:157], v217 offset:18432
	ds_read_b128 v[158:161], v217 offset:19456
	ds_read_b128 v[162:165], v217 offset:20480
	ds_read_b128 v[166:169], v217 offset:21504
	ds_read_b128 v[170:173], v217 offset:22528
	ds_read_b128 v[174:177], v217 offset:23552
	global_load_lds_dwordx4 v[212:213], off
	v_lshl_add_u64 v[218:219], s[30:31], 0, v[200:201]
	s_mov_b32 m0, s40
	s_nop 0
	global_load_lds_dwordx4 v[218:219], off
	s_barrier
	s_waitcnt lgkmcnt(0)
	s_setprio 1
	s_waitcnt lgkmcnt(0)
	v_mfma_f32_16x16x32_bf16 v[62:65], v[130:133], v[146:149], v[62:65]
	v_mfma_f32_16x16x32_bf16 v[58:61], v[138:141], v[146:149], v[58:61]
	v_mfma_f32_16x16x32_bf16 v[54:57], v[130:133], v[154:157], v[54:57]
	v_mfma_f32_16x16x32_bf16 v[50:53], v[138:141], v[154:157], v[50:53]
	v_mfma_f32_16x16x32_bf16 v[36:39], v[130:133], v[162:165], v[36:39]
	v_mfma_f32_16x16x32_bf16 v[32:35], v[138:141], v[162:165], v[32:35]
	v_mfma_f32_16x16x32_bf16 v[20:23], v[130:133], v[170:173], v[20:23]
	v_mfma_f32_16x16x32_bf16 v[16:19], v[138:141], v[170:173], v[16:19]
	v_mfma_f32_16x16x32_bf16 v[62:65], v[134:137], v[150:153], v[62:65]
	v_mfma_f32_16x16x32_bf16 v[58:61], v[142:145], v[150:153], v[58:61]
	v_mfma_f32_16x16x32_bf16 v[54:57], v[134:137], v[158:161], v[54:57]
	v_mfma_f32_16x16x32_bf16 v[50:53], v[142:145], v[158:161], v[50:53]
	v_mfma_f32_16x16x32_bf16 v[36:39], v[134:137], v[166:169], v[36:39]
	v_mfma_f32_16x16x32_bf16 v[32:35], v[142:145], v[166:169], v[32:35]
	v_mfma_f32_16x16x32_bf16 v[20:23], v[134:137], v[174:177], v[20:23]
	v_mfma_f32_16x16x32_bf16 v[16:19], v[142:145], v[174:177], v[16:19]
	s_setprio 0
	s_barrier
	s_add_u32 s58, s28, 0x40000
	s_addc_u32 s59, s29, 0
	s_add_i32 s57, s60, s38
	s_mov_b32 m0, s57
	s_nop 0
	global_load_lds_dwordx4 v48, s[58:59]
	s_add_i32 m0, s57, 0x2000
	s_nop 0
	global_load_lds_dwordx4 v202, s[58:59]
	s_waitcnt vmcnt(6)
	s_barrier
	s_setprio 1
	v_mfma_f32_16x16x32_bf16 v[44:47], v[178:181], v[146:149], v[44:47]
	v_mfma_f32_16x16x32_bf16 v[40:43], v[186:189], v[146:149], v[40:43]
	v_mfma_f32_16x16x32_bf16 v[28:31], v[178:181], v[154:157], v[28:31]
	v_mfma_f32_16x16x32_bf16 v[24:27], v[186:189], v[154:157], v[24:27]
	v_mfma_f32_16x16x32_bf16 v[12:15], v[178:181], v[162:165], v[12:15]
	v_mfma_f32_16x16x32_bf16 v[8:11], v[186:189], v[162:165], v[8:11]
	v_mfma_f32_16x16x32_bf16 v[4:7], v[178:181], v[170:173], v[4:7]
	v_mfma_f32_16x16x32_bf16 v[0:3], v[186:189], v[170:173], v[0:3]
	v_mfma_f32_16x16x32_bf16 v[44:47], v[182:185], v[150:153], v[44:47]
	v_mfma_f32_16x16x32_bf16 v[40:43], v[190:193], v[150:153], v[40:43]
	v_mfma_f32_16x16x32_bf16 v[28:31], v[182:185], v[158:161], v[28:31]
	v_mfma_f32_16x16x32_bf16 v[24:27], v[190:193], v[158:161], v[24:27]
	v_mfma_f32_16x16x32_bf16 v[12:15], v[182:185], v[166:169], v[12:15]
	v_mfma_f32_16x16x32_bf16 v[8:11], v[190:193], v[166:169], v[8:11]
	v_mfma_f32_16x16x32_bf16 v[4:7], v[182:185], v[174:177], v[4:7]
	v_mfma_f32_16x16x32_bf16 v[0:3], v[190:193], v[174:177], v[0:3]
	s_setprio 0
	s_add_i32 s57, 0, 0x18000
	s_barrier
	ds_read_b128 v[130:133], v203 offset:32768
	ds_read_b128 v[134:137], v203 offset:33792
	ds_read_b128 v[138:141], v203 offset:34816
	ds_read_b128 v[142:145], v203 offset:35840
	s_add_u32 s30, s30, 0x40000
	s_addc_u32 s31, s31, 0
	s_mov_b32 m0, s41
	ds_read_b128 v[146:149], v217 offset:32768
	ds_read_b128 v[150:153], v217 offset:33792
	ds_read_b128 v[154:157], v217 offset:34816
	ds_read_b128 v[158:161], v217 offset:35840
	ds_read_b128 v[162:165], v217 offset:36864
	ds_read_b128 v[166:169], v217 offset:37888
	ds_read_b128 v[170:173], v217 offset:38912
	ds_read_b128 v[174:177], v217 offset:39936
	global_load_lds_dwordx4 v198, s[30:31]
	s_mov_b32 m0, s42
	s_nop 0
	global_load_lds_dwordx4 v200, s[30:31]
	s_waitcnt lgkmcnt(8)
	s_barrier
	s_waitcnt lgkmcnt(0)
	s_setprio 1
	s_waitcnt lgkmcnt(0)
	v_mfma_f32_16x16x32_bf16 v[126:129], v[130:133], v[146:149], v[126:129]
	v_mfma_f32_16x16x32_bf16 v[122:125], v[138:141], v[146:149], v[122:125]
	v_mfma_f32_16x16x32_bf16 v[118:121], v[130:133], v[154:157], v[118:121]
	v_mfma_f32_16x16x32_bf16 v[114:117], v[138:141], v[154:157], v[114:117]
	v_mfma_f32_16x16x32_bf16 v[102:105], v[130:133], v[162:165], v[102:105]
	v_mfma_f32_16x16x32_bf16 v[98:101], v[138:141], v[162:165], v[98:101]
	v_mfma_f32_16x16x32_bf16 v[86:89], v[130:133], v[170:173], v[86:89]
	v_mfma_f32_16x16x32_bf16 v[82:85], v[138:141], v[170:173], v[82:85]
	v_mfma_f32_16x16x32_bf16 v[126:129], v[134:137], v[150:153], v[126:129]
	v_mfma_f32_16x16x32_bf16 v[122:125], v[142:145], v[150:153], v[122:125]
	v_mfma_f32_16x16x32_bf16 v[118:121], v[134:137], v[158:161], v[118:121]
	v_mfma_f32_16x16x32_bf16 v[114:117], v[142:145], v[158:161], v[114:117]
	v_mfma_f32_16x16x32_bf16 v[102:105], v[134:137], v[166:169], v[102:105]
	v_mfma_f32_16x16x32_bf16 v[98:101], v[142:145], v[166:169], v[98:101]
	v_mfma_f32_16x16x32_bf16 v[86:89], v[134:137], v[174:177], v[86:89]
	v_mfma_f32_16x16x32_bf16 v[82:85], v[142:145], v[174:177], v[82:85]
	s_setprio 0
	s_barrier
	s_add_i32 s30, 0, 0x1c000
	s_add_i32 s31, s57, s38
	s_add_u32 s58, s28, s66
	s_addc_u32 s59, s29, s67
	s_mov_b32 m0, s31
	ds_read_b128 v[178:181], v203 offset:49152
	ds_read_b128 v[182:185], v203 offset:50176
	ds_read_b128 v[186:189], v203 offset:51200
	ds_read_b128 v[190:193], v203 offset:52224
	global_load_lds_dwordx4 v48, s[58:59]
	s_add_i32 m0, s31, 0x2000
	s_nop 0
	global_load_lds_dwordx4 v202, s[58:59]
	s_barrier
	s_waitcnt lgkmcnt(0)
	s_setprio 1
	s_waitcnt lgkmcnt(0)
	v_mfma_f32_16x16x32_bf16 v[110:113], v[178:181], v[146:149], v[110:113]
	v_mfma_f32_16x16x32_bf16 v[106:109], v[186:189], v[146:149], v[106:109]
	v_mfma_f32_16x16x32_bf16 v[94:97], v[178:181], v[154:157], v[94:97]
	v_mfma_f32_16x16x32_bf16 v[90:93], v[186:189], v[154:157], v[90:93]
	v_mfma_f32_16x16x32_bf16 v[78:81], v[178:181], v[162:165], v[78:81]
	v_mfma_f32_16x16x32_bf16 v[74:77], v[186:189], v[162:165], v[74:77]
	v_mfma_f32_16x16x32_bf16 v[70:73], v[178:181], v[170:173], v[70:73]
	v_mfma_f32_16x16x32_bf16 v[66:69], v[186:189], v[170:173], v[66:69]
	v_mfma_f32_16x16x32_bf16 v[110:113], v[182:185], v[150:153], v[110:113]
	v_mfma_f32_16x16x32_bf16 v[106:109], v[190:193], v[150:153], v[106:109]
	v_mfma_f32_16x16x32_bf16 v[94:97], v[182:185], v[158:161], v[94:97]
	v_mfma_f32_16x16x32_bf16 v[90:93], v[190:193], v[158:161], v[90:93]
	v_mfma_f32_16x16x32_bf16 v[78:81], v[182:185], v[166:169], v[78:81]
	v_mfma_f32_16x16x32_bf16 v[74:77], v[190:193], v[166:169], v[74:77]
	v_mfma_f32_16x16x32_bf16 v[70:73], v[182:185], v[174:177], v[70:73]
	v_mfma_f32_16x16x32_bf16 v[66:69], v[190:193], v[174:177], v[66:69]
	s_setprio 0
	s_mov_b32 m0, s49
	v_lshl_add_u64 v[208:209], v[212:213], 0, s[66:67]
	s_barrier
	ds_read_b128 v[146:149], v217 offset:49152
	ds_read_b128 v[150:153], v217 offset:50176
	ds_read_b128 v[154:157], v217 offset:51200
	ds_read_b128 v[158:161], v217 offset:52224
	ds_read_b128 v[162:165], v217 offset:53248
	ds_read_b128 v[166:169], v217 offset:54272
	ds_read_b128 v[170:173], v217 offset:55296
	ds_read_b128 v[174:177], v217 offset:56320
	global_load_lds_dwordx4 v[208:209], off
	v_lshl_add_u64 v[208:209], v[218:219], 0, s[66:67]
	s_mov_b32 m0, s50
	s_nop 0
	global_load_lds_dwordx4 v[208:209], off
	s_barrier
	s_waitcnt lgkmcnt(0)
	s_setprio 1
	s_waitcnt lgkmcnt(0)
	v_mfma_f32_16x16x32_bf16 v[62:65], v[130:133], v[146:149], v[62:65]
	v_mfma_f32_16x16x32_bf16 v[58:61], v[138:141], v[146:149], v[58:61]
	v_mfma_f32_16x16x32_bf16 v[54:57], v[130:133], v[154:157], v[54:57]
	v_mfma_f32_16x16x32_bf16 v[50:53], v[138:141], v[154:157], v[50:53]
	v_mfma_f32_16x16x32_bf16 v[36:39], v[130:133], v[162:165], v[36:39]
	v_mfma_f32_16x16x32_bf16 v[32:35], v[138:141], v[162:165], v[32:35]
	v_mfma_f32_16x16x32_bf16 v[20:23], v[130:133], v[170:173], v[20:23]
	v_mfma_f32_16x16x32_bf16 v[16:19], v[138:141], v[170:173], v[16:19]
	v_mfma_f32_16x16x32_bf16 v[62:65], v[134:137], v[150:153], v[62:65]
	v_mfma_f32_16x16x32_bf16 v[58:61], v[142:145], v[150:153], v[58:61]
	v_mfma_f32_16x16x32_bf16 v[54:57], v[134:137], v[158:161], v[54:57]
	v_mfma_f32_16x16x32_bf16 v[50:53], v[142:145], v[158:161], v[50:53]
	v_mfma_f32_16x16x32_bf16 v[36:39], v[134:137], v[166:169], v[36:39]
	v_mfma_f32_16x16x32_bf16 v[32:35], v[142:145], v[166:169], v[32:35]
	v_mfma_f32_16x16x32_bf16 v[20:23], v[134:137], v[174:177], v[20:23]
	v_mfma_f32_16x16x32_bf16 v[16:19], v[142:145], v[174:177], v[16:19]
	s_setprio 0
	s_barrier
	s_add_u32 s28, s28, 0x40080
	s_addc_u32 s29, s29, 0
	s_add_i32 s30, s30, s38
	s_mov_b32 m0, s30
	s_nop 0
	global_load_lds_dwordx4 v48, s[28:29]
	s_add_i32 m0, s30, 0x2000
	s_nop 0
	global_load_lds_dwordx4 v202, s[28:29]
	s_waitcnt vmcnt(6)
	s_barrier
	s_setprio 1
	v_mfma_f32_16x16x32_bf16 v[44:47], v[178:181], v[146:149], v[44:47]
	v_mfma_f32_16x16x32_bf16 v[40:43], v[186:189], v[146:149], v[40:43]
	v_mfma_f32_16x16x32_bf16 v[28:31], v[178:181], v[154:157], v[28:31]
	v_mfma_f32_16x16x32_bf16 v[24:27], v[186:189], v[154:157], v[24:27]
	v_mfma_f32_16x16x32_bf16 v[12:15], v[178:181], v[162:165], v[12:15]
	v_mfma_f32_16x16x32_bf16 v[8:11], v[186:189], v[162:165], v[8:11]
	v_mfma_f32_16x16x32_bf16 v[4:7], v[178:181], v[170:173], v[4:7]
	v_mfma_f32_16x16x32_bf16 v[0:3], v[186:189], v[170:173], v[0:3]
	v_mfma_f32_16x16x32_bf16 v[44:47], v[182:185], v[150:153], v[44:47]
	v_mfma_f32_16x16x32_bf16 v[40:43], v[190:193], v[150:153], v[40:43]
	v_mfma_f32_16x16x32_bf16 v[28:31], v[182:185], v[158:161], v[28:31]
	v_mfma_f32_16x16x32_bf16 v[24:27], v[190:193], v[158:161], v[24:27]
	v_mfma_f32_16x16x32_bf16 v[12:15], v[182:185], v[166:169], v[12:15]
	v_mfma_f32_16x16x32_bf16 v[8:11], v[190:193], v[166:169], v[8:11]
	v_mfma_f32_16x16x32_bf16 v[4:7], v[182:185], v[174:177], v[4:7]
	v_mfma_f32_16x16x32_bf16 v[0:3], v[190:193], v[174:177], v[0:3]
	s_setprio 0
	s_add_u32 s24, s24, 0x100
	s_addc_u32 s25, s25, 0
	s_add_u32 s19, s19, 0x100
	s_addc_u32 s27, s27, 0
	s_cmp_ge_i32 s56, s1
	s_mov_b32 s28, s56
	s_barrier
	s_cbranch_scc0 .LBB0_1056
	v_mov_b32_e32 v130, v214
	v_mov_b32_e32 v131, v215
	s_bitcmp1_b32 s55, 0
	v_add_u32_e32 v134, s47, v130
	v_lshlrev_b32_e32 v130, 8, v134
	v_lshl_add_u32 v132, v131, 3, s48
	v_ashrrev_i32_e32 v131, 31, v130
	v_lshl_add_u64 v[130:131], v[130:131], 1, s[12:13]
	v_ashrrev_i32_e32 v133, 31, v132
	s_cselect_b64 s[28:29], -1, 0
	v_lshlrev_b32_e32 v208, 9, v215
	v_lshl_add_u32 v208, v214, 4, v208
	v_lshl_add_u32 v208, s47, 9, v208
	v_lshl_add_u32 v208, s48, 6, v208
	v_mov_b32_e32 v209, 0
	v_lshl_add_u64 v[208:209], v[208:209], 0, s[12:13]
	s_mov_b64 s[24:25], -1
	s_and_b64 vcc, exec, s[28:29]
	s_mov_b32 s57, s81
	s_cbranch_vccz .LBB0_1093
	s_mov_b64 s[24:25], 0x20000
	v_lshl_add_u64 v[130:131], v[208:209], 0, s[24:25]
	s_and_b32 s1, s55, -2
	s_mov_b64 s[24:25], 0x100
	s_cmp_lg_u32 s1, 4
	v_mov_b64_e32 v[210:211], v[130:131]
	s_cbranch_scc1 .LBB0_1060
	v_lshl_add_u32 v134, s26, 8, v134
	v_ashrrev_i32_e32 v135, 31, v134
	v_lshlrev_b64 v[134:135], 11, v[134:135]
	s_lshl_b32 s0, s0, 8
	v_lshl_add_u64 v[134:135], s[14:15], 0, v[134:135]
	s_ashr_i32 s1, s0, 31
	v_lshl_add_u64 v[134:135], s[0:1], 1, v[134:135]
	v_lshl_add_u64 v[210:211], v[132:133], 1, v[134:135]
	s_mov_b64 s[24:25], 0x400

.LBB0_1202:
	ds_read_b128 v[130:133], v218
	ds_read_b128 v[134:137], v218 offset:1024
	ds_read_b128 v[138:141], v218 offset:2048
	ds_read_b128 v[142:145], v218 offset:3072
	s_add_u32 s28, s26, 0xfffc0080
	s_addc_u32 s29, s27, -1
	s_add_i32 s49, 0, 0x10000
	s_cmp_eq_u32 s25, 12
	s_cselect_b32 s31, s19, s29
	s_cselect_b32 s30, s18, s28
	s_cselect_b32 s29, s21, s17
	s_cselect_b32 s28, s20, s15
	v_lshl_add_u64 v[190:191], s[26:27], 0, v[150:151]
	s_add_i32 m0, s23, 0xc000
	ds_read_b128 v[154:157], v172
	ds_read_b128 v[158:161], v172 offset:1024
	ds_read_b128 v[162:165], v172 offset:2048
	ds_read_b128 v[166:169], v172 offset:3072
	ds_read_b128 v[174:177], v172 offset:4096
	ds_read_b128 v[178:181], v172 offset:5120
	ds_read_b128 v[182:185], v172 offset:6144
	ds_read_b128 v[186:189], v172 offset:7168
	global_load_lds_dwordx4 v[190:191], off
	v_lshl_add_u64 v[190:191], s[26:27], 0, v[152:153]
	s_add_i32 m0, s23, 0xe000
	s_nop 0
	global_load_lds_dwordx4 v[190:191], off
	s_waitcnt lgkmcnt(8)
	s_barrier
	s_waitcnt lgkmcnt(0)
	s_setprio 1
	s_waitcnt lgkmcnt(0)
	v_mfma_f32_16x16x32_bf16 v[126:129], v[130:133], v[154:157], v[126:129]
	v_mfma_f32_16x16x32_bf16 v[122:125], v[138:141], v[154:157], v[122:125]
	v_mfma_f32_16x16x32_bf16 v[114:117], v[130:133], v[162:165], v[114:117]
	v_mfma_f32_16x16x32_bf16 v[106:109], v[138:141], v[162:165], v[106:109]
	v_mfma_f32_16x16x32_bf16 v[94:97], v[130:133], v[174:177], v[94:97]
	v_mfma_f32_16x16x32_bf16 v[90:93], v[138:141], v[174:177], v[90:93]
	v_mfma_f32_16x16x32_bf16 v[82:85], v[130:133], v[182:185], v[82:85]
	v_mfma_f32_16x16x32_bf16 v[74:77], v[138:141], v[182:185], v[74:77]
	v_mfma_f32_16x16x32_bf16 v[126:129], v[134:137], v[158:161], v[126:129]
	v_mfma_f32_16x16x32_bf16 v[122:125], v[142:145], v[158:161], v[122:125]
	v_mfma_f32_16x16x32_bf16 v[114:117], v[134:137], v[166:169], v[114:117]
	v_mfma_f32_16x16x32_bf16 v[106:109], v[142:145], v[166:169], v[106:109]
	v_mfma_f32_16x16x32_bf16 v[94:97], v[134:137], v[178:181], v[94:97]
	v_mfma_f32_16x16x32_bf16 v[90:93], v[142:145], v[178:181], v[90:93]
	v_mfma_f32_16x16x32_bf16 v[82:85], v[134:137], v[186:189], v[82:85]
	v_mfma_f32_16x16x32_bf16 v[74:77], v[142:145], v[186:189], v[74:77]
	s_setprio 0
	s_barrier
	s_add_i32 s52, 0, 0x14000
	s_add_i32 s49, s49, s35
	s_mov_b32 m0, s49
	ds_read_b128 v[190:193], v218 offset:16384
	ds_read_b128 v[198:201], v218 offset:17408
	ds_read_b128 v[202:205], v218 offset:18432
	ds_read_b128 v[206:209], v218 offset:19456
	global_load_lds_dwordx4 v48, s[28:29]
	v_lshl_add_u64 v[212:213], s[28:29], 0, v[146:147]
	s_add_i32 m0, s49, 0x2000
	s_nop 0
	global_load_lds_dwordx4 v[212:213], off
	s_barrier
	s_waitcnt lgkmcnt(0)
	s_setprio 1
	s_waitcnt lgkmcnt(0)
	v_mfma_f32_16x16x32_bf16 v[118:121], v[190:193], v[154:157], v[118:121]
	v_mfma_f32_16x16x32_bf16 v[110:113], v[202:205], v[154:157], v[110:113]
	v_mfma_f32_16x16x32_bf16 v[102:105], v[190:193], v[162:165], v[102:105]
	v_mfma_f32_16x16x32_bf16 v[98:101], v[202:205], v[162:165], v[98:101]
	v_mfma_f32_16x16x32_bf16 v[86:89], v[190:193], v[174:177], v[86:89]
	v_mfma_f32_16x16x32_bf16 v[78:81], v[202:205], v[174:177], v[78:81]
	v_mfma_f32_16x16x32_bf16 v[70:73], v[190:193], v[182:185], v[70:73]
	v_mfma_f32_16x16x32_bf16 v[66:69], v[202:205], v[182:185], v[66:69]
	v_mfma_f32_16x16x32_bf16 v[118:121], v[198:201], v[158:161], v[118:121]
	v_mfma_f32_16x16x32_bf16 v[110:113], v[206:209], v[158:161], v[110:113]
	v_mfma_f32_16x16x32_bf16 v[102:105], v[198:201], v[166:169], v[102:105]
	v_mfma_f32_16x16x32_bf16 v[98:101], v[206:209], v[166:169], v[98:101]
	v_mfma_f32_16x16x32_bf16 v[86:89], v[198:201], v[178:181], v[86:89]
	v_mfma_f32_16x16x32_bf16 v[78:81], v[206:209], v[178:181], v[78:81]
	v_mfma_f32_16x16x32_bf16 v[70:73], v[198:201], v[186:189], v[70:73]
	v_mfma_f32_16x16x32_bf16 v[66:69], v[206:209], v[186:189], v[66:69]
	s_setprio 0
	s_mov_b32 m0, s23
	v_lshl_add_u64 v[214:215], s[30:31], 0, v[48:49]
	s_barrier
	ds_read_b128 v[154:157], v172 offset:16384
	ds_read_b128 v[158:161], v172 offset:17408
	ds_read_b128 v[162:165], v172 offset:18432
	ds_read_b128 v[166:169], v172 offset:19456
	ds_read_b128 v[174:177], v172 offset:20480
	ds_read_b128 v[178:181], v172 offset:21504
	ds_read_b128 v[182:185], v172 offset:22528
	ds_read_b128 v[186:189], v172 offset:23552
	global_load_lds_dwordx4 v[214:215], off
	v_lshl_add_u64 v[216:217], s[30:31], 0, v[146:147]
	s_mov_b32 m0, s41
	s_nop 0
	global_load_lds_dwordx4 v[216:217], off
	s_barrier
	s_waitcnt lgkmcnt(0)
	s_setprio 1
	s_waitcnt lgkmcnt(0)
	v_mfma_f32_16x16x32_bf16 v[62:65], v[130:133], v[154:157], v[62:65]
	v_mfma_f32_16x16x32_bf16 v[58:61], v[138:141], v[154:157], v[58:61]
	v_mfma_f32_16x16x32_bf16 v[50:53], v[130:133], v[162:165], v[50:53]
	v_mfma_f32_16x16x32_bf16 v[40:43], v[138:141], v[162:165], v[40:43]
	v_mfma_f32_16x16x32_bf16 v[32:35], v[130:133], v[174:177], v[32:35]
	v_mfma_f32_16x16x32_bf16 v[24:27], v[138:141], v[174:177], v[24:27]
	v_mfma_f32_16x16x32_bf16 v[16:19], v[130:133], v[182:185], v[16:19]
	v_mfma_f32_16x16x32_bf16 v[8:11], v[138:141], v[182:185], v[8:11]
	v_mfma_f32_16x16x32_bf16 v[62:65], v[134:137], v[158:161], v[62:65]
	v_mfma_f32_16x16x32_bf16 v[58:61], v[142:145], v[158:161], v[58:61]
	v_mfma_f32_16x16x32_bf16 v[50:53], v[134:137], v[166:169], v[50:53]
	v_mfma_f32_16x16x32_bf16 v[40:43], v[142:145], v[166:169], v[40:43]
	v_mfma_f32_16x16x32_bf16 v[32:35], v[134:137], v[178:181], v[32:35]
	v_mfma_f32_16x16x32_bf16 v[24:27], v[142:145], v[178:181], v[24:27]
	v_mfma_f32_16x16x32_bf16 v[16:19], v[134:137], v[186:189], v[16:19]
	v_mfma_f32_16x16x32_bf16 v[8:11], v[142:145], v[186:189], v[8:11]
	s_setprio 0
	s_barrier
	s_add_u32 s50, s28, 0x40000
	s_addc_u32 s51, s29, 0
	s_add_i32 s49, s52, s35
	s_mov_b32 m0, s49
	s_nop 0
	global_load_lds_dwordx4 v48, s[50:51]
	v_lshl_add_u64 v[130:131], s[50:51], 0, v[146:147]
	s_add_i32 m0, s49, 0x2000
	s_nop 0
	global_load_lds_dwordx4 v[130:131], off
	s_waitcnt vmcnt(6)
	s_barrier
	s_setprio 1
	v_mfma_f32_16x16x32_bf16 v[54:57], v[190:193], v[154:157], v[54:57]
	v_mfma_f32_16x16x32_bf16 v[44:47], v[202:205], v[154:157], v[44:47]
	v_mfma_f32_16x16x32_bf16 v[36:39], v[190:193], v[162:165], v[36:39]
	v_mfma_f32_16x16x32_bf16 v[28:31], v[202:205], v[162:165], v[28:31]
	v_mfma_f32_16x16x32_bf16 v[20:23], v[190:193], v[174:177], v[20:23]
	v_mfma_f32_16x16x32_bf16 v[12:15], v[202:205], v[174:177], v[12:15]
	v_mfma_f32_16x16x32_bf16 v[4:7], v[190:193], v[182:185], v[4:7]
	v_mfma_f32_16x16x32_bf16 v[0:3], v[202:205], v[182:185], v[0:3]
	v_mfma_f32_16x16x32_bf16 v[54:57], v[198:201], v[158:161], v[54:57]
	v_mfma_f32_16x16x32_bf16 v[44:47], v[206:209], v[158:161], v[44:47]
	v_mfma_f32_16x16x32_bf16 v[36:39], v[198:201], v[166:169], v[36:39]
	v_mfma_f32_16x16x32_bf16 v[28:31], v[206:209], v[166:169], v[28:31]
	v_mfma_f32_16x16x32_bf16 v[20:23], v[198:201], v[178:181], v[20:23]
	v_mfma_f32_16x16x32_bf16 v[12:15], v[206:209], v[178:181], v[12:15]
	v_mfma_f32_16x16x32_bf16 v[4:7], v[198:201], v[186:189], v[4:7]
	v_mfma_f32_16x16x32_bf16 v[0:3], v[206:209], v[186:189], v[0:3]
	s_setprio 0
	s_add_i32 s49, 0, 0x18000
	s_barrier
	ds_read_b128 v[130:133], v218 offset:32768
	ds_read_b128 v[134:137], v218 offset:33792
	ds_read_b128 v[138:141], v218 offset:34816
	ds_read_b128 v[142:145], v218 offset:35840
	s_add_u32 s30, s30, 0x40000
	s_addc_u32 s31, s31, 0
	s_mov_b32 m0, s42
	ds_read_b128 v[154:157], v172 offset:32768
	ds_read_b128 v[158:161], v172 offset:33792
	ds_read_b128 v[162:165], v172 offset:34816
	ds_read_b128 v[166:169], v172 offset:35840
	ds_read_b128 v[174:177], v172 offset:36864
	ds_read_b128 v[178:181], v172 offset:37888
	ds_read_b128 v[182:185], v172 offset:38912
	ds_read_b128 v[186:189], v172 offset:39936
	global_load_lds_dwordx4 v48, s[30:31]
	v_lshl_add_u64 v[190:191], s[30:31], 0, v[146:147]
	s_mov_b32 m0, s43
	s_nop 0
	global_load_lds_dwordx4 v[190:191], off
	s_waitcnt lgkmcnt(8)
	s_barrier
	s_waitcnt lgkmcnt(0)
	s_setprio 1
	s_waitcnt lgkmcnt(0)
	v_mfma_f32_16x16x32_bf16 v[126:129], v[130:133], v[154:157], v[126:129]
	v_mfma_f32_16x16x32_bf16 v[122:125], v[138:141], v[154:157], v[122:125]
	v_mfma_f32_16x16x32_bf16 v[114:117], v[130:133], v[162:165], v[114:117]
	v_mfma_f32_16x16x32_bf16 v[106:109], v[138:141], v[162:165], v[106:109]
	v_mfma_f32_16x16x32_bf16 v[94:97], v[130:133], v[174:177], v[94:97]
	v_mfma_f32_16x16x32_bf16 v[90:93], v[138:141], v[174:177], v[90:93]
	v_mfma_f32_16x16x32_bf16 v[82:85], v[130:133], v[182:185], v[82:85]
	v_mfma_f32_16x16x32_bf16 v[74:77], v[138:141], v[182:185], v[74:77]
	v_mfma_f32_16x16x32_bf16 v[126:129], v[134:137], v[158:161], v[126:129]
	v_mfma_f32_16x16x32_bf16 v[122:125], v[142:145], v[158:161], v[122:125]
	v_mfma_f32_16x16x32_bf16 v[114:117], v[134:137], v[166:169], v[114:117]
	v_mfma_f32_16x16x32_bf16 v[106:109], v[142:145], v[166:169], v[106:109]
	v_mfma_f32_16x16x32_bf16 v[94:97], v[134:137], v[178:181], v[94:97]
	v_mfma_f32_16x16x32_bf16 v[90:93], v[142:145], v[178:181], v[90:93]
	v_mfma_f32_16x16x32_bf16 v[82:85], v[134:137], v[186:189], v[82:85]
	v_mfma_f32_16x16x32_bf16 v[74:77], v[142:145], v[186:189], v[74:77]
	s_setprio 0
	s_barrier
	s_add_i32 s30, 0, 0x1c000
	s_add_i32 s31, s49, s35
	s_add_u32 s52, s28, s66
	s_addc_u32 s53, s29, s67
	s_mov_b32 m0, s31
	ds_read_b128 v[190:193], v218 offset:49152
	ds_read_b128 v[198:201], v218 offset:50176
	ds_read_b128 v[202:205], v218 offset:51200
	ds_read_b128 v[206:209], v218 offset:52224
	global_load_lds_dwordx4 v48, s[52:53]
	v_lshl_add_u64 v[210:211], v[212:213], 0, s[66:67]
	s_add_i32 m0, s31, 0x2000
	s_nop 0
	global_load_lds_dwordx4 v[210:211], off
	s_barrier
	s_waitcnt lgkmcnt(0)
	s_setprio 1
	s_waitcnt lgkmcnt(0)
	v_mfma_f32_16x16x32_bf16 v[118:121], v[190:193], v[154:157], v[118:121]
	v_mfma_f32_16x16x32_bf16 v[110:113], v[202:205], v[154:157], v[110:113]
	v_mfma_f32_16x16x32_bf16 v[102:105], v[190:193], v[162:165], v[102:105]
	v_mfma_f32_16x16x32_bf16 v[98:101], v[202:205], v[162:165], v[98:101]
	v_mfma_f32_16x16x32_bf16 v[86:89], v[190:193], v[174:177], v[86:89]
	v_mfma_f32_16x16x32_bf16 v[78:81], v[202:205], v[174:177], v[78:81]
	v_mfma_f32_16x16x32_bf16 v[70:73], v[190:193], v[182:185], v[70:73]
	v_mfma_f32_16x16x32_bf16 v[66:69], v[202:205], v[182:185], v[66:69]
	v_mfma_f32_16x16x32_bf16 v[118:121], v[198:201], v[158:161], v[118:121]
	v_mfma_f32_16x16x32_bf16 v[110:113], v[206:209], v[158:161], v[110:113]
	v_mfma_f32_16x16x32_bf16 v[102:105], v[198:201], v[166:169], v[102:105]
	v_mfma_f32_16x16x32_bf16 v[98:101], v[206:209], v[166:169], v[98:101]
	v_mfma_f32_16x16x32_bf16 v[86:89], v[198:201], v[178:181], v[86:89]
	v_mfma_f32_16x16x32_bf16 v[78:81], v[206:209], v[178:181], v[78:81]
	v_mfma_f32_16x16x32_bf16 v[70:73], v[198:201], v[186:189], v[70:73]
	v_mfma_f32_16x16x32_bf16 v[66:69], v[206:209], v[186:189], v[66:69]
	s_setprio 0
	s_mov_b32 m0, s46
	v_lshl_add_u64 v[210:211], v[214:215], 0, s[66:67]
	s_barrier
	ds_read_b128 v[154:157], v172 offset:49152
	ds_read_b128 v[158:161], v172 offset:50176
	ds_read_b128 v[162:165], v172 offset:51200
	ds_read_b128 v[166:169], v172 offset:52224
	ds_read_b128 v[174:177], v172 offset:53248
	ds_read_b128 v[178:181], v172 offset:54272
	ds_read_b128 v[182:185], v172 offset:55296
	ds_read_b128 v[186:189], v172 offset:56320
	global_load_lds_dwordx4 v[210:211], off
	v_lshl_add_u64 v[210:211], v[216:217], 0, s[66:67]
	s_mov_b32 m0, s47
	s_nop 0
	global_load_lds_dwordx4 v[210:211], off
	s_barrier
	s_waitcnt lgkmcnt(0)
	s_setprio 1
	s_waitcnt lgkmcnt(0)
	v_mfma_f32_16x16x32_bf16 v[62:65], v[130:133], v[154:157], v[62:65]
	v_mfma_f32_16x16x32_bf16 v[58:61], v[138:141], v[154:157], v[58:61]
	v_mfma_f32_16x16x32_bf16 v[50:53], v[130:133], v[162:165], v[50:53]
	v_mfma_f32_16x16x32_bf16 v[40:43], v[138:141], v[162:165], v[40:43]
	v_mfma_f32_16x16x32_bf16 v[32:35], v[130:133], v[174:177], v[32:35]
	v_mfma_f32_16x16x32_bf16 v[24:27], v[138:141], v[174:177], v[24:27]
	v_mfma_f32_16x16x32_bf16 v[16:19], v[130:133], v[182:185], v[16:19]
	v_mfma_f32_16x16x32_bf16 v[8:11], v[138:141], v[182:185], v[8:11]
	v_mfma_f32_16x16x32_bf16 v[62:65], v[134:137], v[158:161], v[62:65]
	v_mfma_f32_16x16x32_bf16 v[58:61], v[142:145], v[158:161], v[58:61]
	v_mfma_f32_16x16x32_bf16 v[50:53], v[134:137], v[166:169], v[50:53]
	v_mfma_f32_16x16x32_bf16 v[40:43], v[142:145], v[166:169], v[40:43]
	v_mfma_f32_16x16x32_bf16 v[32:35], v[134:137], v[178:181], v[32:35]
	v_mfma_f32_16x16x32_bf16 v[24:27], v[142:145], v[178:181], v[24:27]
	v_mfma_f32_16x16x32_bf16 v[16:19], v[134:137], v[186:189], v[16:19]
	v_mfma_f32_16x16x32_bf16 v[8:11], v[142:145], v[186:189], v[8:11]
	s_setprio 0
	s_barrier
	s_add_u32 s28, s28, 0x40080
	s_addc_u32 s29, s29, 0
	s_add_i32 s30, s30, s35
	s_mov_b32 m0, s30
	s_nop 0
	global_load_lds_dwordx4 v48, s[28:29]
	v_lshl_add_u64 v[130:131], s[28:29], 0, v[146:147]
	s_add_i32 m0, s30, 0x2000
	s_nop 0
	global_load_lds_dwordx4 v[130:131], off
	s_waitcnt vmcnt(6)
	s_barrier
	s_setprio 1
	v_mfma_f32_16x16x32_bf16 v[54:57], v[190:193], v[154:157], v[54:57]
	v_mfma_f32_16x16x32_bf16 v[44:47], v[202:205], v[154:157], v[44:47]
	v_mfma_f32_16x16x32_bf16 v[36:39], v[190:193], v[162:165], v[36:39]
	v_mfma_f32_16x16x32_bf16 v[28:31], v[202:205], v[162:165], v[28:31]
	v_mfma_f32_16x16x32_bf16 v[20:23], v[190:193], v[174:177], v[20:23]
	v_mfma_f32_16x16x32_bf16 v[12:15], v[202:205], v[174:177], v[12:15]
	v_mfma_f32_16x16x32_bf16 v[4:7], v[190:193], v[182:185], v[4:7]
	v_mfma_f32_16x16x32_bf16 v[0:3], v[202:205], v[182:185], v[0:3]
	v_mfma_f32_16x16x32_bf16 v[54:57], v[198:201], v[158:161], v[54:57]
	v_mfma_f32_16x16x32_bf16 v[44:47], v[206:209], v[158:161], v[44:47]
	v_mfma_f32_16x16x32_bf16 v[36:39], v[198:201], v[166:169], v[36:39]
	v_mfma_f32_16x16x32_bf16 v[28:31], v[206:209], v[166:169], v[28:31]
	v_mfma_f32_16x16x32_bf16 v[20:23], v[198:201], v[178:181], v[20:23]
	v_mfma_f32_16x16x32_bf16 v[12:15], v[206:209], v[178:181], v[12:15]
	v_mfma_f32_16x16x32_bf16 v[4:7], v[198:201], v[186:189], v[4:7]
	v_mfma_f32_16x16x32_bf16 v[0:3], v[206:209], v[186:189], v[0:3]
	s_setprio 0
	s_add_i32 s25, s25, 2
	s_add_u32 s26, s26, 0x100
	s_addc_u32 s27, s27, 0
	s_add_u32 s15, s15, 0x100
	s_addc_u32 s17, s17, 0
	s_cmp_gt_u32 s25, 13
	s_barrier
	s_cbranch_scc0 .LBB0_1202
	s_mul_hi_i32 s15, s24, 0x38e38e39
	s_lshr_b32 s17, s15, 31
	s_ashr_i32 s15, s15, 1
	s_add_i32 s15, s15, s17
	s_mul_i32 s17, s15, -9
	s_sub_i32 s25, 0, s24
	s_cmp_eq_u32 s17, s25
	s_mov_b64 s[26:27], 0x30000
	s_cbranch_scc1 .LBB0_1198
	s_mul_hi_i32 s27, s15, 0x1800
	s_mul_i32 s26, s15, 0x1800
	s_branch .LBB0_1198

.LBB0_1219:
	ds_read_b128 v[130:133], v201
	ds_read_b128 v[134:137], v201 offset:1024
	ds_read_b128 v[138:141], v201 offset:2048
	ds_read_b128 v[142:145], v201 offset:3072
	s_add_u32 s26, s24, 0xfffc0080
	s_addc_u32 s27, s25, -1
	s_add_i32 s31, 0, 0x10000
	s_cmp_eq_u32 s30, 12
	s_cselect_b32 s29, s19, s27
	s_cselect_b32 s28, s18, s26
	s_cselect_b32 s27, s21, s17
	s_cselect_b32 s26, s20, s15
	s_add_i32 m0, s41, 0xc000
	ds_read_b128 v[146:149], v210
	ds_read_b128 v[150:153], v210 offset:1024
	ds_read_b128 v[154:157], v210 offset:2048
	ds_read_b128 v[158:161], v210 offset:3072
	ds_read_b128 v[162:165], v210 offset:4096
	ds_read_b128 v[166:169], v210 offset:5120
	ds_read_b128 v[170:173], v210 offset:6144
	ds_read_b128 v[174:177], v210 offset:7168
	global_load_lds_dwordx4 v200, s[24:25]
	s_add_i32 m0, s41, 0xe000
	s_nop 0
	global_load_lds_dwordx4 v202, s[24:25]
	s_waitcnt lgkmcnt(8)
	s_barrier
	s_waitcnt lgkmcnt(0)
	s_setprio 1
	s_waitcnt lgkmcnt(0)
	v_mfma_f32_16x16x32_bf16 v[126:129], v[130:133], v[146:149], v[126:129]
	v_mfma_f32_16x16x32_bf16 v[122:125], v[138:141], v[146:149], v[122:125]
	v_mfma_f32_16x16x32_bf16 v[118:121], v[130:133], v[154:157], v[118:121]
	v_mfma_f32_16x16x32_bf16 v[106:109], v[138:141], v[154:157], v[106:109]
	v_mfma_f32_16x16x32_bf16 v[94:97], v[130:133], v[162:165], v[94:97]
	v_mfma_f32_16x16x32_bf16 v[90:93], v[138:141], v[162:165], v[90:93]
	v_mfma_f32_16x16x32_bf16 v[86:89], v[130:133], v[170:173], v[86:89]
	v_mfma_f32_16x16x32_bf16 v[74:77], v[138:141], v[170:173], v[74:77]
	v_mfma_f32_16x16x32_bf16 v[126:129], v[134:137], v[150:153], v[126:129]
	v_mfma_f32_16x16x32_bf16 v[122:125], v[142:145], v[150:153], v[122:125]
	v_mfma_f32_16x16x32_bf16 v[118:121], v[134:137], v[158:161], v[118:121]
	v_mfma_f32_16x16x32_bf16 v[106:109], v[142:145], v[158:161], v[106:109]
	v_mfma_f32_16x16x32_bf16 v[94:97], v[134:137], v[166:169], v[94:97]
	v_mfma_f32_16x16x32_bf16 v[90:93], v[142:145], v[166:169], v[90:93]
	v_mfma_f32_16x16x32_bf16 v[86:89], v[134:137], v[174:177], v[86:89]
	v_mfma_f32_16x16x32_bf16 v[74:77], v[142:145], v[174:177], v[74:77]
	s_setprio 0
	s_barrier
	s_add_i32 s50, 0, 0x14000
	s_add_i32 s31, s31, s40
	s_mov_b32 m0, s31
	ds_read_b128 v[178:181], v201 offset:16384
	ds_read_b128 v[182:185], v201 offset:17408
	ds_read_b128 v[186:189], v201 offset:18432
	ds_read_b128 v[204:207], v201 offset:19456
	global_load_lds_dwordx4 v48, s[26:27]
	s_add_i32 m0, s31, 0x2000
	s_nop 0
	global_load_lds_dwordx4 v190, s[26:27]
	s_barrier
	s_waitcnt lgkmcnt(0)
	s_setprio 1
	s_waitcnt lgkmcnt(0)
	v_mfma_f32_16x16x32_bf16 v[114:117], v[178:181], v[146:149], v[114:117]
	v_mfma_f32_16x16x32_bf16 v[110:113], v[186:189], v[146:149], v[110:113]
	v_mfma_f32_16x16x32_bf16 v[102:105], v[178:181], v[154:157], v[102:105]
	v_mfma_f32_16x16x32_bf16 v[98:101], v[186:189], v[154:157], v[98:101]
	v_mfma_f32_16x16x32_bf16 v[82:85], v[178:181], v[162:165], v[82:85]
	v_mfma_f32_16x16x32_bf16 v[78:81], v[186:189], v[162:165], v[78:81]
	v_mfma_f32_16x16x32_bf16 v[70:73], v[178:181], v[170:173], v[70:73]
	v_mfma_f32_16x16x32_bf16 v[66:69], v[186:189], v[170:173], v[66:69]
	v_mfma_f32_16x16x32_bf16 v[114:117], v[182:185], v[150:153], v[114:117]
	v_mfma_f32_16x16x32_bf16 v[110:113], v[204:207], v[150:153], v[110:113]
	v_mfma_f32_16x16x32_bf16 v[102:105], v[182:185], v[158:161], v[102:105]
	v_mfma_f32_16x16x32_bf16 v[98:101], v[204:207], v[158:161], v[98:101]
	v_mfma_f32_16x16x32_bf16 v[82:85], v[182:185], v[166:169], v[82:85]
	v_mfma_f32_16x16x32_bf16 v[78:81], v[204:207], v[166:169], v[78:81]
	v_mfma_f32_16x16x32_bf16 v[70:73], v[182:185], v[174:177], v[70:73]
	v_mfma_f32_16x16x32_bf16 v[66:69], v[204:207], v[174:177], v[66:69]
	s_setprio 0
	s_mov_b32 m0, s41
	v_lshl_add_u64 v[216:217], s[28:29], 0, v[48:49]
	s_barrier
	ds_read_b128 v[146:149], v210 offset:16384
	ds_read_b128 v[150:153], v210 offset:17408
	ds_read_b128 v[154:157], v210 offset:18432
	ds_read_b128 v[158:161], v210 offset:19456
	ds_read_b128 v[162:165], v210 offset:20480
	ds_read_b128 v[166:169], v210 offset:21504
	ds_read_b128 v[170:173], v210 offset:22528
	ds_read_b128 v[174:177], v210 offset:23552
	global_load_lds_dwordx4 v[216:217], off
	v_lshl_add_u64 v[218:219], s[28:29], 0, v[190:191]
	s_mov_b32 m0, s42
	s_nop 0
	global_load_lds_dwordx4 v[218:219], off
	s_barrier
	s_waitcnt lgkmcnt(0)
	s_setprio 1
	s_waitcnt lgkmcnt(0)
	v_mfma_f32_16x16x32_bf16 v[62:65], v[130:133], v[146:149], v[62:65]
	v_mfma_f32_16x16x32_bf16 v[58:61], v[138:141], v[146:149], v[58:61]
	v_mfma_f32_16x16x32_bf16 v[54:57], v[130:133], v[154:157], v[54:57]
	v_mfma_f32_16x16x32_bf16 v[40:43], v[138:141], v[154:157], v[40:43]
	v_mfma_f32_16x16x32_bf16 v[36:39], v[130:133], v[162:165], v[36:39]
	v_mfma_f32_16x16x32_bf16 v[24:27], v[138:141], v[162:165], v[24:27]
	v_mfma_f32_16x16x32_bf16 v[20:23], v[130:133], v[170:173], v[20:23]
	v_mfma_f32_16x16x32_bf16 v[8:11], v[138:141], v[170:173], v[8:11]
	v_mfma_f32_16x16x32_bf16 v[62:65], v[134:137], v[150:153], v[62:65]
	v_mfma_f32_16x16x32_bf16 v[58:61], v[142:145], v[150:153], v[58:61]
	v_mfma_f32_16x16x32_bf16 v[54:57], v[134:137], v[158:161], v[54:57]
	v_mfma_f32_16x16x32_bf16 v[40:43], v[142:145], v[158:161], v[40:43]
	v_mfma_f32_16x16x32_bf16 v[36:39], v[134:137], v[166:169], v[36:39]
	v_mfma_f32_16x16x32_bf16 v[24:27], v[142:145], v[166:169], v[24:27]
	v_mfma_f32_16x16x32_bf16 v[20:23], v[134:137], v[174:177], v[20:23]
	v_mfma_f32_16x16x32_bf16 v[8:11], v[142:145], v[174:177], v[8:11]
	s_setprio 0
	s_barrier
	s_add_u32 s34, s26, 0x40000
	s_addc_u32 s35, s27, 0
	s_add_i32 s31, s50, s40
	s_mov_b32 m0, s31
	s_nop 0
	global_load_lds_dwordx4 v48, s[34:35]
	s_add_i32 m0, s31, 0x2000
	s_nop 0
	global_load_lds_dwordx4 v190, s[34:35]
	s_waitcnt vmcnt(6)
	s_barrier
	s_setprio 1
	v_mfma_f32_16x16x32_bf16 v[50:53], v[178:181], v[146:149], v[50:53]
	v_mfma_f32_16x16x32_bf16 v[44:47], v[186:189], v[146:149], v[44:47]
	v_mfma_f32_16x16x32_bf16 v[32:35], v[178:181], v[154:157], v[32:35]
	v_mfma_f32_16x16x32_bf16 v[28:31], v[186:189], v[154:157], v[28:31]
	v_mfma_f32_16x16x32_bf16 v[16:19], v[178:181], v[162:165], v[16:19]
	v_mfma_f32_16x16x32_bf16 v[12:15], v[186:189], v[162:165], v[12:15]
	v_mfma_f32_16x16x32_bf16 v[4:7], v[178:181], v[170:173], v[4:7]
	v_mfma_f32_16x16x32_bf16 v[0:3], v[186:189], v[170:173], v[0:3]
	v_mfma_f32_16x16x32_bf16 v[50:53], v[182:185], v[150:153], v[50:53]
	v_mfma_f32_16x16x32_bf16 v[44:47], v[204:207], v[150:153], v[44:47]
	v_mfma_f32_16x16x32_bf16 v[32:35], v[182:185], v[158:161], v[32:35]
	v_mfma_f32_16x16x32_bf16 v[28:31], v[204:207], v[158:161], v[28:31]
	v_mfma_f32_16x16x32_bf16 v[16:19], v[182:185], v[166:169], v[16:19]
	v_mfma_f32_16x16x32_bf16 v[12:15], v[204:207], v[166:169], v[12:15]
	v_mfma_f32_16x16x32_bf16 v[4:7], v[182:185], v[174:177], v[4:7]
	v_mfma_f32_16x16x32_bf16 v[0:3], v[204:207], v[174:177], v[0:3]
	s_setprio 0
	s_add_i32 s31, 0, 0x18000
	s_barrier
	ds_read_b128 v[130:133], v201 offset:32768
	ds_read_b128 v[134:137], v201 offset:33792
	ds_read_b128 v[138:141], v201 offset:34816
	ds_read_b128 v[142:145], v201 offset:35840
	s_add_u32 s28, s28, 0x40000
	s_addc_u32 s29, s29, 0
	s_mov_b32 m0, s43
	ds_read_b128 v[146:149], v210 offset:32768
	ds_read_b128 v[150:153], v210 offset:33792
	ds_read_b128 v[154:157], v210 offset:34816
	ds_read_b128 v[158:161], v210 offset:35840
	ds_read_b128 v[162:165], v210 offset:36864
	ds_read_b128 v[166:169], v210 offset:37888
	ds_read_b128 v[170:173], v210 offset:38912
	ds_read_b128 v[174:177], v210 offset:39936
	global_load_lds_dwordx4 v48, s[28:29]
	s_mov_b32 m0, s44
	s_nop 0
	global_load_lds_dwordx4 v190, s[28:29]
	s_waitcnt lgkmcnt(8)
	s_barrier
	s_waitcnt lgkmcnt(0)
	s_setprio 1
	s_waitcnt lgkmcnt(0)
	v_mfma_f32_16x16x32_bf16 v[126:129], v[130:133], v[146:149], v[126:129]
	v_mfma_f32_16x16x32_bf16 v[122:125], v[138:141], v[146:149], v[122:125]
	v_mfma_f32_16x16x32_bf16 v[118:121], v[130:133], v[154:157], v[118:121]
	v_mfma_f32_16x16x32_bf16 v[106:109], v[138:141], v[154:157], v[106:109]
	v_mfma_f32_16x16x32_bf16 v[94:97], v[130:133], v[162:165], v[94:97]
	v_mfma_f32_16x16x32_bf16 v[90:93], v[138:141], v[162:165], v[90:93]
	v_mfma_f32_16x16x32_bf16 v[86:89], v[130:133], v[170:173], v[86:89]
	v_mfma_f32_16x16x32_bf16 v[74:77], v[138:141], v[170:173], v[74:77]
	v_mfma_f32_16x16x32_bf16 v[126:129], v[134:137], v[150:153], v[126:129]
	v_mfma_f32_16x16x32_bf16 v[122:125], v[142:145], v[150:153], v[122:125]
	v_mfma_f32_16x16x32_bf16 v[118:121], v[134:137], v[158:161], v[118:121]
	v_mfma_f32_16x16x32_bf16 v[106:109], v[142:145], v[158:161], v[106:109]
	v_mfma_f32_16x16x32_bf16 v[94:97], v[134:137], v[166:169], v[94:97]
	v_mfma_f32_16x16x32_bf16 v[90:93], v[142:145], v[166:169], v[90:93]
	v_mfma_f32_16x16x32_bf16 v[86:89], v[134:137], v[174:177], v[86:89]
	v_mfma_f32_16x16x32_bf16 v[74:77], v[142:145], v[174:177], v[74:77]
	s_setprio 0
	s_barrier
	s_add_i32 s28, 0, 0x1c000
	s_add_i32 s29, s31, s40
	s_add_u32 s52, s26, s66
	s_addc_u32 s53, s27, s67
	s_mov_b32 m0, s29
	ds_read_b128 v[178:181], v201 offset:49152
	ds_read_b128 v[182:185], v201 offset:50176
	ds_read_b128 v[186:189], v201 offset:51200
	ds_read_b128 v[204:207], v201 offset:52224
	global_load_lds_dwordx4 v48, s[52:53]
	s_add_i32 m0, s29, 0x2000
	s_nop 0
	global_load_lds_dwordx4 v190, s[52:53]
	s_barrier
	s_waitcnt lgkmcnt(0)
	s_setprio 1
	s_waitcnt lgkmcnt(0)
	v_mfma_f32_16x16x32_bf16 v[114:117], v[178:181], v[146:149], v[114:117]
	v_mfma_f32_16x16x32_bf16 v[110:113], v[186:189], v[146:149], v[110:113]
	v_mfma_f32_16x16x32_bf16 v[102:105], v[178:181], v[154:157], v[102:105]
	v_mfma_f32_16x16x32_bf16 v[98:101], v[186:189], v[154:157], v[98:101]
	v_mfma_f32_16x16x32_bf16 v[82:85], v[178:181], v[162:165], v[82:85]
	v_mfma_f32_16x16x32_bf16 v[78:81], v[186:189], v[162:165], v[78:81]
	v_mfma_f32_16x16x32_bf16 v[70:73], v[178:181], v[170:173], v[70:73]
	v_mfma_f32_16x16x32_bf16 v[66:69], v[186:189], v[170:173], v[66:69]
	v_mfma_f32_16x16x32_bf16 v[114:117], v[182:185], v[150:153], v[114:117]
	v_mfma_f32_16x16x32_bf16 v[110:113], v[204:207], v[150:153], v[110:113]
	v_mfma_f32_16x16x32_bf16 v[102:105], v[182:185], v[158:161], v[102:105]
	v_mfma_f32_16x16x32_bf16 v[98:101], v[204:207], v[158:161], v[98:101]
	v_mfma_f32_16x16x32_bf16 v[82:85], v[182:185], v[166:169], v[82:85]
	v_mfma_f32_16x16x32_bf16 v[78:81], v[204:207], v[166:169], v[78:81]
	v_mfma_f32_16x16x32_bf16 v[70:73], v[182:185], v[174:177], v[70:73]
	v_mfma_f32_16x16x32_bf16 v[66:69], v[204:207], v[174:177], v[66:69]
	s_setprio 0
	s_mov_b32 m0, s47
	v_lshl_add_u64 v[212:213], v[216:217], 0, s[66:67]
	s_barrier
	ds_read_b128 v[146:149], v210 offset:49152
	ds_read_b128 v[150:153], v210 offset:50176
	ds_read_b128 v[154:157], v210 offset:51200
	ds_read_b128 v[158:161], v210 offset:52224
	ds_read_b128 v[162:165], v210 offset:53248
	ds_read_b128 v[166:169], v210 offset:54272
	ds_read_b128 v[170:173], v210 offset:55296
	ds_read_b128 v[174:177], v210 offset:56320
	global_load_lds_dwordx4 v[212:213], off
	v_lshl_add_u64 v[212:213], v[218:219], 0, s[66:67]
	s_mov_b32 m0, s48
	s_nop 0
	global_load_lds_dwordx4 v[212:213], off
	s_barrier
	s_waitcnt lgkmcnt(0)
	s_setprio 1
	s_waitcnt lgkmcnt(0)
	v_mfma_f32_16x16x32_bf16 v[62:65], v[130:133], v[146:149], v[62:65]
	v_mfma_f32_16x16x32_bf16 v[58:61], v[138:141], v[146:149], v[58:61]
	v_mfma_f32_16x16x32_bf16 v[54:57], v[130:133], v[154:157], v[54:57]
	v_mfma_f32_16x16x32_bf16 v[40:43], v[138:141], v[154:157], v[40:43]
	v_mfma_f32_16x16x32_bf16 v[36:39], v[130:133], v[162:165], v[36:39]
	v_mfma_f32_16x16x32_bf16 v[24:27], v[138:141], v[162:165], v[24:27]
	v_mfma_f32_16x16x32_bf16 v[20:23], v[130:133], v[170:173], v[20:23]
	v_mfma_f32_16x16x32_bf16 v[8:11], v[138:141], v[170:173], v[8:11]
	v_mfma_f32_16x16x32_bf16 v[62:65], v[134:137], v[150:153], v[62:65]
	v_mfma_f32_16x16x32_bf16 v[58:61], v[142:145], v[150:153], v[58:61]
	v_mfma_f32_16x16x32_bf16 v[54:57], v[134:137], v[158:161], v[54:57]
	v_mfma_f32_16x16x32_bf16 v[40:43], v[142:145], v[158:161], v[40:43]
	v_mfma_f32_16x16x32_bf16 v[36:39], v[134:137], v[166:169], v[36:39]
	v_mfma_f32_16x16x32_bf16 v[24:27], v[142:145], v[166:169], v[24:27]
	v_mfma_f32_16x16x32_bf16 v[20:23], v[134:137], v[174:177], v[20:23]
	v_mfma_f32_16x16x32_bf16 v[8:11], v[142:145], v[174:177], v[8:11]
	s_setprio 0
	s_barrier
	s_add_u32 s26, s26, 0x40080
	s_addc_u32 s27, s27, 0
	s_add_i32 s28, s28, s40
	s_mov_b32 m0, s28
	s_nop 0
	global_load_lds_dwordx4 v48, s[26:27]
	s_add_i32 m0, s28, 0x2000
	s_nop 0
	global_load_lds_dwordx4 v190, s[26:27]
	s_waitcnt vmcnt(6)
	s_barrier
	s_setprio 1
	v_mfma_f32_16x16x32_bf16 v[50:53], v[178:181], v[146:149], v[50:53]
	v_mfma_f32_16x16x32_bf16 v[44:47], v[186:189], v[146:149], v[44:47]
	v_mfma_f32_16x16x32_bf16 v[32:35], v[178:181], v[154:157], v[32:35]
	v_mfma_f32_16x16x32_bf16 v[28:31], v[186:189], v[154:157], v[28:31]
	v_mfma_f32_16x16x32_bf16 v[16:19], v[178:181], v[162:165], v[16:19]
	v_mfma_f32_16x16x32_bf16 v[12:15], v[186:189], v[162:165], v[12:15]
	v_mfma_f32_16x16x32_bf16 v[4:7], v[178:181], v[170:173], v[4:7]
	v_mfma_f32_16x16x32_bf16 v[0:3], v[186:189], v[170:173], v[0:3]
	v_mfma_f32_16x16x32_bf16 v[50:53], v[182:185], v[150:153], v[50:53]
	v_mfma_f32_16x16x32_bf16 v[44:47], v[204:207], v[150:153], v[44:47]
	v_mfma_f32_16x16x32_bf16 v[32:35], v[182:185], v[158:161], v[32:35]
	v_mfma_f32_16x16x32_bf16 v[28:31], v[204:207], v[158:161], v[28:31]
	v_mfma_f32_16x16x32_bf16 v[16:19], v[182:185], v[166:169], v[16:19]
	v_mfma_f32_16x16x32_bf16 v[12:15], v[204:207], v[166:169], v[12:15]
	v_mfma_f32_16x16x32_bf16 v[4:7], v[182:185], v[174:177], v[4:7]
	v_mfma_f32_16x16x32_bf16 v[0:3], v[204:207], v[174:177], v[0:3]
	s_setprio 0
	s_add_i32 s30, s30, 2
	s_add_u32 s24, s24, 0x100
	s_addc_u32 s25, s25, 0
	s_add_u32 s15, s15, 0x100
	s_addc_u32 s17, s17, 0
	s_cmp_gt_u32 s30, 13
	s_barrier
	s_cbranch_scc0 .LBB0_1219
	s_mul_hi_i32 s15, s22, 0x38e38e39
	s_lshr_b32 s17, s15, 31
	s_ashr_i32 s15, s15, 1
	s_add_i32 s24, s15, s17
	s_mul_i32 s15, s24, -9
	s_add_i32 s28, s15, s22
	s_cmp_eq_u32 s28, 0
	s_cselect_b64 s[26:27], -1, 0
	s_ashr_i32 s25, s24, 31
	s_cmp_lg_u32 s28, 0
	s_cbranch_scc0 .LBB0_1222
	s_ashr_i32 s29, s28, 31
	s_lshl_b64 s[28:29], s[28:29], 18
	s_lshl_b64 s[30:31], s[24:25], 21
	s_add_u32 s15, s28, s30
	s_addc_u32 s17, s29, s31
	s_add_u32 s28, s15, 0xfffc0000
	s_addc_u32 s29, s17, -1
	s_mov_b64 s[30:31], s[6:7]
	s_cbranch_execnz .LBB0_1215
	s_branch .LBB0_1214

.LBB0_1356:
	ds_read_b128 v[146:149], v137
	ds_read_b128 v[150:153], v137 offset:1024
	ds_read_b128 v[154:157], v137 offset:2048
	ds_read_b128 v[158:161], v137 offset:3072
	s_add_u32 s28, s26, 0xfffc0080
	s_addc_u32 s29, s27, -1
	s_add_i32 s46, 0, 0x10000
	s_cmp_eq_u32 s45, 12
	s_cselect_b32 s31, s19, s29
	s_cselect_b32 s30, s18, s28
	s_cselect_b32 s29, s21, s17
	s_cselect_b32 s28, s20, s15
	s_add_i32 m0, s23, 0xc000
	ds_read_b128 v[162:165], v145
	ds_read_b128 v[166:169], v145 offset:1024
	ds_read_b128 v[170:173], v145 offset:2048
	ds_read_b128 v[174:177], v145 offset:3072
	ds_read_b128 v[178:181], v145 offset:4096
	ds_read_b128 v[182:185], v145 offset:5120
	ds_read_b128 v[186:189], v145 offset:6144
	ds_read_b128 v[190:193], v145 offset:7168
	global_load_lds_dwordx4 v136, s[26:27]
	s_add_i32 m0, s23, 0xe000
	s_nop 0
	global_load_lds_dwordx4 v138, s[26:27]
	s_waitcnt lgkmcnt(8)
	s_barrier
	s_waitcnt lgkmcnt(0)
	s_setprio 1
	s_waitcnt lgkmcnt(0)
	v_mfma_f32_16x16x32_bf16 v[126:129], v[146:149], v[162:165], v[126:129]
	v_mfma_f32_16x16x32_bf16 v[118:121], v[154:157], v[162:165], v[118:121]
	v_mfma_f32_16x16x32_bf16 v[110:113], v[146:149], v[170:173], v[110:113]
	v_mfma_f32_16x16x32_bf16 v[102:105], v[154:157], v[170:173], v[102:105]
	v_mfma_f32_16x16x32_bf16 v[94:97], v[146:149], v[178:181], v[94:97]
	v_mfma_f32_16x16x32_bf16 v[86:89], v[154:157], v[178:181], v[86:89]
	v_mfma_f32_16x16x32_bf16 v[78:81], v[146:149], v[186:189], v[78:81]
	v_mfma_f32_16x16x32_bf16 v[70:73], v[154:157], v[186:189], v[70:73]
	v_mfma_f32_16x16x32_bf16 v[126:129], v[150:153], v[166:169], v[126:129]
	v_mfma_f32_16x16x32_bf16 v[118:121], v[158:161], v[166:169], v[118:121]
	v_mfma_f32_16x16x32_bf16 v[110:113], v[150:153], v[174:177], v[110:113]
	v_mfma_f32_16x16x32_bf16 v[102:105], v[158:161], v[174:177], v[102:105]
	v_mfma_f32_16x16x32_bf16 v[94:97], v[150:153], v[182:185], v[94:97]
	v_mfma_f32_16x16x32_bf16 v[86:89], v[158:161], v[182:185], v[86:89]
	v_mfma_f32_16x16x32_bf16 v[78:81], v[150:153], v[190:193], v[78:81]
	v_mfma_f32_16x16x32_bf16 v[70:73], v[158:161], v[190:193], v[70:73]
	s_setprio 0
	s_barrier
	ds_read_b128 v[198:201], v137 offset:16384
	ds_read_b128 v[202:205], v137 offset:17408
	ds_read_b128 v[206:209], v137 offset:18432
	ds_read_b128 v[210:213], v137 offset:19456
	s_add_i32 s48, 0, 0x14000
	s_add_i32 s46, s46, s37
	s_mov_b32 m0, s46
	global_load_lds_dwordx4 v48, s[28:29]
	s_add_i32 m0, s46, 0x2000
	s_nop 0
	global_load_lds_dwordx4 v130, s[28:29]
	s_barrier
	s_waitcnt lgkmcnt(0)
	s_setprio 1
	s_waitcnt lgkmcnt(0)
	v_mfma_f32_16x16x32_bf16 v[122:125], v[198:201], v[162:165], v[122:125]
	v_mfma_f32_16x16x32_bf16 v[114:117], v[206:209], v[162:165], v[114:117]
	v_mfma_f32_16x16x32_bf16 v[106:109], v[198:201], v[170:173], v[106:109]
	v_mfma_f32_16x16x32_bf16 v[98:101], v[206:209], v[170:173], v[98:101]
	v_mfma_f32_16x16x32_bf16 v[90:93], v[198:201], v[178:181], v[90:93]
	v_mfma_f32_16x16x32_bf16 v[82:85], v[206:209], v[178:181], v[82:85]
	v_mfma_f32_16x16x32_bf16 v[74:77], v[198:201], v[186:189], v[74:77]
	v_mfma_f32_16x16x32_bf16 v[66:69], v[206:209], v[186:189], v[66:69]
	v_mfma_f32_16x16x32_bf16 v[122:125], v[202:205], v[166:169], v[122:125]
	v_mfma_f32_16x16x32_bf16 v[114:117], v[210:213], v[166:169], v[114:117]
	v_mfma_f32_16x16x32_bf16 v[106:109], v[202:205], v[174:177], v[106:109]
	v_mfma_f32_16x16x32_bf16 v[98:101], v[210:213], v[174:177], v[98:101]
	v_mfma_f32_16x16x32_bf16 v[90:93], v[202:205], v[182:185], v[90:93]
	v_mfma_f32_16x16x32_bf16 v[82:85], v[210:213], v[182:185], v[82:85]
	v_mfma_f32_16x16x32_bf16 v[74:77], v[202:205], v[190:193], v[74:77]
	v_mfma_f32_16x16x32_bf16 v[66:69], v[210:213], v[190:193], v[66:69]
	s_setprio 0
	s_mov_b32 m0, s23
	v_lshl_add_u64 v[216:217], s[30:31], 0, v[134:135]
	s_barrier
	ds_read_b128 v[162:165], v145 offset:16384
	ds_read_b128 v[166:169], v145 offset:17408
	ds_read_b128 v[170:173], v145 offset:18432
	ds_read_b128 v[174:177], v145 offset:19456
	ds_read_b128 v[178:181], v145 offset:20480
	ds_read_b128 v[182:185], v145 offset:21504
	ds_read_b128 v[186:189], v145 offset:22528
	ds_read_b128 v[190:193], v145 offset:23552
	global_load_lds_dwordx4 v[216:217], off
	v_lshl_add_u64 v[218:219], s[30:31], 0, v[132:133]
	s_mov_b32 m0, s25
	s_nop 0
	global_load_lds_dwordx4 v[218:219], off
	s_barrier
	s_waitcnt lgkmcnt(0)
	s_setprio 1
	s_waitcnt lgkmcnt(0)
	v_mfma_f32_16x16x32_bf16 v[62:65], v[146:149], v[162:165], v[62:65]
	v_mfma_f32_16x16x32_bf16 v[54:57], v[154:157], v[162:165], v[54:57]
	v_mfma_f32_16x16x32_bf16 v[44:47], v[146:149], v[170:173], v[44:47]
	v_mfma_f32_16x16x32_bf16 v[36:39], v[154:157], v[170:173], v[36:39]
	v_mfma_f32_16x16x32_bf16 v[28:31], v[146:149], v[178:181], v[28:31]
	v_mfma_f32_16x16x32_bf16 v[20:23], v[154:157], v[178:181], v[20:23]
	v_mfma_f32_16x16x32_bf16 v[12:15], v[146:149], v[186:189], v[12:15]
	v_mfma_f32_16x16x32_bf16 v[4:7], v[154:157], v[186:189], v[4:7]
	v_mfma_f32_16x16x32_bf16 v[62:65], v[150:153], v[166:169], v[62:65]
	v_mfma_f32_16x16x32_bf16 v[54:57], v[158:161], v[166:169], v[54:57]
	v_mfma_f32_16x16x32_bf16 v[44:47], v[150:153], v[174:177], v[44:47]
	v_mfma_f32_16x16x32_bf16 v[36:39], v[158:161], v[174:177], v[36:39]
	v_mfma_f32_16x16x32_bf16 v[28:31], v[150:153], v[182:185], v[28:31]
	v_mfma_f32_16x16x32_bf16 v[20:23], v[158:161], v[182:185], v[20:23]
	v_mfma_f32_16x16x32_bf16 v[12:15], v[150:153], v[190:193], v[12:15]
	v_mfma_f32_16x16x32_bf16 v[4:7], v[158:161], v[190:193], v[4:7]
	s_setprio 0
	s_barrier
	s_add_u32 s46, s28, 0x40000
	s_addc_u32 s47, s29, 0
	s_add_i32 s48, s48, s37
	s_mov_b32 m0, s48
	s_nop 0
	global_load_lds_dwordx4 v48, s[46:47]
	s_add_i32 m0, s48, 0x2000
	s_nop 0
	global_load_lds_dwordx4 v130, s[46:47]
	s_waitcnt vmcnt(6)
	s_barrier
	s_setprio 1
	v_mfma_f32_16x16x32_bf16 v[58:61], v[198:201], v[162:165], v[58:61]
	v_mfma_f32_16x16x32_bf16 v[50:53], v[206:209], v[162:165], v[50:53]
	v_mfma_f32_16x16x32_bf16 v[40:43], v[198:201], v[170:173], v[40:43]
	v_mfma_f32_16x16x32_bf16 v[32:35], v[206:209], v[170:173], v[32:35]
	v_mfma_f32_16x16x32_bf16 v[24:27], v[198:201], v[178:181], v[24:27]
	v_mfma_f32_16x16x32_bf16 v[16:19], v[206:209], v[178:181], v[16:19]
	v_mfma_f32_16x16x32_bf16 v[8:11], v[198:201], v[186:189], v[8:11]
	v_mfma_f32_16x16x32_bf16 v[0:3], v[206:209], v[186:189], v[0:3]
	v_mfma_f32_16x16x32_bf16 v[58:61], v[202:205], v[166:169], v[58:61]
	v_mfma_f32_16x16x32_bf16 v[50:53], v[210:213], v[166:169], v[50:53]
	v_mfma_f32_16x16x32_bf16 v[40:43], v[202:205], v[174:177], v[40:43]
	v_mfma_f32_16x16x32_bf16 v[32:35], v[210:213], v[174:177], v[32:35]
	v_mfma_f32_16x16x32_bf16 v[24:27], v[202:205], v[182:185], v[24:27]
	v_mfma_f32_16x16x32_bf16 v[16:19], v[210:213], v[182:185], v[16:19]
	v_mfma_f32_16x16x32_bf16 v[8:11], v[202:205], v[190:193], v[8:11]
	v_mfma_f32_16x16x32_bf16 v[0:3], v[210:213], v[190:193], v[0:3]
	s_setprio 0
	s_add_i32 s46, 0, 0x18000
	s_barrier
	ds_read_b128 v[146:149], v137 offset:32768
	ds_read_b128 v[150:153], v137 offset:33792
	ds_read_b128 v[154:157], v137 offset:34816
	ds_read_b128 v[158:161], v137 offset:35840
	s_add_u32 s30, s30, 0x40000
	s_addc_u32 s31, s31, 0
	s_mov_b32 m0, s40
	ds_read_b128 v[162:165], v145 offset:32768
	ds_read_b128 v[166:169], v145 offset:33792
	ds_read_b128 v[170:173], v145 offset:34816
	ds_read_b128 v[174:177], v145 offset:35840
	ds_read_b128 v[178:181], v145 offset:36864
	ds_read_b128 v[182:185], v145 offset:37888
	ds_read_b128 v[186:189], v145 offset:38912
	ds_read_b128 v[190:193], v145 offset:39936
	global_load_lds_dwordx4 v134, s[30:31]
	s_mov_b32 m0, s41
	s_nop 0
	global_load_lds_dwordx4 v132, s[30:31]
	s_waitcnt lgkmcnt(8)
	s_barrier
	s_waitcnt lgkmcnt(0)
	s_setprio 1
	s_waitcnt lgkmcnt(0)
	v_mfma_f32_16x16x32_bf16 v[126:129], v[146:149], v[162:165], v[126:129]
	v_mfma_f32_16x16x32_bf16 v[118:121], v[154:157], v[162:165], v[118:121]
	v_mfma_f32_16x16x32_bf16 v[110:113], v[146:149], v[170:173], v[110:113]
	v_mfma_f32_16x16x32_bf16 v[102:105], v[154:157], v[170:173], v[102:105]
	v_mfma_f32_16x16x32_bf16 v[94:97], v[146:149], v[178:181], v[94:97]
	v_mfma_f32_16x16x32_bf16 v[86:89], v[154:157], v[178:181], v[86:89]
	v_mfma_f32_16x16x32_bf16 v[78:81], v[146:149], v[186:189], v[78:81]
	v_mfma_f32_16x16x32_bf16 v[70:73], v[154:157], v[186:189], v[70:73]
	v_mfma_f32_16x16x32_bf16 v[126:129], v[150:153], v[166:169], v[126:129]
	v_mfma_f32_16x16x32_bf16 v[118:121], v[158:161], v[166:169], v[118:121]
	v_mfma_f32_16x16x32_bf16 v[110:113], v[150:153], v[174:177], v[110:113]
	v_mfma_f32_16x16x32_bf16 v[102:105], v[158:161], v[174:177], v[102:105]
	v_mfma_f32_16x16x32_bf16 v[94:97], v[150:153], v[182:185], v[94:97]
	v_mfma_f32_16x16x32_bf16 v[86:89], v[158:161], v[182:185], v[86:89]
	v_mfma_f32_16x16x32_bf16 v[78:81], v[150:153], v[190:193], v[78:81]
	v_mfma_f32_16x16x32_bf16 v[70:73], v[158:161], v[190:193], v[70:73]
	s_setprio 0
	s_barrier
	s_add_i32 s30, 0, 0x1c000
	s_add_i32 s31, s46, s37
	s_add_u32 s46, s28, s66
	s_addc_u32 s47, s29, s67
	s_mov_b32 m0, s31
	ds_read_b128 v[198:201], v137 offset:49152
	ds_read_b128 v[202:205], v137 offset:50176
	ds_read_b128 v[206:209], v137 offset:51200
	ds_read_b128 v[210:213], v137 offset:52224
	global_load_lds_dwordx4 v48, s[46:47]
	s_add_i32 m0, s31, 0x2000
	s_nop 0
	global_load_lds_dwordx4 v130, s[46:47]
	s_barrier
	s_waitcnt lgkmcnt(0)
	s_setprio 1
	s_waitcnt lgkmcnt(0)
	v_mfma_f32_16x16x32_bf16 v[122:125], v[198:201], v[162:165], v[122:125]
	v_mfma_f32_16x16x32_bf16 v[114:117], v[206:209], v[162:165], v[114:117]
	v_mfma_f32_16x16x32_bf16 v[106:109], v[198:201], v[170:173], v[106:109]
	v_mfma_f32_16x16x32_bf16 v[98:101], v[206:209], v[170:173], v[98:101]
	v_mfma_f32_16x16x32_bf16 v[90:93], v[198:201], v[178:181], v[90:93]
	v_mfma_f32_16x16x32_bf16 v[82:85], v[206:209], v[178:181], v[82:85]
	v_mfma_f32_16x16x32_bf16 v[74:77], v[198:201], v[186:189], v[74:77]
	v_mfma_f32_16x16x32_bf16 v[66:69], v[206:209], v[186:189], v[66:69]
	v_mfma_f32_16x16x32_bf16 v[122:125], v[202:205], v[166:169], v[122:125]
	v_mfma_f32_16x16x32_bf16 v[114:117], v[210:213], v[166:169], v[114:117]
	v_mfma_f32_16x16x32_bf16 v[106:109], v[202:205], v[174:177], v[106:109]
	v_mfma_f32_16x16x32_bf16 v[98:101], v[210:213], v[174:177], v[98:101]
	v_mfma_f32_16x16x32_bf16 v[90:93], v[202:205], v[182:185], v[90:93]
	v_mfma_f32_16x16x32_bf16 v[82:85], v[210:213], v[182:185], v[82:85]
	v_mfma_f32_16x16x32_bf16 v[74:77], v[202:205], v[190:193], v[74:77]
	v_mfma_f32_16x16x32_bf16 v[66:69], v[210:213], v[190:193], v[66:69]
	s_setprio 0
	s_mov_b32 m0, s42
	v_lshl_add_u64 v[140:141], v[216:217], 0, s[66:67]
	s_barrier
	ds_read_b128 v[162:165], v145 offset:49152
	ds_read_b128 v[166:169], v145 offset:50176
	ds_read_b128 v[170:173], v145 offset:51200
	ds_read_b128 v[174:177], v145 offset:52224
	ds_read_b128 v[178:181], v145 offset:53248
	ds_read_b128 v[182:185], v145 offset:54272
	ds_read_b128 v[186:189], v145 offset:55296
	ds_read_b128 v[190:193], v145 offset:56320
	global_load_lds_dwordx4 v[140:141], off
	v_lshl_add_u64 v[140:141], v[218:219], 0, s[66:67]
	s_mov_b32 m0, s43
	s_nop 0
	global_load_lds_dwordx4 v[140:141], off
	s_barrier
	s_waitcnt lgkmcnt(0)
	s_setprio 1
	s_waitcnt lgkmcnt(0)
	v_mfma_f32_16x16x32_bf16 v[62:65], v[146:149], v[162:165], v[62:65]
	v_mfma_f32_16x16x32_bf16 v[54:57], v[154:157], v[162:165], v[54:57]
	v_mfma_f32_16x16x32_bf16 v[44:47], v[146:149], v[170:173], v[44:47]
	v_mfma_f32_16x16x32_bf16 v[36:39], v[154:157], v[170:173], v[36:39]
	v_mfma_f32_16x16x32_bf16 v[28:31], v[146:149], v[178:181], v[28:31]
	v_mfma_f32_16x16x32_bf16 v[20:23], v[154:157], v[178:181], v[20:23]
	v_mfma_f32_16x16x32_bf16 v[12:15], v[146:149], v[186:189], v[12:15]
	v_mfma_f32_16x16x32_bf16 v[4:7], v[154:157], v[186:189], v[4:7]
	v_mfma_f32_16x16x32_bf16 v[62:65], v[150:153], v[166:169], v[62:65]
	v_mfma_f32_16x16x32_bf16 v[54:57], v[158:161], v[166:169], v[54:57]
	v_mfma_f32_16x16x32_bf16 v[44:47], v[150:153], v[174:177], v[44:47]
	v_mfma_f32_16x16x32_bf16 v[36:39], v[158:161], v[174:177], v[36:39]
	v_mfma_f32_16x16x32_bf16 v[28:31], v[150:153], v[182:185], v[28:31]
	v_mfma_f32_16x16x32_bf16 v[20:23], v[158:161], v[182:185], v[20:23]
	v_mfma_f32_16x16x32_bf16 v[12:15], v[150:153], v[190:193], v[12:15]
	v_mfma_f32_16x16x32_bf16 v[4:7], v[158:161], v[190:193], v[4:7]
	s_setprio 0
	s_barrier
	s_add_u32 s28, s28, 0x40080
	s_addc_u32 s29, s29, 0
	s_add_i32 s30, s30, s37
	s_mov_b32 m0, s30
	s_nop 0
	global_load_lds_dwordx4 v48, s[28:29]
	s_add_i32 m0, s30, 0x2000
	s_nop 0
	global_load_lds_dwordx4 v130, s[28:29]
	s_waitcnt vmcnt(6)
	s_barrier
	s_setprio 1
	v_mfma_f32_16x16x32_bf16 v[58:61], v[198:201], v[162:165], v[58:61]
	v_mfma_f32_16x16x32_bf16 v[50:53], v[206:209], v[162:165], v[50:53]
	v_mfma_f32_16x16x32_bf16 v[40:43], v[198:201], v[170:173], v[40:43]
	v_mfma_f32_16x16x32_bf16 v[32:35], v[206:209], v[170:173], v[32:35]
	v_mfma_f32_16x16x32_bf16 v[24:27], v[198:201], v[178:181], v[24:27]
	v_mfma_f32_16x16x32_bf16 v[16:19], v[206:209], v[178:181], v[16:19]
	v_mfma_f32_16x16x32_bf16 v[8:11], v[198:201], v[186:189], v[8:11]
	v_mfma_f32_16x16x32_bf16 v[0:3], v[206:209], v[186:189], v[0:3]
	v_mfma_f32_16x16x32_bf16 v[58:61], v[202:205], v[166:169], v[58:61]
	v_mfma_f32_16x16x32_bf16 v[50:53], v[210:213], v[166:169], v[50:53]
	v_mfma_f32_16x16x32_bf16 v[40:43], v[202:205], v[174:177], v[40:43]
	v_mfma_f32_16x16x32_bf16 v[32:35], v[210:213], v[174:177], v[32:35]
	v_mfma_f32_16x16x32_bf16 v[24:27], v[202:205], v[182:185], v[24:27]
	v_mfma_f32_16x16x32_bf16 v[16:19], v[210:213], v[182:185], v[16:19]
	v_mfma_f32_16x16x32_bf16 v[8:11], v[202:205], v[190:193], v[8:11]
	v_mfma_f32_16x16x32_bf16 v[0:3], v[210:213], v[190:193], v[0:3]
	s_setprio 0
	s_add_i32 s45, s45, 2
	s_add_u32 s26, s26, 0x100
	s_addc_u32 s27, s27, 0
	s_add_u32 s15, s15, 0x100
	s_addc_u32 s17, s17, 0
	s_cmp_gt_u32 s45, 13
	s_barrier
	s_cbranch_scc0 .LBB0_1356
	v_mul_f32_e32 v147, 0xbfb8aa3b, v126
	v_exp_f32_e32 v148, v147
	v_mul_f32_e32 v147, 0xbfb8aa3b, v118
	v_exp_f32_e32 v150, v147
	v_mul_f32_e32 v147, 0xbfb8aa3b, v127
	v_exp_f32_e32 v149, v147
	v_lshl_or_b32 v140, s22, 7, v144
	v_lshl_add_u32 v146, s24, 8, v142
	v_ashrrev_i32_e32 v141, 31, v140
	v_pk_add_f32 v[148:149], v[148:149], 1.0 op_sel_hi:[1,0]
	s_movk_i32 s15, 0x1600
	s_mov_b32 s22, s14
	s_mov_b32 s24, s16
	s_mov_b64 s[28:29], s[20:21]
	v_rcp_f32_e32 v147, v149
	s_nop 0
	v_mul_f32_e32 v127, v127, v147
	s_nop 0
	v_rcp_f32_e32 v147, v148
	s_nop 0
	v_mul_f32_e32 v126, v126, v147
	v_pk_mul_f32 v[122:123], v[122:123], v[126:127]
	v_mul_f32_e32 v126, 0xbfb8aa3b, v119
	v_exp_f32_e32 v151, v126
	s_nop 0
	v_pk_add_f32 v[126:127], v[150:151], 1.0 op_sel_hi:[1,0]
	s_nop 0
	s_nop 0
	v_rcp_f32_e32 v147, v127
	s_nop 0
	v_mul_f32_e32 v119, v119, v147
	s_nop 0
	v_rcp_f32_e32 v127, v126
	s_nop 0
	v_mul_f32_e32 v118, v118, v127
	v_pk_mul_f32 v[114:115], v[114:115], v[118:119]
	v_mul_f32_e32 v119, 0xbfb8aa3b, v120
	v_mul_f32_e32 v118, 0xbfb8aa3b, v128
	v_exp_f32_e32 v126, v119
	v_mul_f32_e32 v119, 0xbfb8aa3b, v129
	v_exp_f32_e32 v118, v118
	v_exp_f32_e32 v119, v119
	s_nop 0
	v_pk_add_f32 v[118:119], v[118:119], 1.0 op_sel_hi:[1,0]
	s_nop 0
	s_nop 0
	v_rcp_f32_e32 v127, v119
	s_nop 0
	v_mul_f32_e32 v119, v129, v127
	s_nop 0
	v_rcp_f32_e32 v127, v118
	s_nop 0
	v_mul_f32_e32 v118, v128, v127
	v_pk_mul_f32 v[124:125], v[124:125], v[118:119]
	v_mul_f32_e32 v118, 0xbfb8aa3b, v121
	v_exp_f32_e32 v127, v118
	s_nop 0
	v_pk_add_f32 v[118:119], v[126:127], 1.0 op_sel_hi:[1,0]
	s_nop 0
	s_nop 0
	v_rcp_f32_e32 v126, v119
	s_nop 0
	v_mul_f32_e32 v119, v121, v126
	s_nop 0
	v_rcp_f32_e32 v121, v118
	s_nop 0
	v_mul_f32_e32 v118, v120, v121
	v_pk_mul_f32 v[116:117], v[116:117], v[118:119]
	v_cvt_pk_bf16_f32 v120, v114, v115
	v_mov_b64_e32 v[114:115], s[12:13]
	v_cvt_pk_bf16_f32 v118, v122, v123
	v_cvt_pk_bf16_f32 v121, v116, v117
	v_mad_i64_i32 v[122:123], s[26:27], v146, s15, v[114:115]
	v_lshlrev_b64 v[116:117], 1, v[140:141]
	v_cvt_pk_bf16_f32 v119, v124, v125
	v_lshl_add_u64 v[122:123], v[122:123], 0, v[116:117]
	global_store_dwordx4 v[122:123], v[118:121], off
	s_nop 1
	v_mul_f32_e32 v119, 0xbfb8aa3b, v102
	v_mul_f32_e32 v118, 0xbfb8aa3b, v110
	v_exp_f32_e32 v120, v119
	v_mul_f32_e32 v119, 0xbfb8aa3b, v111
	v_exp_f32_e32 v118, v118
	v_exp_f32_e32 v119, v119
	s_nop 0
	v_pk_add_f32 v[118:119], v[118:119], 1.0 op_sel_hi:[1,0]
	s_nop 0
	s_nop 0
	v_rcp_f32_e32 v121, v119
	s_nop 0
	v_mul_f32_e32 v111, v111, v121
	s_nop 0
	v_rcp_f32_e32 v119, v118
	s_nop 0
	v_mul_f32_e32 v110, v110, v119
	v_pk_mul_f32 v[106:107], v[106:107], v[110:111]
	v_mul_f32_e32 v110, 0xbfb8aa3b, v103
	v_exp_f32_e32 v121, v110
	s_nop 0
	v_pk_add_f32 v[110:111], v[120:121], 1.0 op_sel_hi:[1,0]
	s_nop 0
	s_nop 0
	v_rcp_f32_e32 v118, v111
	s_nop 0
	v_mul_f32_e32 v103, v103, v118
	s_nop 0
	v_rcp_f32_e32 v111, v110
	s_nop 0
	v_mul_f32_e32 v102, v102, v111
	v_pk_mul_f32 v[102:103], v[98:99], v[102:103]
	v_mul_f32_e32 v99, 0xbfb8aa3b, v104
	v_mul_f32_e32 v98, 0xbfb8aa3b, v112
	v_exp_f32_e32 v110, v99
	v_mul_f32_e32 v99, 0xbfb8aa3b, v113
	v_exp_f32_e32 v98, v98
	v_exp_f32_e32 v99, v99
	s_nop 0
	v_pk_add_f32 v[98:99], v[98:99], 1.0 op_sel_hi:[1,0]
	s_nop 0
	s_nop 0
	v_rcp_f32_e32 v111, v99
	s_nop 0
	v_mul_f32_e32 v99, v113, v111
	s_nop 0
	v_rcp_f32_e32 v111, v98
	s_nop 0
	v_mul_f32_e32 v98, v112, v111
	v_pk_mul_f32 v[108:109], v[108:109], v[98:99]
	v_mul_f32_e32 v98, 0xbfb8aa3b, v105
	v_exp_f32_e32 v111, v98
	s_nop 0
	v_pk_add_f32 v[98:99], v[110:111], 1.0 op_sel_hi:[1,0]
	s_nop 0
	s_nop 0
	v_rcp_f32_e32 v110, v99
	s_nop 0
	v_mul_f32_e32 v99, v105, v110
	s_nop 0
	v_rcp_f32_e32 v105, v98
	s_nop 0
	v_mul_f32_e32 v98, v104, v105
	v_or_b32_e32 v110, 16, v146
	v_pk_mul_f32 v[104:105], v[100:101], v[98:99]
	v_cvt_pk_bf16_f32 v100, v102, v103
	v_mad_i64_i32 v[102:103], s[26:27], v110, s15, v[114:115]
	v_cvt_pk_bf16_f32 v98, v106, v107
	v_cvt_pk_bf16_f32 v99, v108, v109
	v_cvt_pk_bf16_f32 v101, v104, v105
	v_lshl_add_u64 v[102:103], v[102:103], 0, v[116:117]
	global_store_dwordx4 v[102:103], v[98:101], off
	s_nop 1
	v_mul_f32_e32 v99, 0xbfb8aa3b, v86
	v_mul_f32_e32 v98, 0xbfb8aa3b, v94
	v_exp_f32_e32 v100, v99
	v_mul_f32_e32 v99, 0xbfb8aa3b, v95
	v_exp_f32_e32 v98, v98
	v_exp_f32_e32 v99, v99
	s_nop 0
	v_pk_add_f32 v[98:99], v[98:99], 1.0 op_sel_hi:[1,0]
	s_nop 0
	s_nop 0
	v_rcp_f32_e32 v101, v99
	s_nop 0
	v_mul_f32_e32 v95, v95, v101
	s_nop 0
	v_rcp_f32_e32 v99, v98
	s_nop 0
	v_mul_f32_e32 v94, v94, v99
	v_pk_mul_f32 v[90:91], v[90:91], v[94:95]
	v_mul_f32_e32 v94, 0xbfb8aa3b, v87
	v_exp_f32_e32 v101, v94
	s_nop 0
	v_pk_add_f32 v[94:95], v[100:101], 1.0 op_sel_hi:[1,0]
	s_nop 0
	s_nop 0
	v_rcp_f32_e32 v98, v95
	s_nop 0
	v_mul_f32_e32 v87, v87, v98
	s_nop 0
	v_rcp_f32_e32 v95, v94
	s_nop 0
	v_mul_f32_e32 v86, v86, v95
	v_pk_mul_f32 v[86:87], v[82:83], v[86:87]
	v_mul_f32_e32 v83, 0xbfb8aa3b, v88
	v_mul_f32_e32 v82, 0xbfb8aa3b, v96
	v_exp_f32_e32 v94, v83
	v_mul_f32_e32 v83, 0xbfb8aa3b, v97
	v_exp_f32_e32 v82, v82
	v_exp_f32_e32 v83, v83
	s_nop 0
	v_pk_add_f32 v[82:83], v[82:83], 1.0 op_sel_hi:[1,0]
	s_nop 0
	s_nop 0
	v_rcp_f32_e32 v95, v83
	s_nop 0
	v_mul_f32_e32 v83, v97, v95
	s_nop 0
	v_rcp_f32_e32 v95, v82
	s_nop 0
	v_mul_f32_e32 v82, v96, v95
	v_pk_mul_f32 v[92:93], v[92:93], v[82:83]
	v_mul_f32_e32 v82, 0xbfb8aa3b, v89
	v_exp_f32_e32 v95, v82
	s_nop 0
	v_pk_add_f32 v[82:83], v[94:95], 1.0 op_sel_hi:[1,0]
	s_nop 0
	s_nop 0
	v_rcp_f32_e32 v94, v83
	s_nop 0
	v_mul_f32_e32 v83, v89, v94
	s_nop 0
	v_rcp_f32_e32 v89, v82
	s_nop 0
	v_mul_f32_e32 v82, v88, v89
	v_or_b32_e32 v94, 32, v146
	v_pk_mul_f32 v[88:89], v[84:85], v[82:83]
	v_cvt_pk_bf16_f32 v84, v86, v87
	v_mad_i64_i32 v[86:87], s[26:27], v94, s15, v[114:115]
	v_cvt_pk_bf16_f32 v82, v90, v91
	v_cvt_pk_bf16_f32 v83, v92, v93
	v_cvt_pk_bf16_f32 v85, v88, v89
	v_lshl_add_u64 v[86:87], v[86:87], 0, v[116:117]
	global_store_dwordx4 v[86:87], v[82:85], off
	s_nop 1
	v_mul_f32_e32 v83, 0xbfb8aa3b, v70
	v_mul_f32_e32 v82, 0xbfb8aa3b, v78
	v_exp_f32_e32 v84, v83
	v_mul_f32_e32 v83, 0xbfb8aa3b, v79
	v_exp_f32_e32 v82, v82
	v_exp_f32_e32 v83, v83
	s_nop 0
	v_pk_add_f32 v[82:83], v[82:83], 1.0 op_sel_hi:[1,0]
	s_nop 0
	s_nop 0
	v_rcp_f32_e32 v85, v83
	s_nop 0
	v_mul_f32_e32 v79, v79, v85
	s_nop 0
	v_rcp_f32_e32 v83, v82
	s_nop 0
	v_mul_f32_e32 v78, v78, v83
	v_pk_mul_f32 v[74:75], v[74:75], v[78:79]
	v_mul_f32_e32 v78, 0xbfb8aa3b, v71
	v_exp_f32_e32 v85, v78
	s_nop 0
	v_pk_add_f32 v[78:79], v[84:85], 1.0 op_sel_hi:[1,0]
	s_nop 0
	s_nop 0
	v_rcp_f32_e32 v82, v79
	s_nop 0
	v_mul_f32_e32 v71, v71, v82
	s_nop 0
	v_rcp_f32_e32 v79, v78
	s_nop 0
	v_mul_f32_e32 v70, v70, v79
	v_pk_mul_f32 v[70:71], v[66:67], v[70:71]
	v_mul_f32_e32 v67, 0xbfb8aa3b, v72
	v_mul_f32_e32 v66, 0xbfb8aa3b, v80
	v_exp_f32_e32 v78, v67
	v_mul_f32_e32 v67, 0xbfb8aa3b, v81
	v_exp_f32_e32 v66, v66
	v_exp_f32_e32 v67, v67
	s_nop 0
	v_pk_add_f32 v[66:67], v[66:67], 1.0 op_sel_hi:[1,0]
	s_nop 0
	s_nop 0
	v_rcp_f32_e32 v79, v67
	s_nop 0
	v_mul_f32_e32 v67, v81, v79
	s_nop 0
	v_rcp_f32_e32 v79, v66
	s_nop 0
	v_mul_f32_e32 v66, v80, v79
	v_pk_mul_f32 v[76:77], v[76:77], v[66:67]
	v_mul_f32_e32 v66, 0xbfb8aa3b, v73
	v_exp_f32_e32 v79, v66
	s_nop 0
	v_pk_add_f32 v[66:67], v[78:79], 1.0 op_sel_hi:[1,0]
	s_nop 0
	s_nop 0
	v_rcp_f32_e32 v78, v67
	s_nop 0
	v_mul_f32_e32 v67, v73, v78
	s_nop 0
	v_rcp_f32_e32 v73, v66
	s_nop 0
	v_mul_f32_e32 v66, v72, v73
	v_or_b32_e32 v78, 48, v146
	v_pk_mul_f32 v[72:73], v[68:69], v[66:67]
	v_cvt_pk_bf16_f32 v68, v70, v71
	v_mad_i64_i32 v[70:71], s[26:27], v78, s15, v[114:115]
	v_cvt_pk_bf16_f32 v66, v74, v75
	v_cvt_pk_bf16_f32 v67, v76, v77
	v_cvt_pk_bf16_f32 v69, v72, v73
	v_lshl_add_u64 v[70:71], v[70:71], 0, v[116:117]
	global_store_dwordx4 v[70:71], v[66:69], off
	v_add_u32_e32 v70, 0x80, v146
	s_nop 0
	v_mul_f32_e32 v67, 0xbfb8aa3b, v54
	v_mul_f32_e32 v66, 0xbfb8aa3b, v62
	v_exp_f32_e32 v68, v67
	v_mul_f32_e32 v67, 0xbfb8aa3b, v63
	v_exp_f32_e32 v66, v66
	v_exp_f32_e32 v67, v67
	s_nop 0
	v_pk_add_f32 v[66:67], v[66:67], 1.0 op_sel_hi:[1,0]
	s_nop 0
	s_nop 0
	v_rcp_f32_e32 v69, v67
	s_nop 0
	v_mul_f32_e32 v63, v63, v69
	s_nop 0
	v_rcp_f32_e32 v67, v66
	s_nop 0
	v_mul_f32_e32 v62, v62, v67
	v_pk_mul_f32 v[58:59], v[58:59], v[62:63]
	v_mul_f32_e32 v62, 0xbfb8aa3b, v55
	v_exp_f32_e32 v69, v62
	s_nop 0
	v_pk_add_f32 v[62:63], v[68:69], 1.0 op_sel_hi:[1,0]
	s_nop 0
	s_nop 0
	v_rcp_f32_e32 v66, v63
	s_nop 0
	v_mul_f32_e32 v55, v55, v66
	s_nop 0
	v_rcp_f32_e32 v63, v62
	s_nop 0
	v_mul_f32_e32 v54, v54, v63
	v_pk_mul_f32 v[54:55], v[50:51], v[54:55]
	v_mul_f32_e32 v51, 0xbfb8aa3b, v56
	v_mul_f32_e32 v50, 0xbfb8aa3b, v64
	v_exp_f32_e32 v62, v51
	v_mul_f32_e32 v51, 0xbfb8aa3b, v65
	v_exp_f32_e32 v50, v50
	v_exp_f32_e32 v51, v51
	s_nop 0
	v_pk_add_f32 v[50:51], v[50:51], 1.0 op_sel_hi:[1,0]
	s_nop 0
	s_nop 0
	v_rcp_f32_e32 v63, v51
	s_nop 0
	v_mul_f32_e32 v51, v65, v63
	s_nop 0
	v_rcp_f32_e32 v63, v50
	s_nop 0
	v_mul_f32_e32 v50, v64, v63
	v_pk_mul_f32 v[60:61], v[60:61], v[50:51]
	v_mul_f32_e32 v50, 0xbfb8aa3b, v57
	v_exp_f32_e32 v63, v50
	s_nop 0
	v_pk_add_f32 v[50:51], v[62:63], 1.0 op_sel_hi:[1,0]
	s_nop 0
	s_nop 0
	v_rcp_f32_e32 v62, v51
	s_nop 0
	v_mul_f32_e32 v51, v57, v62
	s_nop 0
	v_rcp_f32_e32 v57, v50
	s_nop 0
	v_mul_f32_e32 v50, v56, v57
	v_pk_mul_f32 v[56:57], v[52:53], v[50:51]
	v_cvt_pk_bf16_f32 v52, v54, v55
	v_mad_i64_i32 v[54:55], s[26:27], v70, s15, v[114:115]
	v_cvt_pk_bf16_f32 v50, v58, v59
	v_cvt_pk_bf16_f32 v51, v60, v61
	v_cvt_pk_bf16_f32 v53, v56, v57
	v_lshl_add_u64 v[54:55], v[54:55], 0, v[116:117]
	global_store_dwordx4 v[54:55], v[50:53], off
	s_nop 1
	v_mul_f32_e32 v51, 0xbfb8aa3b, v36
	v_mul_f32_e32 v50, 0xbfb8aa3b, v44
	v_exp_f32_e32 v52, v51
	v_mul_f32_e32 v51, 0xbfb8aa3b, v45
	v_exp_f32_e32 v50, v50
	v_exp_f32_e32 v51, v51
	s_nop 0
	v_pk_add_f32 v[50:51], v[50:51], 1.0 op_sel_hi:[1,0]
	s_nop 0
	s_nop 0
	v_rcp_f32_e32 v53, v51
	s_nop 0
	v_mul_f32_e32 v45, v45, v53
	s_nop 0
	v_rcp_f32_e32 v51, v50
	s_nop 0
	v_mul_f32_e32 v44, v44, v51
	v_pk_mul_f32 v[40:41], v[40:41], v[44:45]
	v_mul_f32_e32 v44, 0xbfb8aa3b, v37
	v_exp_f32_e32 v53, v44
	s_nop 0
	v_pk_add_f32 v[44:45], v[52:53], 1.0 op_sel_hi:[1,0]
	s_nop 0
	s_nop 0
	v_rcp_f32_e32 v50, v45
	s_nop 0
	v_mul_f32_e32 v37, v37, v50
	s_nop 0
	v_rcp_f32_e32 v45, v44
	s_nop 0
	v_mul_f32_e32 v36, v36, v45
	v_pk_mul_f32 v[36:37], v[32:33], v[36:37]
	v_mul_f32_e32 v33, 0xbfb8aa3b, v38
	v_mul_f32_e32 v32, 0xbfb8aa3b, v46
	v_exp_f32_e32 v44, v33
	v_mul_f32_e32 v33, 0xbfb8aa3b, v47
	v_exp_f32_e32 v32, v32
	v_exp_f32_e32 v33, v33
	s_nop 0
	v_pk_add_f32 v[32:33], v[32:33], 1.0 op_sel_hi:[1,0]
	s_nop 0
	s_nop 0
	v_rcp_f32_e32 v45, v33
	s_nop 0
	v_mul_f32_e32 v33, v47, v45
	s_nop 0
	v_rcp_f32_e32 v45, v32
	s_nop 0
	v_mul_f32_e32 v32, v46, v45
	v_pk_mul_f32 v[42:43], v[42:43], v[32:33]
	v_mul_f32_e32 v32, 0xbfb8aa3b, v39
	v_exp_f32_e32 v45, v32
	s_nop 0
	v_pk_add_f32 v[32:33], v[44:45], 1.0 op_sel_hi:[1,0]
	s_nop 0
	s_nop 0
	v_rcp_f32_e32 v44, v33
	s_nop 0
	v_mul_f32_e32 v33, v39, v44
	s_nop 0
	v_rcp_f32_e32 v39, v32
	s_nop 0
	v_mul_f32_e32 v32, v38, v39
	v_add_u32_e32 v44, 0x90, v146
	v_pk_mul_f32 v[38:39], v[34:35], v[32:33]
	v_cvt_pk_bf16_f32 v34, v36, v37
	v_mad_i64_i32 v[36:37], s[26:27], v44, s15, v[114:115]
	v_cvt_pk_bf16_f32 v32, v40, v41
	v_cvt_pk_bf16_f32 v33, v42, v43
	v_cvt_pk_bf16_f32 v35, v38, v39
	v_lshl_add_u64 v[36:37], v[36:37], 0, v[116:117]
	global_store_dwordx4 v[36:37], v[32:35], off
	s_nop 1
	v_mul_f32_e32 v33, 0xbfb8aa3b, v20
	v_mul_f32_e32 v32, 0xbfb8aa3b, v28
	v_exp_f32_e32 v34, v33
	v_mul_f32_e32 v33, 0xbfb8aa3b, v29
	v_exp_f32_e32 v32, v32
	v_exp_f32_e32 v33, v33
	s_nop 0
	v_pk_add_f32 v[32:33], v[32:33], 1.0 op_sel_hi:[1,0]
	s_nop 0
	s_nop 0
	v_rcp_f32_e32 v35, v33
	s_nop 0
	v_mul_f32_e32 v29, v29, v35
	s_nop 0
	v_rcp_f32_e32 v33, v32
	s_nop 0
	v_mul_f32_e32 v28, v28, v33
	v_pk_mul_f32 v[24:25], v[24:25], v[28:29]
	v_mul_f32_e32 v28, 0xbfb8aa3b, v21
	v_exp_f32_e32 v35, v28
	s_nop 0
	v_pk_add_f32 v[28:29], v[34:35], 1.0 op_sel_hi:[1,0]
	s_nop 0
	s_nop 0
	v_rcp_f32_e32 v32, v29
	s_nop 0
	v_mul_f32_e32 v21, v21, v32
	s_nop 0
	v_rcp_f32_e32 v29, v28
	s_nop 0
	v_mul_f32_e32 v20, v20, v29
	v_pk_mul_f32 v[20:21], v[16:17], v[20:21]
	v_mul_f32_e32 v17, 0xbfb8aa3b, v22
	v_mul_f32_e32 v16, 0xbfb8aa3b, v30
	v_exp_f32_e32 v28, v17
	v_mul_f32_e32 v17, 0xbfb8aa3b, v31
	v_exp_f32_e32 v16, v16
	v_exp_f32_e32 v17, v17
	s_nop 0
	v_pk_add_f32 v[16:17], v[16:17], 1.0 op_sel_hi:[1,0]
	s_nop 0
	s_nop 0
	v_rcp_f32_e32 v29, v17
	s_nop 0
	v_mul_f32_e32 v17, v31, v29
	s_nop 0
	v_rcp_f32_e32 v29, v16
	s_nop 0
	v_mul_f32_e32 v16, v30, v29
	v_pk_mul_f32 v[26:27], v[26:27], v[16:17]
	v_mul_f32_e32 v16, 0xbfb8aa3b, v23
	v_exp_f32_e32 v29, v16
	s_nop 0
	v_pk_add_f32 v[16:17], v[28:29], 1.0 op_sel_hi:[1,0]
	s_nop 0
	s_nop 0
	v_rcp_f32_e32 v28, v17
	s_nop 0
	v_mul_f32_e32 v17, v23, v28
	s_nop 0
	v_rcp_f32_e32 v23, v16
	s_nop 0
	v_mul_f32_e32 v16, v22, v23
	v_add_u32_e32 v28, 0xa0, v146
	v_pk_mul_f32 v[22:23], v[18:19], v[16:17]
	v_cvt_pk_bf16_f32 v18, v20, v21
	v_mad_i64_i32 v[20:21], s[26:27], v28, s15, v[114:115]
	v_cvt_pk_bf16_f32 v16, v24, v25
	v_cvt_pk_bf16_f32 v17, v26, v27
	v_cvt_pk_bf16_f32 v19, v22, v23
	v_lshl_add_u64 v[20:21], v[20:21], 0, v[116:117]
	global_store_dwordx4 v[20:21], v[16:19], off
	s_nop 1
	v_mul_f32_e32 v17, 0xbfb8aa3b, v4
	v_mul_f32_e32 v16, 0xbfb8aa3b, v12
	v_exp_f32_e32 v18, v17
	v_mul_f32_e32 v17, 0xbfb8aa3b, v13
	v_exp_f32_e32 v16, v16
	v_exp_f32_e32 v17, v17
	s_nop 0
	v_pk_add_f32 v[16:17], v[16:17], 1.0 op_sel_hi:[1,0]
	s_nop 0
	s_nop 0
	v_rcp_f32_e32 v19, v17
	s_nop 0
	v_mul_f32_e32 v13, v13, v19
	s_nop 0
	v_rcp_f32_e32 v17, v16
	s_nop 0
	v_mul_f32_e32 v12, v12, v17
	v_pk_mul_f32 v[8:9], v[8:9], v[12:13]
	v_mul_f32_e32 v12, 0xbfb8aa3b, v5
	v_exp_f32_e32 v19, v12
	s_nop 0
	v_pk_add_f32 v[12:13], v[18:19], 1.0 op_sel_hi:[1,0]
	s_nop 0
	s_nop 0
	v_rcp_f32_e32 v16, v13
	s_nop 0
	v_mul_f32_e32 v5, v5, v16
	s_nop 0
	v_rcp_f32_e32 v13, v12
	s_nop 0
	v_mul_f32_e32 v4, v4, v13
	v_pk_mul_f32 v[4:5], v[0:1], v[4:5]
	v_mul_f32_e32 v1, 0xbfb8aa3b, v6
	v_mul_f32_e32 v0, 0xbfb8aa3b, v14
	v_exp_f32_e32 v12, v1
	v_mul_f32_e32 v1, 0xbfb8aa3b, v15
	v_exp_f32_e32 v0, v0
	v_exp_f32_e32 v1, v1
	s_nop 0
	v_pk_add_f32 v[0:1], v[0:1], 1.0 op_sel_hi:[1,0]
	s_nop 0
	s_nop 0
	v_rcp_f32_e32 v13, v1
	s_nop 0
	v_mul_f32_e32 v1, v15, v13
	s_nop 0
	v_rcp_f32_e32 v13, v0
	s_nop 0
	v_mul_f32_e32 v0, v14, v13
	v_pk_mul_f32 v[10:11], v[10:11], v[0:1]
	v_mul_f32_e32 v0, 0xbfb8aa3b, v7
	v_exp_f32_e32 v13, v0
	s_nop 0
	v_pk_add_f32 v[0:1], v[12:13], 1.0 op_sel_hi:[1,0]
	s_nop 0
	s_nop 0
	v_rcp_f32_e32 v12, v1
	s_nop 0
	v_mul_f32_e32 v1, v7, v12
	s_nop 0
	v_rcp_f32_e32 v7, v0
	s_nop 0
	v_mul_f32_e32 v0, v6, v7
	v_add_u32_e32 v12, 0xb0, v146
	v_pk_mul_f32 v[6:7], v[2:3], v[0:1]
	v_cvt_pk_bf16_f32 v2, v4, v5
	v_mad_i64_i32 v[4:5], s[26:27], v12, s15, v[114:115]
	v_cvt_pk_bf16_f32 v0, v8, v9
	v_cvt_pk_bf16_f32 v1, v10, v11
	v_cvt_pk_bf16_f32 v3, v6, v7
	v_lshl_add_u64 v[4:5], v[4:5], 0, v[116:117]
	s_and_b64 vcc, exec, s[0:1]
	s_mov_b64 s[26:27], s[18:19]
	global_store_dwordx4 v[4:5], v[0:3], off
	s_cbranch_vccz .LBB0_1353
	s_waitcnt vmcnt(0)
	s_cmpk_gt_u32 s5, 0xff
	s_cbranch_scc1 .LBB0_1360
	s_barrier

.LBB0_1421:
	ds_read_b128 v[130:133], v202
	ds_read_b128 v[134:137], v202 offset:1024
	ds_read_b128 v[138:141], v202 offset:2048
	ds_read_b128 v[142:145], v202 offset:3072
	s_add_u32 s18, s16, 0x100
	s_addc_u32 s19, s17, 0
	s_add_i32 s47, 0, 0x10000
	s_cmp_eq_u32 s46, 40
	s_cselect_b32 s23, s11, s19
	s_cselect_b32 s22, s10, s18
	s_cselect_b32 s21, s13, s45
	s_cselect_b32 s20, s12, s44
	v_lshl_add_u64 v[188:189], s[16:17], 0, v[152:153]
	s_add_i32 m0, s31, 0xc000
	ds_read_b128 v[156:159], v206
	ds_read_b128 v[160:163], v206 offset:1024
	ds_read_b128 v[164:167], v206 offset:2048
	ds_read_b128 v[168:171], v206 offset:3072
	ds_read_b128 v[172:175], v206 offset:4096
	ds_read_b128 v[176:179], v206 offset:5120
	ds_read_b128 v[180:183], v206 offset:6144
	ds_read_b128 v[184:187], v206 offset:7168
	global_load_lds_dwordx4 v[188:189], off
	v_lshl_add_u64 v[188:189], s[16:17], 0, v[154:155]
	s_add_i32 m0, s31, 0xe000
	s_nop 0
	global_load_lds_dwordx4 v[188:189], off
	s_waitcnt lgkmcnt(8)
	s_barrier
	s_waitcnt lgkmcnt(0)
	s_setprio 1
	s_waitcnt lgkmcnt(0)
	v_mfma_f32_16x16x32_bf16 v[126:129], v[130:133], v[156:159], v[126:129]
	v_mfma_f32_16x16x32_bf16 v[122:125], v[138:141], v[156:159], v[122:125]
	v_mfma_f32_16x16x32_bf16 v[114:117], v[130:133], v[164:167], v[114:117]
	v_mfma_f32_16x16x32_bf16 v[106:109], v[138:141], v[164:167], v[106:109]
	v_mfma_f32_16x16x32_bf16 v[98:101], v[130:133], v[172:175], v[98:101]
	v_mfma_f32_16x16x32_bf16 v[90:93], v[138:141], v[172:175], v[90:93]
	v_mfma_f32_16x16x32_bf16 v[82:85], v[130:133], v[180:183], v[82:85]
	v_mfma_f32_16x16x32_bf16 v[74:77], v[138:141], v[180:183], v[74:77]
	v_mfma_f32_16x16x32_bf16 v[126:129], v[134:137], v[160:163], v[126:129]
	v_mfma_f32_16x16x32_bf16 v[122:125], v[142:145], v[160:163], v[122:125]
	v_mfma_f32_16x16x32_bf16 v[114:117], v[134:137], v[168:171], v[114:117]
	v_mfma_f32_16x16x32_bf16 v[106:109], v[142:145], v[168:171], v[106:109]
	v_mfma_f32_16x16x32_bf16 v[98:101], v[134:137], v[176:179], v[98:101]
	v_mfma_f32_16x16x32_bf16 v[90:93], v[142:145], v[176:179], v[90:93]
	v_mfma_f32_16x16x32_bf16 v[82:85], v[134:137], v[184:187], v[82:85]
	v_mfma_f32_16x16x32_bf16 v[74:77], v[142:145], v[184:187], v[74:77]
	s_setprio 0
	s_barrier
	ds_read_b128 v[188:191], v202 offset:16384
	ds_read_b128 v[198:201], v202 offset:17408
	ds_read_b128 v[208:211], v202 offset:18432
	ds_read_b128 v[212:215], v202 offset:19456
	s_add_i32 s48, 0, 0x14000
	s_add_i32 s16, s47, s25
	s_mov_b32 m0, s16
	global_load_lds_dwordx4 v48, s[20:21]
	s_add_i32 m0, s16, 0x2000
	s_nop 0
	global_load_lds_dwordx4 v146, s[20:21]
	s_barrier
	s_waitcnt lgkmcnt(0)
	s_setprio 1
	s_waitcnt lgkmcnt(0)
	v_mfma_f32_16x16x32_bf16 v[118:121], v[188:191], v[156:159], v[118:121]
	v_mfma_f32_16x16x32_bf16 v[110:113], v[208:211], v[156:159], v[110:113]
	v_mfma_f32_16x16x32_bf16 v[102:105], v[188:191], v[164:167], v[102:105]
	v_mfma_f32_16x16x32_bf16 v[94:97], v[208:211], v[164:167], v[94:97]
	v_mfma_f32_16x16x32_bf16 v[86:89], v[188:191], v[172:175], v[86:89]
	v_mfma_f32_16x16x32_bf16 v[78:81], v[208:211], v[172:175], v[78:81]
	v_mfma_f32_16x16x32_bf16 v[70:73], v[188:191], v[180:183], v[70:73]
	v_mfma_f32_16x16x32_bf16 v[66:69], v[208:211], v[180:183], v[66:69]
	v_mfma_f32_16x16x32_bf16 v[118:121], v[198:201], v[160:163], v[118:121]
	v_mfma_f32_16x16x32_bf16 v[110:113], v[212:215], v[160:163], v[110:113]
	v_mfma_f32_16x16x32_bf16 v[102:105], v[198:201], v[168:171], v[102:105]
	v_mfma_f32_16x16x32_bf16 v[94:97], v[212:215], v[168:171], v[94:97]
	v_mfma_f32_16x16x32_bf16 v[86:89], v[198:201], v[176:179], v[86:89]
	v_mfma_f32_16x16x32_bf16 v[78:81], v[212:215], v[176:179], v[78:81]
	v_mfma_f32_16x16x32_bf16 v[70:73], v[198:201], v[184:187], v[70:73]
	v_mfma_f32_16x16x32_bf16 v[66:69], v[212:215], v[184:187], v[66:69]
	s_setprio 0
	s_mov_b32 m0, s31
	v_lshl_add_u64 v[216:217], s[22:23], 0, v[48:49]
	s_barrier
	ds_read_b128 v[156:159], v206 offset:16384
	ds_read_b128 v[160:163], v206 offset:17408
	ds_read_b128 v[164:167], v206 offset:18432
	ds_read_b128 v[168:171], v206 offset:19456
	ds_read_b128 v[172:175], v206 offset:20480
	ds_read_b128 v[176:179], v206 offset:21504
	ds_read_b128 v[180:183], v206 offset:22528
	ds_read_b128 v[184:187], v206 offset:23552
	global_load_lds_dwordx4 v[216:217], off
	v_lshl_add_u64 v[218:219], s[22:23], 0, v[146:147]
	s_mov_b32 m0, s34
	s_nop 0
	global_load_lds_dwordx4 v[218:219], off
	s_barrier
	s_waitcnt lgkmcnt(0)
	s_setprio 1
	s_waitcnt lgkmcnt(0)
	v_mfma_f32_16x16x32_bf16 v[62:65], v[130:133], v[156:159], v[62:65]
	v_mfma_f32_16x16x32_bf16 v[58:61], v[138:141], v[156:159], v[58:61]
	v_mfma_f32_16x16x32_bf16 v[50:53], v[130:133], v[164:167], v[50:53]
	v_mfma_f32_16x16x32_bf16 v[40:43], v[138:141], v[164:167], v[40:43]
	v_mfma_f32_16x16x32_bf16 v[32:35], v[130:133], v[172:175], v[32:35]
	v_mfma_f32_16x16x32_bf16 v[24:27], v[138:141], v[172:175], v[24:27]
	v_mfma_f32_16x16x32_bf16 v[16:19], v[130:133], v[180:183], v[16:19]
	v_mfma_f32_16x16x32_bf16 v[8:11], v[138:141], v[180:183], v[8:11]
	v_mfma_f32_16x16x32_bf16 v[62:65], v[134:137], v[160:163], v[62:65]
	v_mfma_f32_16x16x32_bf16 v[58:61], v[142:145], v[160:163], v[58:61]
	v_mfma_f32_16x16x32_bf16 v[50:53], v[134:137], v[168:171], v[50:53]
	v_mfma_f32_16x16x32_bf16 v[40:43], v[142:145], v[168:171], v[40:43]
	v_mfma_f32_16x16x32_bf16 v[32:35], v[134:137], v[176:179], v[32:35]
	v_mfma_f32_16x16x32_bf16 v[24:27], v[142:145], v[176:179], v[24:27]
	v_mfma_f32_16x16x32_bf16 v[16:19], v[134:137], v[184:187], v[16:19]
	v_mfma_f32_16x16x32_bf16 v[8:11], v[142:145], v[184:187], v[8:11]
	s_setprio 0
	s_barrier
	s_add_u32 s16, s20, 0xb0000
	s_addc_u32 s17, s21, 0
	s_add_i32 s47, s48, s25
	s_mov_b32 m0, s47
	s_nop 0
	global_load_lds_dwordx4 v48, s[16:17]
	s_add_i32 m0, s47, 0x2000
	s_nop 0
	global_load_lds_dwordx4 v146, s[16:17]
	s_waitcnt vmcnt(6)
	s_barrier
	s_setprio 1
	v_mfma_f32_16x16x32_bf16 v[54:57], v[188:191], v[156:159], v[54:57]
	v_mfma_f32_16x16x32_bf16 v[44:47], v[208:211], v[156:159], v[44:47]
	v_mfma_f32_16x16x32_bf16 v[36:39], v[188:191], v[164:167], v[36:39]
	v_mfma_f32_16x16x32_bf16 v[28:31], v[208:211], v[164:167], v[28:31]
	v_mfma_f32_16x16x32_bf16 v[20:23], v[188:191], v[172:175], v[20:23]
	v_mfma_f32_16x16x32_bf16 v[12:15], v[208:211], v[172:175], v[12:15]
	v_mfma_f32_16x16x32_bf16 v[4:7], v[188:191], v[180:183], v[4:7]
	v_mfma_f32_16x16x32_bf16 v[0:3], v[208:211], v[180:183], v[0:3]
	v_mfma_f32_16x16x32_bf16 v[54:57], v[198:201], v[160:163], v[54:57]
	v_mfma_f32_16x16x32_bf16 v[44:47], v[212:215], v[160:163], v[44:47]
	v_mfma_f32_16x16x32_bf16 v[36:39], v[198:201], v[168:171], v[36:39]
	v_mfma_f32_16x16x32_bf16 v[28:31], v[212:215], v[168:171], v[28:31]
	v_mfma_f32_16x16x32_bf16 v[20:23], v[198:201], v[176:179], v[20:23]
	v_mfma_f32_16x16x32_bf16 v[12:15], v[212:215], v[176:179], v[12:15]
	v_mfma_f32_16x16x32_bf16 v[4:7], v[198:201], v[184:187], v[4:7]
	v_mfma_f32_16x16x32_bf16 v[0:3], v[212:215], v[184:187], v[0:3]
	s_setprio 0
	s_add_i32 s47, 0, 0x18000
	s_barrier
	ds_read_b128 v[130:133], v202 offset:32768
	ds_read_b128 v[134:137], v202 offset:33792
	ds_read_b128 v[138:141], v202 offset:34816
	ds_read_b128 v[142:145], v202 offset:35840
	s_add_u32 s16, s22, 0xb0000
	s_addc_u32 s17, s23, 0
	s_mov_b32 m0, s35
	ds_read_b128 v[156:159], v206 offset:32768
	ds_read_b128 v[160:163], v206 offset:33792
	ds_read_b128 v[164:167], v206 offset:34816
	ds_read_b128 v[168:171], v206 offset:35840
	ds_read_b128 v[172:175], v206 offset:36864
	ds_read_b128 v[176:179], v206 offset:37888
	ds_read_b128 v[180:183], v206 offset:38912
	ds_read_b128 v[184:187], v206 offset:39936
	global_load_lds_dwordx4 v48, s[16:17]
	s_mov_b32 m0, s36
	s_nop 0
	global_load_lds_dwordx4 v146, s[16:17]
	s_waitcnt lgkmcnt(8)
	s_barrier
	s_waitcnt lgkmcnt(0)
	s_setprio 1
	s_waitcnt lgkmcnt(0)
	v_mfma_f32_16x16x32_bf16 v[126:129], v[130:133], v[156:159], v[126:129]
	v_mfma_f32_16x16x32_bf16 v[122:125], v[138:141], v[156:159], v[122:125]
	v_mfma_f32_16x16x32_bf16 v[114:117], v[130:133], v[164:167], v[114:117]
	v_mfma_f32_16x16x32_bf16 v[106:109], v[138:141], v[164:167], v[106:109]
	v_mfma_f32_16x16x32_bf16 v[98:101], v[130:133], v[172:175], v[98:101]
	v_mfma_f32_16x16x32_bf16 v[90:93], v[138:141], v[172:175], v[90:93]
	v_mfma_f32_16x16x32_bf16 v[82:85], v[130:133], v[180:183], v[82:85]
	v_mfma_f32_16x16x32_bf16 v[74:77], v[138:141], v[180:183], v[74:77]
	v_mfma_f32_16x16x32_bf16 v[126:129], v[134:137], v[160:163], v[126:129]
	v_mfma_f32_16x16x32_bf16 v[122:125], v[142:145], v[160:163], v[122:125]
	v_mfma_f32_16x16x32_bf16 v[114:117], v[134:137], v[168:171], v[114:117]
	v_mfma_f32_16x16x32_bf16 v[106:109], v[142:145], v[168:171], v[106:109]
	v_mfma_f32_16x16x32_bf16 v[98:101], v[134:137], v[176:179], v[98:101]
	v_mfma_f32_16x16x32_bf16 v[90:93], v[142:145], v[176:179], v[90:93]
	v_mfma_f32_16x16x32_bf16 v[82:85], v[134:137], v[184:187], v[82:85]
	v_mfma_f32_16x16x32_bf16 v[74:77], v[142:145], v[184:187], v[74:77]
	s_setprio 0
	s_barrier
	s_add_i32 s22, 0, 0x1c000
	s_add_i32 s16, s47, s25
	s_add_u32 s52, s20, s66
	s_addc_u32 s53, s21, s67
	s_mov_b32 m0, s16
	ds_read_b128 v[188:191], v202 offset:49152
	ds_read_b128 v[198:201], v202 offset:50176
	ds_read_b128 v[208:211], v202 offset:51200
	ds_read_b128 v[212:215], v202 offset:52224
	global_load_lds_dwordx4 v48, s[52:53]
	s_add_i32 m0, s16, 0x2000
	s_nop 0
	global_load_lds_dwordx4 v146, s[52:53]
	s_barrier
	s_waitcnt lgkmcnt(0)
	s_setprio 1
	s_waitcnt lgkmcnt(0)
	v_mfma_f32_16x16x32_bf16 v[118:121], v[188:191], v[156:159], v[118:121]
	v_mfma_f32_16x16x32_bf16 v[110:113], v[208:211], v[156:159], v[110:113]
	v_mfma_f32_16x16x32_bf16 v[102:105], v[188:191], v[164:167], v[102:105]
	v_mfma_f32_16x16x32_bf16 v[94:97], v[208:211], v[164:167], v[94:97]
	v_mfma_f32_16x16x32_bf16 v[86:89], v[188:191], v[172:175], v[86:89]
	v_mfma_f32_16x16x32_bf16 v[78:81], v[208:211], v[172:175], v[78:81]
	v_mfma_f32_16x16x32_bf16 v[70:73], v[188:191], v[180:183], v[70:73]
	v_mfma_f32_16x16x32_bf16 v[66:69], v[208:211], v[180:183], v[66:69]
	v_mfma_f32_16x16x32_bf16 v[118:121], v[198:201], v[160:163], v[118:121]
	v_mfma_f32_16x16x32_bf16 v[110:113], v[212:215], v[160:163], v[110:113]
	v_mfma_f32_16x16x32_bf16 v[102:105], v[198:201], v[168:171], v[102:105]
	v_mfma_f32_16x16x32_bf16 v[94:97], v[212:215], v[168:171], v[94:97]
	v_mfma_f32_16x16x32_bf16 v[86:89], v[198:201], v[176:179], v[86:89]
	v_mfma_f32_16x16x32_bf16 v[78:81], v[212:215], v[176:179], v[78:81]
	v_mfma_f32_16x16x32_bf16 v[70:73], v[198:201], v[184:187], v[70:73]
	v_mfma_f32_16x16x32_bf16 v[66:69], v[212:215], v[184:187], v[66:69]
	s_setprio 0
	s_mov_b32 m0, s39
	v_lshl_add_u64 v[192:193], v[216:217], 0, s[66:67]
	s_barrier
	ds_read_b128 v[156:159], v206 offset:49152
	ds_read_b128 v[160:163], v206 offset:50176
	ds_read_b128 v[164:167], v206 offset:51200
	ds_read_b128 v[168:171], v206 offset:52224
	ds_read_b128 v[172:175], v206 offset:53248
	ds_read_b128 v[176:179], v206 offset:54272
	ds_read_b128 v[180:183], v206 offset:55296
	ds_read_b128 v[184:187], v206 offset:56320
	global_load_lds_dwordx4 v[192:193], off
	v_lshl_add_u64 v[192:193], v[218:219], 0, s[66:67]
	s_mov_b32 m0, s40
	s_nop 0
	global_load_lds_dwordx4 v[192:193], off
	s_barrier
	s_waitcnt lgkmcnt(0)
	s_setprio 1
	s_waitcnt lgkmcnt(0)
	v_mfma_f32_16x16x32_bf16 v[62:65], v[130:133], v[156:159], v[62:65]
	v_mfma_f32_16x16x32_bf16 v[58:61], v[138:141], v[156:159], v[58:61]
	v_mfma_f32_16x16x32_bf16 v[50:53], v[130:133], v[164:167], v[50:53]
	v_mfma_f32_16x16x32_bf16 v[40:43], v[138:141], v[164:167], v[40:43]
	v_mfma_f32_16x16x32_bf16 v[32:35], v[130:133], v[172:175], v[32:35]
	v_mfma_f32_16x16x32_bf16 v[24:27], v[138:141], v[172:175], v[24:27]
	v_mfma_f32_16x16x32_bf16 v[16:19], v[130:133], v[180:183], v[16:19]
	v_mfma_f32_16x16x32_bf16 v[8:11], v[138:141], v[180:183], v[8:11]
	v_mfma_f32_16x16x32_bf16 v[62:65], v[134:137], v[160:163], v[62:65]
	v_mfma_f32_16x16x32_bf16 v[58:61], v[142:145], v[160:163], v[58:61]
	v_mfma_f32_16x16x32_bf16 v[50:53], v[134:137], v[168:171], v[50:53]
	v_mfma_f32_16x16x32_bf16 v[40:43], v[142:145], v[168:171], v[40:43]
	v_mfma_f32_16x16x32_bf16 v[32:35], v[134:137], v[176:179], v[32:35]
	v_mfma_f32_16x16x32_bf16 v[24:27], v[142:145], v[176:179], v[24:27]
	v_mfma_f32_16x16x32_bf16 v[16:19], v[134:137], v[184:187], v[16:19]
	v_mfma_f32_16x16x32_bf16 v[8:11], v[142:145], v[184:187], v[8:11]
	s_setprio 0
	s_barrier
	s_add_u32 s16, s20, 0xb0080
	s_addc_u32 s17, s21, 0
	s_add_i32 s20, s22, s25
	s_mov_b32 m0, s20
	s_nop 0
	global_load_lds_dwordx4 v48, s[16:17]
	s_add_i32 m0, s20, 0x2000
	s_nop 0
	global_load_lds_dwordx4 v146, s[16:17]
	s_waitcnt vmcnt(6)
	s_barrier
	s_setprio 1
	v_mfma_f32_16x16x32_bf16 v[54:57], v[188:191], v[156:159], v[54:57]
	v_mfma_f32_16x16x32_bf16 v[44:47], v[208:211], v[156:159], v[44:47]
	v_mfma_f32_16x16x32_bf16 v[36:39], v[188:191], v[164:167], v[36:39]
	v_mfma_f32_16x16x32_bf16 v[28:31], v[208:211], v[164:167], v[28:31]
	v_mfma_f32_16x16x32_bf16 v[20:23], v[188:191], v[172:175], v[20:23]
	v_mfma_f32_16x16x32_bf16 v[12:15], v[208:211], v[172:175], v[12:15]
	v_mfma_f32_16x16x32_bf16 v[4:7], v[188:191], v[180:183], v[4:7]
	v_mfma_f32_16x16x32_bf16 v[0:3], v[208:211], v[180:183], v[0:3]
	v_mfma_f32_16x16x32_bf16 v[54:57], v[198:201], v[160:163], v[54:57]
	v_mfma_f32_16x16x32_bf16 v[44:47], v[212:215], v[160:163], v[44:47]
	v_mfma_f32_16x16x32_bf16 v[36:39], v[198:201], v[168:171], v[36:39]
	v_mfma_f32_16x16x32_bf16 v[28:31], v[212:215], v[168:171], v[28:31]
	v_mfma_f32_16x16x32_bf16 v[20:23], v[198:201], v[176:179], v[20:23]
	v_mfma_f32_16x16x32_bf16 v[12:15], v[212:215], v[176:179], v[12:15]
	v_mfma_f32_16x16x32_bf16 v[4:7], v[198:201], v[184:187], v[4:7]
	v_mfma_f32_16x16x32_bf16 v[0:3], v[212:215], v[184:187], v[0:3]
	s_setprio 0
	s_add_i32 s46, s46, 2
	s_add_u32 s44, s44, 0x100
	s_addc_u32 s45, s45, 0
	s_cmp_gt_u32 s46, 41
	s_mov_b64 s[16:17], s[18:19]
	s_barrier
	s_cbranch_scc0 .LBB0_1421
	s_mul_hi_i32 s16, s14, 0x38e38e39
	s_lshr_b32 s17, s16, 31
	s_ashr_i32 s16, s16, 1
	s_add_i32 s16, s16, s17
	s_mul_i32 s17, s16, -9
	v_lshl_or_b32 v156, s15, 8, v205
	s_ashr_i32 s15, s14, 31
	s_add_i32 s18, s17, s14
	s_lshl_b64 s[14:15], s[14:15], 19
	s_ashr_i32 s17, s16, 31
	v_lshl_add_u64 v[158:159], v[150:151], 0, s[14:15]
	v_sub_co_u32_e64 v130, s[14:15], s18, 1
	s_lshl_b64 s[18:19], s[16:17], 23
	s_and_b64 s[14:15], s[14:15], exec
	v_ashrrev_i32_e32 v131, 31, v130
	s_cselect_b32 s14, 32, s16
	v_lshlrev_b64 v[130:131], 20, v[130:131]
	s_mul_hi_i32 s15, s14, 0x6000
	s_mulk_i32 s14, 0x6000
	v_ashrrev_i32_e32 v157, 31, v156
	v_lshl_add_u64 v[130:131], s[6:7], 0, v[130:131]
	s_add_u32 s14, s37, s14
	v_lshl_add_u64 v[130:131], v[130:131], 0, s[18:19]
	s_addc_u32 s15, s38, s15
	v_lshlrev_b64 v[208:209], 2, v[156:157]
	v_lshl_add_u64 v[162:163], v[130:131], 0, v[148:149]
	v_lshl_add_u64 v[130:131], s[14:15], 0, v[208:209]
	v_lshl_add_u64 v[156:157], v[156:157], 1, v[158:159]
	global_load_dwordx4 v[142:145], v[130:131], off
	global_load_dwordx4 v[138:141], v[130:131], off offset:64
	global_load_dwordx4 v[134:137], v[130:131], off offset:512
	s_nop 0
	global_load_dwordx4 v[130:133], v[130:131], off offset:576
	s_nop 0
	s_mov_b32 s14, 0x40000
	s_nop 0
	v_lshl_add_u64 v[162:163], v[162:163], 0, v[208:209]
	s_nop 0
	s_mov_b32 s15, s42
	s_nop 0
	s_mov_b32 s14, 0x48000
	s_nop 0
	s_mov_b32 s14, 0x50000
	s_nop 0
	s_mov_b32 s14, 0x58000
	s_nop 0
	s_mov_b32 s14, 0x20000
	s_nop 0
	s_nop 0
	s_mov_b64 s[18:19], s[12:13]
	s_mov_b64 s[16:17], s[10:11]
	v_and_b32_e32 v202, 16, v224
	v_lshrrev_b32_e32 v203, 1, v202
	v_add_u32_e32 v202, v202, v203
	v_mov_b32_e32 v203, 0
	v_mov_b32_e32 v223, 0
	v_lshl_add_u64 v[246:247], v[156:157], 0, v[202:203]
	v_mov_b32_e32 v222, 0x0
	v_lshl_add_u64 v[190:191], v[246:247], 0, v[222:223]
	global_load_dwordx4 v[198:201], v[190:191], off
	global_load_dwordx4 v[218:221], v[190:191], off offset:256
	v_mov_b32_e32 v222, 0x8000
	v_lshl_add_u64 v[190:191], v[246:247], 0, v[222:223]
	global_load_dwordx4 v[242:245], v[190:191], off
	global_load_dwordx4 v[164:167], v[190:191], off offset:256
	v_mov_b32_e32 v222, 0x10000
	v_lshl_add_u64 v[190:191], v[246:247], 0, v[222:223]
	global_load_dwordx4 v[168:171], v[190:191], off
	global_load_dwordx4 v[172:175], v[190:191], off offset:256
	v_mov_b32_e32 v222, 0x18000
	v_lshl_add_u64 v[190:191], v[246:247], 0, v[222:223]
	global_load_dwordx4 v[176:179], v[190:191], off
	global_load_dwordx4 v[180:183], v[190:191], off offset:256
	v_mov_b32_e32 v222, 0x40000
	v_lshl_add_u64 v[190:191], v[246:247], 0, v[222:223]
	global_load_dwordx4 v[184:187], v[190:191], off
	s_waitcnt vmcnt(8)
	v_permlane16_swap_b32 v198, v200
	v_permlane16_swap_b32 v199, v201
	s_nop 1
	v_lshlrev_b32_e32 v210, 16, v198
	v_and_b32_e32 v211, 0xffff0000, v198
	v_lshlrev_b32_e32 v212, 16, v199
	v_and_b32_e32 v213, 0xffff0000, v199
	v_pk_fma_f32 v[126:127], v[126:127], v[142:143], v[210:211]
	v_pk_fma_f32 v[128:129], v[128:129], v[144:145], v[212:213]
	v_lshlrev_b32_e32 v214, 16, v200
	v_and_b32_e32 v215, 0xffff0000, v200
	v_lshlrev_b32_e32 v216, 16, v201
	v_and_b32_e32 v217, 0xffff0000, v201
	v_pk_fma_f32 v[122:123], v[122:123], v[138:139], v[214:215]
	v_pk_fma_f32 v[124:125], v[124:125], v[140:141], v[216:217]
	v_mov_b32_e32 v222, 0x0
	v_lshl_add_u64 v[192:193], v[162:163], 0, v[222:223]
	global_store_dwordx4 v[192:193], v[126:129], off
	global_store_dwordx4 v[192:193], v[122:125], off offset:64
	global_load_dwordx4 v[198:201], v[190:191], off offset:256
	s_waitcnt vmcnt(10)
	v_permlane16_swap_b32 v218, v220
	v_permlane16_swap_b32 v219, v221
	s_nop 1
	v_lshlrev_b32_e32 v210, 16, v218
	v_and_b32_e32 v211, 0xffff0000, v218
	v_lshlrev_b32_e32 v212, 16, v219
	v_and_b32_e32 v213, 0xffff0000, v219
	v_pk_fma_f32 v[118:119], v[118:119], v[134:135], v[210:211]
	v_pk_fma_f32 v[120:121], v[120:121], v[136:137], v[212:213]
	v_lshlrev_b32_e32 v214, 16, v220
	v_and_b32_e32 v215, 0xffff0000, v220
	v_lshlrev_b32_e32 v216, 16, v221
	v_and_b32_e32 v217, 0xffff0000, v221
	v_pk_fma_f32 v[110:111], v[110:111], v[130:131], v[214:215]
	v_pk_fma_f32 v[112:113], v[112:113], v[132:133], v[216:217]
	v_mov_b32_e32 v222, 0x0
	v_lshl_add_u64 v[192:193], v[162:163], 0, v[222:223]
	global_store_dwordx4 v[192:193], v[118:121], off offset:512
	global_store_dwordx4 v[192:193], v[110:113], off offset:576
	v_mov_b32_e32 v222, 0x48000
	v_lshl_add_u64 v[190:191], v[246:247], 0, v[222:223]
	global_load_dwordx4 v[218:221], v[190:191], off
	s_waitcnt vmcnt(12)
	v_permlane16_swap_b32 v242, v244
	v_permlane16_swap_b32 v243, v245
	s_nop 1
	v_lshlrev_b32_e32 v210, 16, v242
	v_and_b32_e32 v211, 0xffff0000, v242
	v_lshlrev_b32_e32 v212, 16, v243
	v_and_b32_e32 v213, 0xffff0000, v243
	v_pk_fma_f32 v[114:115], v[114:115], v[142:143], v[210:211]
	v_pk_fma_f32 v[116:117], v[116:117], v[144:145], v[212:213]
	v_lshlrev_b32_e32 v214, 16, v244
	v_and_b32_e32 v215, 0xffff0000, v244
	v_lshlrev_b32_e32 v216, 16, v245
	v_and_b32_e32 v217, 0xffff0000, v245
	v_pk_fma_f32 v[106:107], v[106:107], v[138:139], v[214:215]
	v_pk_fma_f32 v[108:109], v[108:109], v[140:141], v[216:217]
	v_mov_b32_e32 v222, 0x10000
	v_lshl_add_u64 v[192:193], v[162:163], 0, v[222:223]
	global_store_dwordx4 v[192:193], v[114:117], off
	global_store_dwordx4 v[192:193], v[106:109], off offset:64
	global_load_dwordx4 v[242:245], v[190:191], off offset:256
	s_waitcnt vmcnt(14)
	v_permlane16_swap_b32 v164, v166
	v_permlane16_swap_b32 v165, v167
	s_nop 1
	v_lshlrev_b32_e32 v210, 16, v164
	v_and_b32_e32 v211, 0xffff0000, v164
	v_lshlrev_b32_e32 v212, 16, v165
	v_and_b32_e32 v213, 0xffff0000, v165
	v_pk_fma_f32 v[102:103], v[102:103], v[134:135], v[210:211]
	v_pk_fma_f32 v[104:105], v[104:105], v[136:137], v[212:213]
	v_lshlrev_b32_e32 v214, 16, v166
	v_and_b32_e32 v215, 0xffff0000, v166
	v_lshlrev_b32_e32 v216, 16, v167
	v_and_b32_e32 v217, 0xffff0000, v167
	v_pk_fma_f32 v[94:95], v[94:95], v[130:131], v[214:215]
	v_pk_fma_f32 v[96:97], v[96:97], v[132:133], v[216:217]
	v_mov_b32_e32 v222, 0x10000
	v_lshl_add_u64 v[192:193], v[162:163], 0, v[222:223]
	global_store_dwordx4 v[192:193], v[102:105], off offset:512
	global_store_dwordx4 v[192:193], v[94:97], off offset:576
	v_mov_b32_e32 v222, 0x50000
	v_lshl_add_u64 v[190:191], v[246:247], 0, v[222:223]
	global_load_dwordx4 v[164:167], v[190:191], off
	s_waitcnt vmcnt(16)
	v_permlane16_swap_b32 v168, v170
	v_permlane16_swap_b32 v169, v171
	s_nop 1
	v_lshlrev_b32_e32 v210, 16, v168
	v_and_b32_e32 v211, 0xffff0000, v168
	v_lshlrev_b32_e32 v212, 16, v169
	v_and_b32_e32 v213, 0xffff0000, v169
	v_pk_fma_f32 v[98:99], v[98:99], v[142:143], v[210:211]
	v_pk_fma_f32 v[100:101], v[100:101], v[144:145], v[212:213]
	v_lshlrev_b32_e32 v214, 16, v170
	v_and_b32_e32 v215, 0xffff0000, v170
	v_lshlrev_b32_e32 v216, 16, v171
	v_and_b32_e32 v217, 0xffff0000, v171
	v_pk_fma_f32 v[90:91], v[90:91], v[138:139], v[214:215]
	v_pk_fma_f32 v[92:93], v[92:93], v[140:141], v[216:217]
	v_mov_b32_e32 v222, 0x20000
	v_lshl_add_u64 v[192:193], v[162:163], 0, v[222:223]
	global_store_dwordx4 v[192:193], v[98:101], off
	global_store_dwordx4 v[192:193], v[90:93], off offset:64
	global_load_dwordx4 v[168:171], v[190:191], off offset:256
	s_waitcnt vmcnt(18)
	v_permlane16_swap_b32 v172, v174
	v_permlane16_swap_b32 v173, v175
	s_nop 1
	v_lshlrev_b32_e32 v210, 16, v172
	v_and_b32_e32 v211, 0xffff0000, v172
	v_lshlrev_b32_e32 v212, 16, v173
	v_and_b32_e32 v213, 0xffff0000, v173
	v_pk_fma_f32 v[86:87], v[86:87], v[134:135], v[210:211]
	v_pk_fma_f32 v[88:89], v[88:89], v[136:137], v[212:213]
	v_lshlrev_b32_e32 v214, 16, v174
	v_and_b32_e32 v215, 0xffff0000, v174
	v_lshlrev_b32_e32 v216, 16, v175
	v_and_b32_e32 v217, 0xffff0000, v175
	v_pk_fma_f32 v[78:79], v[78:79], v[130:131], v[214:215]
	v_pk_fma_f32 v[80:81], v[80:81], v[132:133], v[216:217]
	v_mov_b32_e32 v222, 0x20000
	v_lshl_add_u64 v[192:193], v[162:163], 0, v[222:223]
	global_store_dwordx4 v[192:193], v[86:89], off offset:512
	global_store_dwordx4 v[192:193], v[78:81], off offset:576
	v_mov_b32_e32 v222, 0x58000
	v_lshl_add_u64 v[190:191], v[246:247], 0, v[222:223]
	global_load_dwordx4 v[172:175], v[190:191], off
	s_waitcnt vmcnt(20)
	v_permlane16_swap_b32 v176, v178
	v_permlane16_swap_b32 v177, v179
	s_nop 1
	v_lshlrev_b32_e32 v210, 16, v176
	v_and_b32_e32 v211, 0xffff0000, v176
	v_lshlrev_b32_e32 v212, 16, v177
	v_and_b32_e32 v213, 0xffff0000, v177
	v_pk_fma_f32 v[82:83], v[82:83], v[142:143], v[210:211]
	v_pk_fma_f32 v[84:85], v[84:85], v[144:145], v[212:213]
	v_lshlrev_b32_e32 v214, 16, v178
	v_and_b32_e32 v215, 0xffff0000, v178
	v_lshlrev_b32_e32 v216, 16, v179
	v_and_b32_e32 v217, 0xffff0000, v179
	v_pk_fma_f32 v[74:75], v[74:75], v[138:139], v[214:215]
	v_pk_fma_f32 v[76:77], v[76:77], v[140:141], v[216:217]
	v_mov_b32_e32 v222, 0x30000
	v_lshl_add_u64 v[192:193], v[162:163], 0, v[222:223]
	global_store_dwordx4 v[192:193], v[82:85], off
	global_store_dwordx4 v[192:193], v[74:77], off offset:64
	global_load_dwordx4 v[176:179], v[190:191], off offset:256
	s_waitcnt vmcnt(22)
	v_permlane16_swap_b32 v180, v182
	v_permlane16_swap_b32 v181, v183
	s_nop 1
	v_lshlrev_b32_e32 v210, 16, v180
	v_and_b32_e32 v211, 0xffff0000, v180
	v_lshlrev_b32_e32 v212, 16, v181
	v_and_b32_e32 v213, 0xffff0000, v181
	v_pk_fma_f32 v[70:71], v[70:71], v[134:135], v[210:211]
	v_pk_fma_f32 v[72:73], v[72:73], v[136:137], v[212:213]
	v_lshlrev_b32_e32 v214, 16, v182
	v_and_b32_e32 v215, 0xffff0000, v182
	v_lshlrev_b32_e32 v216, 16, v183
	v_and_b32_e32 v217, 0xffff0000, v183
	v_pk_fma_f32 v[66:67], v[66:67], v[130:131], v[214:215]
	v_pk_fma_f32 v[68:69], v[68:69], v[132:133], v[216:217]
	v_mov_b32_e32 v222, 0x30000
	v_lshl_add_u64 v[192:193], v[162:163], 0, v[222:223]
	global_store_dwordx4 v[192:193], v[70:73], off offset:512
	global_store_dwordx4 v[192:193], v[66:69], off offset:576
	s_waitcnt vmcnt(23)
	v_permlane16_swap_b32 v184, v186
	v_permlane16_swap_b32 v185, v187
	s_nop 1
	v_lshlrev_b32_e32 v210, 16, v184
	v_and_b32_e32 v211, 0xffff0000, v184
	v_lshlrev_b32_e32 v212, 16, v185
	v_and_b32_e32 v213, 0xffff0000, v185
	v_pk_fma_f32 v[62:63], v[62:63], v[142:143], v[210:211]
	v_pk_fma_f32 v[64:65], v[64:65], v[144:145], v[212:213]
	v_lshlrev_b32_e32 v214, 16, v186
	v_and_b32_e32 v215, 0xffff0000, v186
	v_lshlrev_b32_e32 v216, 16, v187
	v_and_b32_e32 v217, 0xffff0000, v187
	v_pk_fma_f32 v[58:59], v[58:59], v[138:139], v[214:215]
	v_pk_fma_f32 v[60:61], v[60:61], v[140:141], v[216:217]
	v_mov_b32_e32 v222, 0x80000
	v_lshl_add_u64 v[192:193], v[162:163], 0, v[222:223]
	global_store_dwordx4 v[192:193], v[62:65], off
	global_store_dwordx4 v[192:193], v[58:61], off offset:64
	s_waitcnt vmcnt(22)
	v_permlane16_swap_b32 v198, v200
	v_permlane16_swap_b32 v199, v201
	s_nop 1
	v_lshlrev_b32_e32 v210, 16, v198
	v_and_b32_e32 v211, 0xffff0000, v198
	v_lshlrev_b32_e32 v212, 16, v199
	v_and_b32_e32 v213, 0xffff0000, v199
	v_pk_fma_f32 v[54:55], v[54:55], v[134:135], v[210:211]
	v_pk_fma_f32 v[56:57], v[56:57], v[136:137], v[212:213]
	v_lshlrev_b32_e32 v214, 16, v200
	v_and_b32_e32 v215, 0xffff0000, v200
	v_lshlrev_b32_e32 v216, 16, v201
	v_and_b32_e32 v217, 0xffff0000, v201
	v_pk_fma_f32 v[44:45], v[44:45], v[130:131], v[214:215]
	v_pk_fma_f32 v[46:47], v[46:47], v[132:133], v[216:217]
	v_mov_b32_e32 v222, 0x80000
	v_lshl_add_u64 v[192:193], v[162:163], 0, v[222:223]
	global_store_dwordx4 v[192:193], v[54:57], off offset:512
	global_store_dwordx4 v[192:193], v[44:47], off offset:576
	s_waitcnt vmcnt(21)
	v_permlane16_swap_b32 v218, v220
	v_permlane16_swap_b32 v219, v221
	s_nop 1
	v_lshlrev_b32_e32 v210, 16, v218
	v_and_b32_e32 v211, 0xffff0000, v218
	v_lshlrev_b32_e32 v212, 16, v219
	v_and_b32_e32 v213, 0xffff0000, v219
	v_pk_fma_f32 v[50:51], v[50:51], v[142:143], v[210:211]
	v_pk_fma_f32 v[52:53], v[52:53], v[144:145], v[212:213]
	v_lshlrev_b32_e32 v214, 16, v220
	v_and_b32_e32 v215, 0xffff0000, v220
	v_lshlrev_b32_e32 v216, 16, v221
	v_and_b32_e32 v217, 0xffff0000, v221
	v_pk_fma_f32 v[40:41], v[40:41], v[138:139], v[214:215]
	v_pk_fma_f32 v[42:43], v[42:43], v[140:141], v[216:217]
	v_mov_b32_e32 v222, 0x90000
	v_lshl_add_u64 v[192:193], v[162:163], 0, v[222:223]
	global_store_dwordx4 v[192:193], v[50:53], off
	global_store_dwordx4 v[192:193], v[40:43], off offset:64
	s_waitcnt vmcnt(20)
	v_permlane16_swap_b32 v242, v244
	v_permlane16_swap_b32 v243, v245
	s_nop 1
	v_lshlrev_b32_e32 v210, 16, v242
	v_and_b32_e32 v211, 0xffff0000, v242
	v_lshlrev_b32_e32 v212, 16, v243
	v_and_b32_e32 v213, 0xffff0000, v243
	v_pk_fma_f32 v[36:37], v[36:37], v[134:135], v[210:211]
	v_pk_fma_f32 v[38:39], v[38:39], v[136:137], v[212:213]
	v_lshlrev_b32_e32 v214, 16, v244
	v_and_b32_e32 v215, 0xffff0000, v244
	v_lshlrev_b32_e32 v216, 16, v245
	v_and_b32_e32 v217, 0xffff0000, v245
	v_pk_fma_f32 v[28:29], v[28:29], v[130:131], v[214:215]
	v_pk_fma_f32 v[30:31], v[30:31], v[132:133], v[216:217]
	v_mov_b32_e32 v222, 0x90000
	v_lshl_add_u64 v[192:193], v[162:163], 0, v[222:223]
	global_store_dwordx4 v[192:193], v[36:39], off offset:512
	global_store_dwordx4 v[192:193], v[28:31], off offset:576
	s_waitcnt vmcnt(19)
	v_permlane16_swap_b32 v164, v166
	v_permlane16_swap_b32 v165, v167
	s_nop 1
	v_lshlrev_b32_e32 v210, 16, v164
	v_and_b32_e32 v211, 0xffff0000, v164
	v_lshlrev_b32_e32 v212, 16, v165
	v_and_b32_e32 v213, 0xffff0000, v165
	v_pk_fma_f32 v[32:33], v[32:33], v[142:143], v[210:211]
	v_pk_fma_f32 v[34:35], v[34:35], v[144:145], v[212:213]
	v_lshlrev_b32_e32 v214, 16, v166
	v_and_b32_e32 v215, 0xffff0000, v166
	v_lshlrev_b32_e32 v216, 16, v167
	v_and_b32_e32 v217, 0xffff0000, v167
	v_pk_fma_f32 v[24:25], v[24:25], v[138:139], v[214:215]
	v_pk_fma_f32 v[26:27], v[26:27], v[140:141], v[216:217]
	v_mov_b32_e32 v222, 0xa0000
	v_lshl_add_u64 v[192:193], v[162:163], 0, v[222:223]
	global_store_dwordx4 v[192:193], v[32:35], off
	global_store_dwordx4 v[192:193], v[24:27], off offset:64
	s_waitcnt vmcnt(18)
	v_permlane16_swap_b32 v168, v170
	v_permlane16_swap_b32 v169, v171
	s_nop 1
	v_lshlrev_b32_e32 v210, 16, v168
	v_and_b32_e32 v211, 0xffff0000, v168
	v_lshlrev_b32_e32 v212, 16, v169
	v_and_b32_e32 v213, 0xffff0000, v169
	v_pk_fma_f32 v[20:21], v[20:21], v[134:135], v[210:211]
	v_pk_fma_f32 v[22:23], v[22:23], v[136:137], v[212:213]
	v_lshlrev_b32_e32 v214, 16, v170
	v_and_b32_e32 v215, 0xffff0000, v170
	v_lshlrev_b32_e32 v216, 16, v171
	v_and_b32_e32 v217, 0xffff0000, v171
	v_pk_fma_f32 v[12:13], v[12:13], v[130:131], v[214:215]
	v_pk_fma_f32 v[14:15], v[14:15], v[132:133], v[216:217]
	v_mov_b32_e32 v222, 0xa0000
	v_lshl_add_u64 v[192:193], v[162:163], 0, v[222:223]
	global_store_dwordx4 v[192:193], v[20:23], off offset:512
	global_store_dwordx4 v[192:193], v[12:15], off offset:576
	s_waitcnt vmcnt(17)
	v_permlane16_swap_b32 v172, v174
	v_permlane16_swap_b32 v173, v175
	s_nop 1
	v_lshlrev_b32_e32 v210, 16, v172
	v_and_b32_e32 v211, 0xffff0000, v172
	v_lshlrev_b32_e32 v212, 16, v173
	v_and_b32_e32 v213, 0xffff0000, v173
	v_pk_fma_f32 v[16:17], v[16:17], v[142:143], v[210:211]
	v_pk_fma_f32 v[18:19], v[18:19], v[144:145], v[212:213]
	v_lshlrev_b32_e32 v214, 16, v174
	v_and_b32_e32 v215, 0xffff0000, v174
	v_lshlrev_b32_e32 v216, 16, v175
	v_and_b32_e32 v217, 0xffff0000, v175
	v_pk_fma_f32 v[8:9], v[8:9], v[138:139], v[214:215]
	v_pk_fma_f32 v[10:11], v[10:11], v[140:141], v[216:217]
	v_mov_b32_e32 v222, 0xb0000
	v_lshl_add_u64 v[192:193], v[162:163], 0, v[222:223]
	global_store_dwordx4 v[192:193], v[16:19], off
	global_store_dwordx4 v[192:193], v[8:11], off offset:64
	s_waitcnt vmcnt(16)
	v_permlane16_swap_b32 v176, v178
	v_permlane16_swap_b32 v177, v179
	s_nop 1
	v_lshlrev_b32_e32 v210, 16, v176
	v_and_b32_e32 v211, 0xffff0000, v176
	v_lshlrev_b32_e32 v212, 16, v177
	v_and_b32_e32 v213, 0xffff0000, v177
	v_pk_fma_f32 v[4:5], v[4:5], v[134:135], v[210:211]
	v_pk_fma_f32 v[6:7], v[6:7], v[136:137], v[212:213]
	v_lshlrev_b32_e32 v214, 16, v178
	v_and_b32_e32 v215, 0xffff0000, v178
	v_lshlrev_b32_e32 v216, 16, v179
	v_and_b32_e32 v217, 0xffff0000, v179
	v_pk_fma_f32 v[0:1], v[0:1], v[130:131], v[214:215]
	v_pk_fma_f32 v[2:3], v[2:3], v[132:133], v[216:217]
	v_mov_b32_e32 v222, 0xb0000
	v_lshl_add_u64 v[192:193], v[162:163], 0, v[222:223]
	global_store_dwordx4 v[192:193], v[4:7], off offset:512
	global_store_dwordx4 v[192:193], v[0:3], off offset:576
	s_mov_b32 s14, 0x30000
	s_mov_b32 s14, 0x80000
	s_mov_b32 s14, 0x90000
	s_mov_b32 s14, 0xa0000
	s_mov_b32 s14, 0xb0000
	s_and_b64 vcc, exec, s[0:1]
	s_mov_b32 s14, s43
	s_cbranch_vccz .LBB0_1418
	s_waitcnt vmcnt(0)
	s_cmpk_gt_u32 s24, 0xff
	s_cbranch_scc1 .LBB0_1425
	s_barrier

.LBB0_1435:
	ds_read_b128 v[130:133], v214
	ds_read_b128 v[134:137], v214 offset:1024
	ds_read_b128 v[138:141], v214 offset:2048
	ds_read_b128 v[142:145], v214 offset:3072
	s_add_u32 s20, s18, 0x100
	s_addc_u32 s21, s19, 0
	s_add_i32 s47, 0, 0x10000
	s_cmp_eq_u32 s46, 40
	s_cselect_b32 s25, s13, s21
	s_cselect_b32 s24, s12, s20
	s_cselect_b32 s23, s15, s45
	s_cselect_b32 s22, s14, s44
	v_lshl_add_u64 v[186:187], s[18:19], 0, v[150:151]
	s_add_i32 m0, s31, 0xc000
	ds_read_b128 v[154:157], v244
	ds_read_b128 v[158:161], v244 offset:1024
	ds_read_b128 v[162:165], v244 offset:2048
	ds_read_b128 v[166:169], v244 offset:3072
	ds_read_b128 v[170:173], v244 offset:4096
	ds_read_b128 v[174:177], v244 offset:5120
	ds_read_b128 v[178:181], v244 offset:6144
	ds_read_b128 v[182:185], v244 offset:7168
	global_load_lds_dwordx4 v[186:187], off
	v_lshl_add_u64 v[186:187], s[18:19], 0, v[152:153]
	s_add_i32 m0, s31, 0xe000
	s_nop 0
	global_load_lds_dwordx4 v[186:187], off
	s_waitcnt lgkmcnt(8)
	s_barrier
	s_waitcnt lgkmcnt(0)
	s_setprio 1
	s_waitcnt lgkmcnt(0)
	v_mfma_f32_16x16x32_bf16 v[126:129], v[130:133], v[154:157], v[126:129]
	v_mfma_f32_16x16x32_bf16 v[122:125], v[138:141], v[154:157], v[122:125]
	v_mfma_f32_16x16x32_bf16 v[114:117], v[130:133], v[162:165], v[114:117]
	v_mfma_f32_16x16x32_bf16 v[106:109], v[138:141], v[162:165], v[106:109]
	v_mfma_f32_16x16x32_bf16 v[98:101], v[130:133], v[170:173], v[98:101]
	v_mfma_f32_16x16x32_bf16 v[90:93], v[138:141], v[170:173], v[90:93]
	v_mfma_f32_16x16x32_bf16 v[82:85], v[130:133], v[178:181], v[82:85]
	v_mfma_f32_16x16x32_bf16 v[74:77], v[138:141], v[178:181], v[74:77]
	v_mfma_f32_16x16x32_bf16 v[126:129], v[134:137], v[158:161], v[126:129]
	v_mfma_f32_16x16x32_bf16 v[122:125], v[142:145], v[158:161], v[122:125]
	v_mfma_f32_16x16x32_bf16 v[114:117], v[134:137], v[166:169], v[114:117]
	v_mfma_f32_16x16x32_bf16 v[106:109], v[142:145], v[166:169], v[106:109]
	v_mfma_f32_16x16x32_bf16 v[98:101], v[134:137], v[174:177], v[98:101]
	v_mfma_f32_16x16x32_bf16 v[90:93], v[142:145], v[174:177], v[90:93]
	v_mfma_f32_16x16x32_bf16 v[82:85], v[134:137], v[182:185], v[82:85]
	v_mfma_f32_16x16x32_bf16 v[74:77], v[142:145], v[182:185], v[74:77]
	s_setprio 0
	s_barrier
	s_add_i32 s48, 0, 0x14000
	s_add_i32 s18, s47, s30
	s_mov_b32 m0, s18
	ds_read_b128 v[186:189], v214 offset:16384
	ds_read_b128 v[190:193], v214 offset:17408
	ds_read_b128 v[198:201], v214 offset:18432
	ds_read_b128 v[202:205], v214 offset:19456
	global_load_lds_dwordx4 v48, s[22:23]
	v_lshl_add_u64 v[208:209], s[22:23], 0, v[146:147]
	s_add_i32 m0, s18, 0x2000
	s_nop 0
	global_load_lds_dwordx4 v[208:209], off
	s_barrier
	s_waitcnt lgkmcnt(0)
	s_setprio 1
	s_waitcnt lgkmcnt(0)
	v_mfma_f32_16x16x32_bf16 v[118:121], v[186:189], v[154:157], v[118:121]
	v_mfma_f32_16x16x32_bf16 v[110:113], v[198:201], v[154:157], v[110:113]
	v_mfma_f32_16x16x32_bf16 v[102:105], v[186:189], v[162:165], v[102:105]
	v_mfma_f32_16x16x32_bf16 v[94:97], v[198:201], v[162:165], v[94:97]
	v_mfma_f32_16x16x32_bf16 v[86:89], v[186:189], v[170:173], v[86:89]
	v_mfma_f32_16x16x32_bf16 v[78:81], v[198:201], v[170:173], v[78:81]
	v_mfma_f32_16x16x32_bf16 v[70:73], v[186:189], v[178:181], v[70:73]
	v_mfma_f32_16x16x32_bf16 v[66:69], v[198:201], v[178:181], v[66:69]
	v_mfma_f32_16x16x32_bf16 v[118:121], v[190:193], v[158:161], v[118:121]
	v_mfma_f32_16x16x32_bf16 v[110:113], v[202:205], v[158:161], v[110:113]
	v_mfma_f32_16x16x32_bf16 v[102:105], v[190:193], v[166:169], v[102:105]
	v_mfma_f32_16x16x32_bf16 v[94:97], v[202:205], v[166:169], v[94:97]
	v_mfma_f32_16x16x32_bf16 v[86:89], v[190:193], v[174:177], v[86:89]
	v_mfma_f32_16x16x32_bf16 v[78:81], v[202:205], v[174:177], v[78:81]
	v_mfma_f32_16x16x32_bf16 v[70:73], v[190:193], v[182:185], v[70:73]
	v_mfma_f32_16x16x32_bf16 v[66:69], v[202:205], v[182:185], v[66:69]
	s_setprio 0
	s_mov_b32 m0, s31
	v_lshl_add_u64 v[210:211], s[24:25], 0, v[48:49]
	s_barrier
	ds_read_b128 v[154:157], v244 offset:16384
	ds_read_b128 v[158:161], v244 offset:17408
	ds_read_b128 v[162:165], v244 offset:18432
	ds_read_b128 v[166:169], v244 offset:19456
	ds_read_b128 v[170:173], v244 offset:20480
	ds_read_b128 v[174:177], v244 offset:21504
	ds_read_b128 v[178:181], v244 offset:22528
	ds_read_b128 v[182:185], v244 offset:23552
	global_load_lds_dwordx4 v[210:211], off
	v_lshl_add_u64 v[212:213], s[24:25], 0, v[146:147]
	s_mov_b32 m0, s34
	s_nop 0
	global_load_lds_dwordx4 v[212:213], off
	s_barrier
	s_waitcnt lgkmcnt(0)
	s_setprio 1
	s_waitcnt lgkmcnt(0)
	v_mfma_f32_16x16x32_bf16 v[62:65], v[130:133], v[154:157], v[62:65]
	v_mfma_f32_16x16x32_bf16 v[58:61], v[138:141], v[154:157], v[58:61]
	v_mfma_f32_16x16x32_bf16 v[50:53], v[130:133], v[162:165], v[50:53]
	v_mfma_f32_16x16x32_bf16 v[40:43], v[138:141], v[162:165], v[40:43]
	v_mfma_f32_16x16x32_bf16 v[32:35], v[130:133], v[170:173], v[32:35]
	v_mfma_f32_16x16x32_bf16 v[24:27], v[138:141], v[170:173], v[24:27]
	v_mfma_f32_16x16x32_bf16 v[16:19], v[130:133], v[178:181], v[16:19]
	v_mfma_f32_16x16x32_bf16 v[8:11], v[138:141], v[178:181], v[8:11]
	v_mfma_f32_16x16x32_bf16 v[62:65], v[134:137], v[158:161], v[62:65]
	v_mfma_f32_16x16x32_bf16 v[58:61], v[142:145], v[158:161], v[58:61]
	v_mfma_f32_16x16x32_bf16 v[50:53], v[134:137], v[166:169], v[50:53]
	v_mfma_f32_16x16x32_bf16 v[40:43], v[142:145], v[166:169], v[40:43]
	v_mfma_f32_16x16x32_bf16 v[32:35], v[134:137], v[174:177], v[32:35]
	v_mfma_f32_16x16x32_bf16 v[24:27], v[142:145], v[174:177], v[24:27]
	v_mfma_f32_16x16x32_bf16 v[16:19], v[134:137], v[182:185], v[16:19]
	v_mfma_f32_16x16x32_bf16 v[8:11], v[142:145], v[182:185], v[8:11]
	s_setprio 0
	s_barrier
	s_add_u32 s18, s22, 0xb0000
	s_addc_u32 s19, s23, 0
	s_add_i32 s47, s48, s30
	s_mov_b32 m0, s47
	s_nop 0
	global_load_lds_dwordx4 v48, s[18:19]
	s_add_i32 m0, s47, 0x2000
	s_nop 0
	global_load_lds_dwordx4 v146, s[18:19]
	s_waitcnt vmcnt(6)
	s_barrier
	s_setprio 1
	v_mfma_f32_16x16x32_bf16 v[54:57], v[186:189], v[154:157], v[54:57]
	v_mfma_f32_16x16x32_bf16 v[44:47], v[198:201], v[154:157], v[44:47]
	v_mfma_f32_16x16x32_bf16 v[36:39], v[186:189], v[162:165], v[36:39]
	v_mfma_f32_16x16x32_bf16 v[28:31], v[198:201], v[162:165], v[28:31]
	v_mfma_f32_16x16x32_bf16 v[20:23], v[186:189], v[170:173], v[20:23]
	v_mfma_f32_16x16x32_bf16 v[12:15], v[198:201], v[170:173], v[12:15]
	v_mfma_f32_16x16x32_bf16 v[4:7], v[186:189], v[178:181], v[4:7]
	v_mfma_f32_16x16x32_bf16 v[0:3], v[198:201], v[178:181], v[0:3]
	v_mfma_f32_16x16x32_bf16 v[54:57], v[190:193], v[158:161], v[54:57]
	v_mfma_f32_16x16x32_bf16 v[44:47], v[202:205], v[158:161], v[44:47]
	v_mfma_f32_16x16x32_bf16 v[36:39], v[190:193], v[166:169], v[36:39]
	v_mfma_f32_16x16x32_bf16 v[28:31], v[202:205], v[166:169], v[28:31]
	v_mfma_f32_16x16x32_bf16 v[20:23], v[190:193], v[174:177], v[20:23]
	v_mfma_f32_16x16x32_bf16 v[12:15], v[202:205], v[174:177], v[12:15]
	v_mfma_f32_16x16x32_bf16 v[4:7], v[190:193], v[182:185], v[4:7]
	v_mfma_f32_16x16x32_bf16 v[0:3], v[202:205], v[182:185], v[0:3]
	s_setprio 0
	s_add_i32 s47, 0, 0x18000
	s_barrier
	ds_read_b128 v[130:133], v214 offset:32768
	ds_read_b128 v[134:137], v214 offset:33792
	ds_read_b128 v[138:141], v214 offset:34816
	ds_read_b128 v[142:145], v214 offset:35840
	s_add_u32 s18, s24, 0xb0000
	s_addc_u32 s19, s25, 0
	s_mov_b32 m0, s35
	ds_read_b128 v[154:157], v244 offset:32768
	ds_read_b128 v[158:161], v244 offset:33792
	ds_read_b128 v[162:165], v244 offset:34816
	ds_read_b128 v[166:169], v244 offset:35840
	ds_read_b128 v[170:173], v244 offset:36864
	ds_read_b128 v[174:177], v244 offset:37888
	ds_read_b128 v[178:181], v244 offset:38912
	ds_read_b128 v[182:185], v244 offset:39936
	global_load_lds_dwordx4 v48, s[18:19]
	s_mov_b32 m0, s36
	s_nop 0
	global_load_lds_dwordx4 v146, s[18:19]
	s_waitcnt lgkmcnt(8)
	s_barrier
	s_waitcnt lgkmcnt(0)
	s_setprio 1
	s_waitcnt lgkmcnt(0)
	v_mfma_f32_16x16x32_bf16 v[126:129], v[130:133], v[154:157], v[126:129]
	v_mfma_f32_16x16x32_bf16 v[122:125], v[138:141], v[154:157], v[122:125]
	v_mfma_f32_16x16x32_bf16 v[114:117], v[130:133], v[162:165], v[114:117]
	v_mfma_f32_16x16x32_bf16 v[106:109], v[138:141], v[162:165], v[106:109]
	v_mfma_f32_16x16x32_bf16 v[98:101], v[130:133], v[170:173], v[98:101]
	v_mfma_f32_16x16x32_bf16 v[90:93], v[138:141], v[170:173], v[90:93]
	v_mfma_f32_16x16x32_bf16 v[82:85], v[130:133], v[178:181], v[82:85]
	v_mfma_f32_16x16x32_bf16 v[74:77], v[138:141], v[178:181], v[74:77]
	v_mfma_f32_16x16x32_bf16 v[126:129], v[134:137], v[158:161], v[126:129]
	v_mfma_f32_16x16x32_bf16 v[122:125], v[142:145], v[158:161], v[122:125]
	v_mfma_f32_16x16x32_bf16 v[114:117], v[134:137], v[166:169], v[114:117]
	v_mfma_f32_16x16x32_bf16 v[106:109], v[142:145], v[166:169], v[106:109]
	v_mfma_f32_16x16x32_bf16 v[98:101], v[134:137], v[174:177], v[98:101]
	v_mfma_f32_16x16x32_bf16 v[90:93], v[142:145], v[174:177], v[90:93]
	v_mfma_f32_16x16x32_bf16 v[82:85], v[134:137], v[182:185], v[82:85]
	v_mfma_f32_16x16x32_bf16 v[74:77], v[142:145], v[182:185], v[74:77]
	s_setprio 0
	s_barrier
	s_add_i32 s24, 0, 0x1c000
	s_add_i32 s18, s47, s30
	s_add_u32 s52, s22, s66
	s_addc_u32 s53, s23, s67
	s_mov_b32 m0, s18
	ds_read_b128 v[186:189], v214 offset:49152
	ds_read_b128 v[190:193], v214 offset:50176
	ds_read_b128 v[198:201], v214 offset:51200
	ds_read_b128 v[202:205], v214 offset:52224
	global_load_lds_dwordx4 v48, s[52:53]
	s_add_i32 m0, s18, 0x2000
	s_nop 0
	global_load_lds_dwordx4 v146, s[52:53]
	s_barrier
	s_waitcnt lgkmcnt(0)
	s_setprio 1
	s_waitcnt lgkmcnt(0)
	v_mfma_f32_16x16x32_bf16 v[118:121], v[186:189], v[154:157], v[118:121]
	v_mfma_f32_16x16x32_bf16 v[110:113], v[198:201], v[154:157], v[110:113]
	v_mfma_f32_16x16x32_bf16 v[102:105], v[186:189], v[162:165], v[102:105]
	v_mfma_f32_16x16x32_bf16 v[94:97], v[198:201], v[162:165], v[94:97]
	v_mfma_f32_16x16x32_bf16 v[86:89], v[186:189], v[170:173], v[86:89]
	v_mfma_f32_16x16x32_bf16 v[78:81], v[198:201], v[170:173], v[78:81]
	v_mfma_f32_16x16x32_bf16 v[70:73], v[186:189], v[178:181], v[70:73]
	v_mfma_f32_16x16x32_bf16 v[66:69], v[198:201], v[178:181], v[66:69]
	v_mfma_f32_16x16x32_bf16 v[118:121], v[190:193], v[158:161], v[118:121]
	v_mfma_f32_16x16x32_bf16 v[110:113], v[202:205], v[158:161], v[110:113]
	v_mfma_f32_16x16x32_bf16 v[102:105], v[190:193], v[166:169], v[102:105]
	v_mfma_f32_16x16x32_bf16 v[94:97], v[202:205], v[166:169], v[94:97]
	v_mfma_f32_16x16x32_bf16 v[86:89], v[190:193], v[174:177], v[86:89]
	v_mfma_f32_16x16x32_bf16 v[78:81], v[202:205], v[174:177], v[78:81]
	v_mfma_f32_16x16x32_bf16 v[70:73], v[190:193], v[182:185], v[70:73]
	v_mfma_f32_16x16x32_bf16 v[66:69], v[202:205], v[182:185], v[66:69]
	s_setprio 0
	s_mov_b32 m0, s39
	v_lshl_add_u64 v[206:207], v[210:211], 0, s[66:67]
	s_barrier
	ds_read_b128 v[154:157], v244 offset:49152
	ds_read_b128 v[158:161], v244 offset:50176
	ds_read_b128 v[162:165], v244 offset:51200
	ds_read_b128 v[166:169], v244 offset:52224
	ds_read_b128 v[170:173], v244 offset:53248
	ds_read_b128 v[174:177], v244 offset:54272
	ds_read_b128 v[178:181], v244 offset:55296
	ds_read_b128 v[182:185], v244 offset:56320
	global_load_lds_dwordx4 v[206:207], off
	v_lshl_add_u64 v[206:207], v[212:213], 0, s[66:67]
	s_mov_b32 m0, s40
	s_nop 0
	global_load_lds_dwordx4 v[206:207], off
	s_barrier
	s_waitcnt lgkmcnt(0)
	s_setprio 1
	s_waitcnt lgkmcnt(0)
	v_mfma_f32_16x16x32_bf16 v[62:65], v[130:133], v[154:157], v[62:65]
	v_mfma_f32_16x16x32_bf16 v[58:61], v[138:141], v[154:157], v[58:61]
	v_mfma_f32_16x16x32_bf16 v[50:53], v[130:133], v[162:165], v[50:53]
	v_mfma_f32_16x16x32_bf16 v[40:43], v[138:141], v[162:165], v[40:43]
	v_mfma_f32_16x16x32_bf16 v[32:35], v[130:133], v[170:173], v[32:35]
	v_mfma_f32_16x16x32_bf16 v[24:27], v[138:141], v[170:173], v[24:27]
	v_mfma_f32_16x16x32_bf16 v[16:19], v[130:133], v[178:181], v[16:19]
	v_mfma_f32_16x16x32_bf16 v[8:11], v[138:141], v[178:181], v[8:11]
	v_mfma_f32_16x16x32_bf16 v[62:65], v[134:137], v[158:161], v[62:65]
	v_mfma_f32_16x16x32_bf16 v[58:61], v[142:145], v[158:161], v[58:61]
	v_mfma_f32_16x16x32_bf16 v[50:53], v[134:137], v[166:169], v[50:53]
	v_mfma_f32_16x16x32_bf16 v[40:43], v[142:145], v[166:169], v[40:43]
	v_mfma_f32_16x16x32_bf16 v[32:35], v[134:137], v[174:177], v[32:35]
	v_mfma_f32_16x16x32_bf16 v[24:27], v[142:145], v[174:177], v[24:27]
	v_mfma_f32_16x16x32_bf16 v[16:19], v[134:137], v[182:185], v[16:19]
	v_mfma_f32_16x16x32_bf16 v[8:11], v[142:145], v[182:185], v[8:11]
	s_setprio 0
	s_barrier
	s_add_u32 s18, s22, 0xb0080
	s_addc_u32 s19, s23, 0
	s_add_i32 s22, s24, s30
	s_mov_b32 m0, s22
	s_nop 0
	global_load_lds_dwordx4 v48, s[18:19]
	s_add_i32 m0, s22, 0x2000
	s_nop 0
	global_load_lds_dwordx4 v146, s[18:19]
	s_waitcnt vmcnt(6)
	s_barrier
	s_setprio 1
	v_mfma_f32_16x16x32_bf16 v[54:57], v[186:189], v[154:157], v[54:57]
	v_mfma_f32_16x16x32_bf16 v[44:47], v[198:201], v[154:157], v[44:47]
	v_mfma_f32_16x16x32_bf16 v[36:39], v[186:189], v[162:165], v[36:39]
	v_mfma_f32_16x16x32_bf16 v[28:31], v[198:201], v[162:165], v[28:31]
	v_mfma_f32_16x16x32_bf16 v[20:23], v[186:189], v[170:173], v[20:23]
	v_mfma_f32_16x16x32_bf16 v[12:15], v[198:201], v[170:173], v[12:15]
	v_mfma_f32_16x16x32_bf16 v[4:7], v[186:189], v[178:181], v[4:7]
	v_mfma_f32_16x16x32_bf16 v[0:3], v[198:201], v[178:181], v[0:3]
	v_mfma_f32_16x16x32_bf16 v[54:57], v[190:193], v[158:161], v[54:57]
	v_mfma_f32_16x16x32_bf16 v[44:47], v[202:205], v[158:161], v[44:47]
	v_mfma_f32_16x16x32_bf16 v[36:39], v[190:193], v[166:169], v[36:39]
	v_mfma_f32_16x16x32_bf16 v[28:31], v[202:205], v[166:169], v[28:31]
	v_mfma_f32_16x16x32_bf16 v[20:23], v[190:193], v[174:177], v[20:23]
	v_mfma_f32_16x16x32_bf16 v[12:15], v[202:205], v[174:177], v[12:15]
	v_mfma_f32_16x16x32_bf16 v[4:7], v[190:193], v[182:185], v[4:7]
	v_mfma_f32_16x16x32_bf16 v[0:3], v[202:205], v[182:185], v[0:3]
	s_setprio 0
	s_add_i32 s46, s46, 2
	s_add_u32 s44, s44, 0x100
	s_addc_u32 s45, s45, 0
	s_cmp_gt_u32 s46, 41
	s_mov_b64 s[18:19], s[20:21]
	s_barrier
	s_cbranch_scc0 .LBB0_1435
	s_mul_hi_i32 s18, s16, 0x38e38e39
	s_lshr_b32 s19, s18, 31
	s_ashr_i32 s18, s18, 1
	s_add_i32 s18, s18, s19
	s_mul_i32 s19, s18, -9
	v_lshl_or_b32 v154, s17, 8, v243
	s_sub_i32 s17, 0, s16
	s_cmp_lg_u32 s19, s17
	s_cselect_b32 s17, s18, 32
	s_mul_hi_i32 s19, s17, 0x6000
	s_mulk_i32 s17, 0x6000
	s_add_u32 s18, s37, s17
	s_addc_u32 s19, s38, s19
	s_ashr_i32 s17, s16, 31
	s_lshl_b64 s[16:17], s[16:17], 18
	v_ashrrev_i32_e32 v155, 31, v154
	v_lshl_add_u64 v[156:157], s[16:17], 0, v[148:149]
	v_lshl_add_u64 v[130:131], v[154:155], 2, s[18:19]
	v_lshl_add_u64 v[154:155], v[156:157], 0, v[154:155]
	v_lshlrev_b64 v[184:185], 1, v[154:155]
	v_lshl_add_u64 v[154:155], s[10:11], 0, v[184:185]
	global_load_dwordx4 v[142:145], v[130:131], off
	global_load_dwordx4 v[138:141], v[130:131], off offset:64
	global_load_dwordx4 v[134:137], v[130:131], off offset:512
	s_nop 0
	global_load_dwordx4 v[130:133], v[130:131], off offset:576
	s_nop 0
	s_mov_b32 s16, 0x40000
	s_nop 0
	s_mov_b32 s17, 0x48000
	s_nop 0
	s_mov_b32 s18, 0x50000
	s_nop 0
	s_mov_b32 s19, 0x58000
	s_nop 0
	v_lshl_add_u64 v[184:185], s[6:7], 0, v[184:185]
	s_nop 0
	s_mov_b64 s[20:21], s[14:15]
	s_nop 0
	v_and_b32_e32 v210, 16, v224
	v_lshrrev_b32_e32 v211, 1, v210
	v_add_u32_e32 v210, v210, v211
	v_mov_b32_e32 v211, 0
	v_mov_b32_e32 v213, 0
	v_lshl_add_u64 v[214:215], v[154:155], 0, v[210:211]
	v_lshl_add_u64 v[216:217], v[184:185], 0, v[210:211]
	v_mov_b32_e32 v212, 0x0
	v_lshl_add_u64 v[218:219], v[214:215], 0, v[212:213]
	global_load_dwordx4 v[164:167], v[218:219], off
	global_load_dwordx4 v[168:171], v[218:219], off offset:256
	v_mov_b32_e32 v212, 0x8000
	v_lshl_add_u64 v[218:219], v[214:215], 0, v[212:213]
	global_load_dwordx4 v[172:175], v[218:219], off
	global_load_dwordx4 v[176:179], v[218:219], off offset:256
	v_mov_b32_e32 v212, 0x10000
	v_lshl_add_u64 v[218:219], v[214:215], 0, v[212:213]
	global_load_dwordx4 v[180:183], v[218:219], off
	global_load_dwordx4 v[198:201], v[218:219], off offset:256
	v_mov_b32_e32 v212, 0x18000
	v_lshl_add_u64 v[218:219], v[214:215], 0, v[212:213]
	global_load_dwordx4 v[202:205], v[218:219], off
	global_load_dwordx4 v[206:209], v[218:219], off offset:256
	s_waitcnt vmcnt(7)
	v_permlane16_swap_b32 v164, v166
	v_permlane16_swap_b32 v165, v167
	s_nop 1
	v_lshlrev_b32_e32 v186, 16, v164
	v_and_b32_e32 v187, 0xffff0000, v164
	v_lshlrev_b32_e32 v188, 16, v165
	v_and_b32_e32 v189, 0xffff0000, v165
	v_pk_fma_f32 v[126:127], v[126:127], v[142:143], v[186:187]
	v_pk_fma_f32 v[128:129], v[128:129], v[144:145], v[188:189]
	v_lshlrev_b32_e32 v190, 16, v166
	v_and_b32_e32 v191, 0xffff0000, v166
	v_lshlrev_b32_e32 v192, 16, v167
	v_and_b32_e32 v193, 0xffff0000, v167
	v_pk_fma_f32 v[122:123], v[122:123], v[138:139], v[190:191]
	v_pk_fma_f32 v[124:125], v[124:125], v[140:141], v[192:193]
	v_cvt_pk_bf16_f32 v126, v126, v127
	v_cvt_pk_bf16_f32 v127, v128, v129
	v_cvt_pk_bf16_f32 v128, v122, v123
	v_cvt_pk_bf16_f32 v129, v124, v125
	s_nop 1
	v_permlane16_swap_b32 v126, v128
	v_permlane16_swap_b32 v127, v129
	v_mov_b32_e32 v212, 0x0
	v_lshl_add_u64 v[220:221], v[216:217], 0, v[212:213]
	global_store_dwordx4 v[220:221], v[126:129], off
	v_mov_b32_e32 v212, 0x40000
	v_lshl_add_u64 v[218:219], v[214:215], 0, v[212:213]
	global_load_dwordx4 v[164:167], v[218:219], off
	s_waitcnt vmcnt(8)
	v_permlane16_swap_b32 v168, v170
	v_permlane16_swap_b32 v169, v171
	s_nop 1
	v_lshlrev_b32_e32 v186, 16, v168
	v_and_b32_e32 v187, 0xffff0000, v168
	v_lshlrev_b32_e32 v188, 16, v169
	v_and_b32_e32 v189, 0xffff0000, v169
	v_pk_fma_f32 v[118:119], v[118:119], v[134:135], v[186:187]
	v_pk_fma_f32 v[120:121], v[120:121], v[136:137], v[188:189]
	v_lshlrev_b32_e32 v190, 16, v170
	v_and_b32_e32 v191, 0xffff0000, v170
	v_lshlrev_b32_e32 v192, 16, v171
	v_and_b32_e32 v193, 0xffff0000, v171
	v_pk_fma_f32 v[110:111], v[110:111], v[130:131], v[190:191]
	v_pk_fma_f32 v[112:113], v[112:113], v[132:133], v[192:193]
	v_cvt_pk_bf16_f32 v118, v118, v119
	v_cvt_pk_bf16_f32 v119, v120, v121
	v_cvt_pk_bf16_f32 v120, v110, v111
	v_cvt_pk_bf16_f32 v121, v112, v113
	s_nop 1
	v_permlane16_swap_b32 v118, v120
	v_permlane16_swap_b32 v119, v121
	v_mov_b32_e32 v212, 0x0
	v_lshl_add_u64 v[220:221], v[216:217], 0, v[212:213]
	global_store_dwordx4 v[220:221], v[118:121], off offset:256
	global_load_dwordx4 v[168:171], v[218:219], off offset:256
	s_waitcnt vmcnt(9)
	v_permlane16_swap_b32 v172, v174
	v_permlane16_swap_b32 v173, v175
	s_nop 1
	v_lshlrev_b32_e32 v186, 16, v172
	v_and_b32_e32 v187, 0xffff0000, v172
	v_lshlrev_b32_e32 v188, 16, v173
	v_and_b32_e32 v189, 0xffff0000, v173
	v_pk_fma_f32 v[114:115], v[114:115], v[142:143], v[186:187]
	v_pk_fma_f32 v[116:117], v[116:117], v[144:145], v[188:189]
	v_lshlrev_b32_e32 v190, 16, v174
	v_and_b32_e32 v191, 0xffff0000, v174
	v_lshlrev_b32_e32 v192, 16, v175
	v_and_b32_e32 v193, 0xffff0000, v175
	v_pk_fma_f32 v[106:107], v[106:107], v[138:139], v[190:191]
	v_pk_fma_f32 v[108:109], v[108:109], v[140:141], v[192:193]
	v_cvt_pk_bf16_f32 v114, v114, v115
	v_cvt_pk_bf16_f32 v115, v116, v117
	v_cvt_pk_bf16_f32 v116, v106, v107
	v_cvt_pk_bf16_f32 v117, v108, v109
	s_nop 1
	v_permlane16_swap_b32 v114, v116
	v_permlane16_swap_b32 v115, v117
	v_mov_b32_e32 v212, 0x8000
	v_lshl_add_u64 v[220:221], v[216:217], 0, v[212:213]
	global_store_dwordx4 v[220:221], v[114:117], off
	v_mov_b32_e32 v212, 0x48000
	v_lshl_add_u64 v[218:219], v[214:215], 0, v[212:213]
	global_load_dwordx4 v[172:175], v[218:219], off
	s_waitcnt vmcnt(10)
	v_permlane16_swap_b32 v176, v178
	v_permlane16_swap_b32 v177, v179
	s_nop 1
	v_lshlrev_b32_e32 v186, 16, v176
	v_and_b32_e32 v187, 0xffff0000, v176
	v_lshlrev_b32_e32 v188, 16, v177
	v_and_b32_e32 v189, 0xffff0000, v177
	v_pk_fma_f32 v[102:103], v[102:103], v[134:135], v[186:187]
	v_pk_fma_f32 v[104:105], v[104:105], v[136:137], v[188:189]
	v_lshlrev_b32_e32 v190, 16, v178
	v_and_b32_e32 v191, 0xffff0000, v178
	v_lshlrev_b32_e32 v192, 16, v179
	v_and_b32_e32 v193, 0xffff0000, v179
	v_pk_fma_f32 v[94:95], v[94:95], v[130:131], v[190:191]
	v_pk_fma_f32 v[96:97], v[96:97], v[132:133], v[192:193]
	v_cvt_pk_bf16_f32 v102, v102, v103
	v_cvt_pk_bf16_f32 v103, v104, v105
	v_cvt_pk_bf16_f32 v104, v94, v95
	v_cvt_pk_bf16_f32 v105, v96, v97
	s_nop 1
	v_permlane16_swap_b32 v102, v104
	v_permlane16_swap_b32 v103, v105
	v_mov_b32_e32 v212, 0x8000
	v_lshl_add_u64 v[220:221], v[216:217], 0, v[212:213]
	global_store_dwordx4 v[220:221], v[102:105], off offset:256
	global_load_dwordx4 v[176:179], v[218:219], off offset:256
	s_waitcnt vmcnt(11)
	v_permlane16_swap_b32 v180, v182
	v_permlane16_swap_b32 v181, v183
	s_nop 1
	v_lshlrev_b32_e32 v186, 16, v180
	v_and_b32_e32 v187, 0xffff0000, v180
	v_lshlrev_b32_e32 v188, 16, v181
	v_and_b32_e32 v189, 0xffff0000, v181
	v_pk_fma_f32 v[98:99], v[98:99], v[142:143], v[186:187]
	v_pk_fma_f32 v[100:101], v[100:101], v[144:145], v[188:189]
	v_lshlrev_b32_e32 v190, 16, v182
	v_and_b32_e32 v191, 0xffff0000, v182
	v_lshlrev_b32_e32 v192, 16, v183
	v_and_b32_e32 v193, 0xffff0000, v183
	v_pk_fma_f32 v[90:91], v[90:91], v[138:139], v[190:191]
	v_pk_fma_f32 v[92:93], v[92:93], v[140:141], v[192:193]
	v_cvt_pk_bf16_f32 v98, v98, v99
	v_cvt_pk_bf16_f32 v99, v100, v101
	v_cvt_pk_bf16_f32 v100, v90, v91
	v_cvt_pk_bf16_f32 v101, v92, v93
	s_nop 1
	v_permlane16_swap_b32 v98, v100
	v_permlane16_swap_b32 v99, v101
	v_mov_b32_e32 v212, 0x10000
	v_lshl_add_u64 v[220:221], v[216:217], 0, v[212:213]
	global_store_dwordx4 v[220:221], v[98:101], off
	v_mov_b32_e32 v212, 0x50000
	v_lshl_add_u64 v[218:219], v[214:215], 0, v[212:213]
	global_load_dwordx4 v[180:183], v[218:219], off
	s_waitcnt vmcnt(12)
	v_permlane16_swap_b32 v198, v200
	v_permlane16_swap_b32 v199, v201
	s_nop 1
	v_lshlrev_b32_e32 v186, 16, v198
	v_and_b32_e32 v187, 0xffff0000, v198
	v_lshlrev_b32_e32 v188, 16, v199
	v_and_b32_e32 v189, 0xffff0000, v199
	v_pk_fma_f32 v[86:87], v[86:87], v[134:135], v[186:187]
	v_pk_fma_f32 v[88:89], v[88:89], v[136:137], v[188:189]
	v_lshlrev_b32_e32 v190, 16, v200
	v_and_b32_e32 v191, 0xffff0000, v200
	v_lshlrev_b32_e32 v192, 16, v201
	v_and_b32_e32 v193, 0xffff0000, v201
	v_pk_fma_f32 v[78:79], v[78:79], v[130:131], v[190:191]
	v_pk_fma_f32 v[80:81], v[80:81], v[132:133], v[192:193]
	v_cvt_pk_bf16_f32 v86, v86, v87
	v_cvt_pk_bf16_f32 v87, v88, v89
	v_cvt_pk_bf16_f32 v88, v78, v79
	v_cvt_pk_bf16_f32 v89, v80, v81
	s_nop 1
	v_permlane16_swap_b32 v86, v88
	v_permlane16_swap_b32 v87, v89
	v_mov_b32_e32 v212, 0x10000
	v_lshl_add_u64 v[220:221], v[216:217], 0, v[212:213]
	global_store_dwordx4 v[220:221], v[86:89], off offset:256
	global_load_dwordx4 v[198:201], v[218:219], off offset:256
	s_waitcnt vmcnt(13)
	v_permlane16_swap_b32 v202, v204
	v_permlane16_swap_b32 v203, v205
	s_nop 1
	v_lshlrev_b32_e32 v186, 16, v202
	v_and_b32_e32 v187, 0xffff0000, v202
	v_lshlrev_b32_e32 v188, 16, v203
	v_and_b32_e32 v189, 0xffff0000, v203
	v_pk_fma_f32 v[82:83], v[82:83], v[142:143], v[186:187]
	v_pk_fma_f32 v[84:85], v[84:85], v[144:145], v[188:189]
	v_lshlrev_b32_e32 v190, 16, v204
	v_and_b32_e32 v191, 0xffff0000, v204
	v_lshlrev_b32_e32 v192, 16, v205
	v_and_b32_e32 v193, 0xffff0000, v205
	v_pk_fma_f32 v[74:75], v[74:75], v[138:139], v[190:191]
	v_pk_fma_f32 v[76:77], v[76:77], v[140:141], v[192:193]
	v_cvt_pk_bf16_f32 v82, v82, v83
	v_cvt_pk_bf16_f32 v83, v84, v85
	v_cvt_pk_bf16_f32 v84, v74, v75
	v_cvt_pk_bf16_f32 v85, v76, v77
	s_nop 1
	v_permlane16_swap_b32 v82, v84
	v_permlane16_swap_b32 v83, v85
	v_mov_b32_e32 v212, 0x18000
	v_lshl_add_u64 v[220:221], v[216:217], 0, v[212:213]
	global_store_dwordx4 v[220:221], v[82:85], off
	v_mov_b32_e32 v212, 0x58000
	v_lshl_add_u64 v[218:219], v[214:215], 0, v[212:213]
	global_load_dwordx4 v[202:205], v[218:219], off
	s_waitcnt vmcnt(14)
	v_permlane16_swap_b32 v206, v208
	v_permlane16_swap_b32 v207, v209
	s_nop 1
	v_lshlrev_b32_e32 v186, 16, v206
	v_and_b32_e32 v187, 0xffff0000, v206
	v_lshlrev_b32_e32 v188, 16, v207
	v_and_b32_e32 v189, 0xffff0000, v207
	v_pk_fma_f32 v[70:71], v[70:71], v[134:135], v[186:187]
	v_pk_fma_f32 v[72:73], v[72:73], v[136:137], v[188:189]
	v_lshlrev_b32_e32 v190, 16, v208
	v_and_b32_e32 v191, 0xffff0000, v208
	v_lshlrev_b32_e32 v192, 16, v209
	v_and_b32_e32 v193, 0xffff0000, v209
	v_pk_fma_f32 v[66:67], v[66:67], v[130:131], v[190:191]
	v_pk_fma_f32 v[68:69], v[68:69], v[132:133], v[192:193]
	v_cvt_pk_bf16_f32 v70, v70, v71
	v_cvt_pk_bf16_f32 v71, v72, v73
	v_cvt_pk_bf16_f32 v72, v66, v67
	v_cvt_pk_bf16_f32 v73, v68, v69
	s_nop 1
	v_permlane16_swap_b32 v70, v72
	v_permlane16_swap_b32 v71, v73
	v_mov_b32_e32 v212, 0x18000
	v_lshl_add_u64 v[220:221], v[216:217], 0, v[212:213]
	global_store_dwordx4 v[220:221], v[70:73], off offset:256
	global_load_dwordx4 v[206:209], v[218:219], off offset:256
	s_waitcnt vmcnt(14)
	v_permlane16_swap_b32 v164, v166
	v_permlane16_swap_b32 v165, v167
	s_nop 1
	v_lshlrev_b32_e32 v186, 16, v164
	v_and_b32_e32 v187, 0xffff0000, v164
	v_lshlrev_b32_e32 v188, 16, v165
	v_and_b32_e32 v189, 0xffff0000, v165
	v_pk_fma_f32 v[62:63], v[62:63], v[142:143], v[186:187]
	v_pk_fma_f32 v[64:65], v[64:65], v[144:145], v[188:189]
	v_lshlrev_b32_e32 v190, 16, v166
	v_and_b32_e32 v191, 0xffff0000, v166
	v_lshlrev_b32_e32 v192, 16, v167
	v_and_b32_e32 v193, 0xffff0000, v167
	v_pk_fma_f32 v[58:59], v[58:59], v[138:139], v[190:191]
	v_pk_fma_f32 v[60:61], v[60:61], v[140:141], v[192:193]
	v_cvt_pk_bf16_f32 v62, v62, v63
	v_cvt_pk_bf16_f32 v63, v64, v65
	v_cvt_pk_bf16_f32 v64, v58, v59
	v_cvt_pk_bf16_f32 v65, v60, v61
	s_nop 1
	v_permlane16_swap_b32 v62, v64
	v_permlane16_swap_b32 v63, v65
	v_mov_b32_e32 v212, 0x40000
	v_lshl_add_u64 v[220:221], v[216:217], 0, v[212:213]
	global_store_dwordx4 v[220:221], v[62:65], off
	s_waitcnt vmcnt(13)
	v_permlane16_swap_b32 v168, v170
	v_permlane16_swap_b32 v169, v171
	s_nop 1
	v_lshlrev_b32_e32 v186, 16, v168
	v_and_b32_e32 v187, 0xffff0000, v168
	v_lshlrev_b32_e32 v188, 16, v169
	v_and_b32_e32 v189, 0xffff0000, v169
	v_pk_fma_f32 v[54:55], v[54:55], v[134:135], v[186:187]
	v_pk_fma_f32 v[56:57], v[56:57], v[136:137], v[188:189]
	v_lshlrev_b32_e32 v190, 16, v170
	v_and_b32_e32 v191, 0xffff0000, v170
	v_lshlrev_b32_e32 v192, 16, v171
	v_and_b32_e32 v193, 0xffff0000, v171
	v_pk_fma_f32 v[44:45], v[44:45], v[130:131], v[190:191]
	v_pk_fma_f32 v[46:47], v[46:47], v[132:133], v[192:193]
	v_cvt_pk_bf16_f32 v54, v54, v55
	v_cvt_pk_bf16_f32 v55, v56, v57
	v_cvt_pk_bf16_f32 v56, v44, v45
	v_cvt_pk_bf16_f32 v57, v46, v47
	s_nop 1
	v_permlane16_swap_b32 v54, v56
	v_permlane16_swap_b32 v55, v57
	v_mov_b32_e32 v212, 0x40000
	v_lshl_add_u64 v[220:221], v[216:217], 0, v[212:213]
	global_store_dwordx4 v[220:221], v[54:57], off offset:256
	s_waitcnt vmcnt(12)
	v_permlane16_swap_b32 v172, v174
	v_permlane16_swap_b32 v173, v175
	s_nop 1
	v_lshlrev_b32_e32 v186, 16, v172
	v_and_b32_e32 v187, 0xffff0000, v172
	v_lshlrev_b32_e32 v188, 16, v173
	v_and_b32_e32 v189, 0xffff0000, v173
	v_pk_fma_f32 v[50:51], v[50:51], v[142:143], v[186:187]
	v_pk_fma_f32 v[52:53], v[52:53], v[144:145], v[188:189]
	v_lshlrev_b32_e32 v190, 16, v174
	v_and_b32_e32 v191, 0xffff0000, v174
	v_lshlrev_b32_e32 v192, 16, v175
	v_and_b32_e32 v193, 0xffff0000, v175
	v_pk_fma_f32 v[40:41], v[40:41], v[138:139], v[190:191]
	v_pk_fma_f32 v[42:43], v[42:43], v[140:141], v[192:193]
	v_cvt_pk_bf16_f32 v50, v50, v51
	v_cvt_pk_bf16_f32 v51, v52, v53
	v_cvt_pk_bf16_f32 v52, v40, v41
	v_cvt_pk_bf16_f32 v53, v42, v43
	s_nop 1
	v_permlane16_swap_b32 v50, v52
	v_permlane16_swap_b32 v51, v53
	v_mov_b32_e32 v212, 0x48000
	v_lshl_add_u64 v[220:221], v[216:217], 0, v[212:213]
	global_store_dwordx4 v[220:221], v[50:53], off
	s_waitcnt vmcnt(11)
	v_permlane16_swap_b32 v176, v178
	v_permlane16_swap_b32 v177, v179
	s_nop 1
	v_lshlrev_b32_e32 v186, 16, v176
	v_and_b32_e32 v187, 0xffff0000, v176
	v_lshlrev_b32_e32 v188, 16, v177
	v_and_b32_e32 v189, 0xffff0000, v177
	v_pk_fma_f32 v[36:37], v[36:37], v[134:135], v[186:187]
	v_pk_fma_f32 v[38:39], v[38:39], v[136:137], v[188:189]
	v_lshlrev_b32_e32 v190, 16, v178
	v_and_b32_e32 v191, 0xffff0000, v178
	v_lshlrev_b32_e32 v192, 16, v179
	v_and_b32_e32 v193, 0xffff0000, v179
	v_pk_fma_f32 v[28:29], v[28:29], v[130:131], v[190:191]
	v_pk_fma_f32 v[30:31], v[30:31], v[132:133], v[192:193]
	v_cvt_pk_bf16_f32 v36, v36, v37
	v_cvt_pk_bf16_f32 v37, v38, v39
	v_cvt_pk_bf16_f32 v38, v28, v29
	v_cvt_pk_bf16_f32 v39, v30, v31
	s_nop 1
	v_permlane16_swap_b32 v36, v38
	v_permlane16_swap_b32 v37, v39
	v_mov_b32_e32 v212, 0x48000
	v_lshl_add_u64 v[220:221], v[216:217], 0, v[212:213]
	global_store_dwordx4 v[220:221], v[36:39], off offset:256
	s_waitcnt vmcnt(10)
	v_permlane16_swap_b32 v180, v182
	v_permlane16_swap_b32 v181, v183
	s_nop 1
	v_lshlrev_b32_e32 v186, 16, v180
	v_and_b32_e32 v187, 0xffff0000, v180
	v_lshlrev_b32_e32 v188, 16, v181
	v_and_b32_e32 v189, 0xffff0000, v181
	v_pk_fma_f32 v[32:33], v[32:33], v[142:143], v[186:187]
	v_pk_fma_f32 v[34:35], v[34:35], v[144:145], v[188:189]
	v_lshlrev_b32_e32 v190, 16, v182
	v_and_b32_e32 v191, 0xffff0000, v182
	v_lshlrev_b32_e32 v192, 16, v183
	v_and_b32_e32 v193, 0xffff0000, v183
	v_pk_fma_f32 v[24:25], v[24:25], v[138:139], v[190:191]
	v_pk_fma_f32 v[26:27], v[26:27], v[140:141], v[192:193]
	v_cvt_pk_bf16_f32 v32, v32, v33
	v_cvt_pk_bf16_f32 v33, v34, v35
	v_cvt_pk_bf16_f32 v34, v24, v25
	v_cvt_pk_bf16_f32 v35, v26, v27
	s_nop 1
	v_permlane16_swap_b32 v32, v34
	v_permlane16_swap_b32 v33, v35
	v_mov_b32_e32 v212, 0x50000
	v_lshl_add_u64 v[220:221], v[216:217], 0, v[212:213]
	global_store_dwordx4 v[220:221], v[32:35], off
	s_waitcnt vmcnt(9)
	v_permlane16_swap_b32 v198, v200
	v_permlane16_swap_b32 v199, v201
	s_nop 1
	v_lshlrev_b32_e32 v186, 16, v198
	v_and_b32_e32 v187, 0xffff0000, v198
	v_lshlrev_b32_e32 v188, 16, v199
	v_and_b32_e32 v189, 0xffff0000, v199
	v_pk_fma_f32 v[20:21], v[20:21], v[134:135], v[186:187]
	v_pk_fma_f32 v[22:23], v[22:23], v[136:137], v[188:189]
	v_lshlrev_b32_e32 v190, 16, v200
	v_and_b32_e32 v191, 0xffff0000, v200
	v_lshlrev_b32_e32 v192, 16, v201
	v_and_b32_e32 v193, 0xffff0000, v201
	v_pk_fma_f32 v[12:13], v[12:13], v[130:131], v[190:191]
	v_pk_fma_f32 v[14:15], v[14:15], v[132:133], v[192:193]
	v_cvt_pk_bf16_f32 v20, v20, v21
	v_cvt_pk_bf16_f32 v21, v22, v23
	v_cvt_pk_bf16_f32 v22, v12, v13
	v_cvt_pk_bf16_f32 v23, v14, v15
	s_nop 1
	v_permlane16_swap_b32 v20, v22
	v_permlane16_swap_b32 v21, v23
	v_mov_b32_e32 v212, 0x50000
	v_lshl_add_u64 v[220:221], v[216:217], 0, v[212:213]
	global_store_dwordx4 v[220:221], v[20:23], off offset:256
	s_waitcnt vmcnt(8)
	v_permlane16_swap_b32 v202, v204
	v_permlane16_swap_b32 v203, v205
	s_nop 1
	v_lshlrev_b32_e32 v186, 16, v202
	v_and_b32_e32 v187, 0xffff0000, v202
	v_lshlrev_b32_e32 v188, 16, v203
	v_and_b32_e32 v189, 0xffff0000, v203
	v_pk_fma_f32 v[16:17], v[16:17], v[142:143], v[186:187]
	v_pk_fma_f32 v[18:19], v[18:19], v[144:145], v[188:189]
	v_lshlrev_b32_e32 v190, 16, v204
	v_and_b32_e32 v191, 0xffff0000, v204
	v_lshlrev_b32_e32 v192, 16, v205
	v_and_b32_e32 v193, 0xffff0000, v205
	v_pk_fma_f32 v[8:9], v[8:9], v[138:139], v[190:191]
	v_pk_fma_f32 v[10:11], v[10:11], v[140:141], v[192:193]
	v_cvt_pk_bf16_f32 v16, v16, v17
	v_cvt_pk_bf16_f32 v17, v18, v19
	v_cvt_pk_bf16_f32 v18, v8, v9
	v_cvt_pk_bf16_f32 v19, v10, v11
	s_nop 1
	v_permlane16_swap_b32 v16, v18
	v_permlane16_swap_b32 v17, v19
	v_mov_b32_e32 v212, 0x58000
	v_lshl_add_u64 v[220:221], v[216:217], 0, v[212:213]
	global_store_dwordx4 v[220:221], v[16:19], off
	s_waitcnt vmcnt(7)
	v_permlane16_swap_b32 v206, v208
	v_permlane16_swap_b32 v207, v209
	s_nop 1
	v_lshlrev_b32_e32 v186, 16, v206
	v_and_b32_e32 v187, 0xffff0000, v206
	v_lshlrev_b32_e32 v188, 16, v207
	v_and_b32_e32 v189, 0xffff0000, v207
	v_pk_fma_f32 v[4:5], v[4:5], v[134:135], v[186:187]
	v_pk_fma_f32 v[6:7], v[6:7], v[136:137], v[188:189]
	v_lshlrev_b32_e32 v190, 16, v208
	v_and_b32_e32 v191, 0xffff0000, v208
	v_lshlrev_b32_e32 v192, 16, v209
	v_and_b32_e32 v193, 0xffff0000, v209
	v_pk_fma_f32 v[0:1], v[0:1], v[130:131], v[190:191]
	v_pk_fma_f32 v[2:3], v[2:3], v[132:133], v[192:193]
	v_cvt_pk_bf16_f32 v4, v4, v5
	v_cvt_pk_bf16_f32 v5, v6, v7
	v_cvt_pk_bf16_f32 v6, v0, v1
	v_cvt_pk_bf16_f32 v7, v2, v3
	s_nop 1
	v_permlane16_swap_b32 v4, v6
	v_permlane16_swap_b32 v5, v7
	v_mov_b32_e32 v212, 0x58000
	v_lshl_add_u64 v[220:221], v[216:217], 0, v[212:213]
	global_store_dwordx4 v[220:221], v[4:7], off offset:256
	s_mov_b32 s16, s43
	s_mov_b32 s17, s42
	s_and_b64 vcc, exec, s[0:1]
	s_mov_b64 s[18:19], s[12:13]
	s_cbranch_vccz .LBB0_1432
	s_waitcnt vmcnt(0)
	s_cmpk_gt_u32 s29, 0xff
	s_cbranch_scc1 .LBB0_1439
	s_barrier
